# setprio-pair+redundant-lgkmcnt trim in GEMM loops; GQA Q hoist/table reuse/scalar sink; NA bias-table loads de-serialized
# speedup vs baseline: 1.0048x; 1.0048x over previous
; #define LAS __attribute__((address_space(3)))
; __device__ __forceinline__ void gqa_phase(const PP P, LAS unsigned char* lds, int tid, int cb, int G) {
;     ...
;         for (int c = 0; c < 6; ++c) { const int id = tid + 512 * c, row = id >> 3, ch = id & 7; *(LAS u32x4*)(lds + GQ_K + row * GK_PITCH + ch * 16) = kreg[c]; }
; #pragma unroll
;         for (int c = 0; c < 6; ++c) { const int id = tid + 512 * c, d = id / 48, ch = id - d * 48; LAS u32x2* vp = (LAS u32x2*)(lds + GQ_V + d * GV_PITCH + ch * 16);
;             vp[0] = (u32x2){vreg[c].x, vreg[c].y}; vp[1] = (u32x2){vreg[c].z, vreg[c].w}; }
;         const int kvg = unit & 3, m0 = (unit >> 2) * 128;
;         int row0, L; if (m0 < M_P) { row0 = m0 & ~4095; L = 4096; } else { row0 = M_P + ((m0 - M_P) & ~2047); L = 2048; }
;         const int head = kvg * 4 + (wave >> 1);
;         { const float* tbg = (const float*)(P.ws() + WS_TB) + head * 257; for (int i = lane; i < 257; i += 64) tbl[i] = tbg[i] * LOG2E; }
;         if (unit + G < 3072) GQA_LOAD(unit + G);
;         __syncthreads();
;         const float sink2 = P.in(21)[head] * LOG2E;
;         for (int sub = 0; sub < 2; ++sub) {
;             const int qoff = ((wave & 1) * 2 + sub) * 32;
;             const bf16_t* qp = Z + (size_t)(m0 + qoff + r32) * ZLD1 + head * 64 + hi * 8;
;             bf16x8 qr[4];
; #pragma unroll
;             for (int ds = 0; ds < 4; ++ds) qr[ds] = *(const bf16x8*)(qp + ds * 16);
.LBB0_46:
	s_bfe_u32 s0, s2, 0x20002
	s_mulk_i32 s0, 0x404
	s_mul_i32 s1, s16, 0x101
	s_add_i32 s0, s1, s0
	s_ashr_i32 s1, s0, 31
	s_mov_b32 s22, s11
	v_lshl_add_u64 v[2:3], s[0:1], 2, v[140:141]
	s_mov_b64 s[0:1], 0
	v_mov_b32_e32 v0, v183
	v_mov_b32_e32 v4, v182
	s_lshl_b32 s3, s22, 5
	s_and_b32 s3, s3, 0xffffff80
	s_or_b32 s3, s3, s17
	s_lshl_b32 s12, s22, 2
	s_and_b32 s12, s12, 12
	s_add_i32 s12, s12, s16
	s_lshl_b32 s12, s12, 7
	s_mov_b32 s13, 0
	v_or_b32_e32 v230, s3, v164
	s_movk_i32 s18, 0xa00
	v_lshl_add_u64 v[228:229], v[124:125], 0, s[12:13]
	s_mov_b32 s20, 0x14000
	v_mad_i64_i32 v[226:227], s[12:13], v230, s18, v[228:229]
	s_nop 0
	global_load_dwordx4 v[110:113], v[226:227], off
	global_load_dwordx4 v[106:109], v[226:227], off offset:32
	global_load_dwordx4 v[102:105], v[226:227], off offset:64
	global_load_dwordx4 v[98:101], v[226:227], off offset:96
	v_lshl_add_u64 v[228:229], v[226:227], 0, s[20:21]
	s_nop 0
	global_load_dwordx4 v[222:225], v[228:229], off
	global_load_dwordx4 v[218:221], v[228:229], off offset:32
	global_load_dwordx4 v[214:217], v[228:229], off offset:64
	global_load_dwordx4 v[210:213], v[228:229], off offset:96
	s_barrier
	s_waitcnt vmcnt(0)
	ds_write_b128 v184, v[54:57]
	ds_write_b128 v185, v[50:53]
	ds_write_b128 v186, v[58:61]
	ds_write_b128 v187, v[62:65]
	ds_write_b128 v188, v[66:69]
	ds_write_b128 v189, v[70:73]
	ds_write2_b64 v190, v[74:75], v[76:77] offset1:1
	ds_write2_b64 v191, v[78:79], v[80:81] offset1:1
	ds_write2_b64 v192, v[82:83], v[84:85] offset1:1
	ds_write2_b64 v193, v[86:87], v[88:89] offset1:1
	ds_write2_b64 v194, v[90:91], v[92:93] offset1:1
	ds_write2_b64 v195, v[94:95], v[96:97] offset1:1
	s_cmp_eq_u32 s22, s34
	s_cbranch_scc1 .Lgqa_tbl_fill
	s_and_b32 s3, s10, 3
	s_cmp_eq_u32 s3, 0
	s_cbranch_scc1 .Lgqa_tbl_skip
.Lgqa_tbl_fill:
.LBB0_47:
	global_load_dword v5, v[2:3], off
	v_add_u32_e32 v4, 64, v4
	s_movk_i32 s3, 0xc0
	s_mov_b64 s[12:13], 0x100
	v_cmp_lt_u32_e32 vcc, s3, v4
	v_lshl_add_u64 v[2:3], v[2:3], 0, s[12:13]
	s_or_b64 s[0:1], vcc, s[0:1]
	s_waitcnt vmcnt(0)
	v_mul_f32_e32 v5, 0x3fb8aa3b, v5
	ds_write_b32 v0, v5
	v_add_u32_e32 v0, 0x100, v0
	s_andn2_b64 exec, exec, s[0:1]
	s_cbranch_execnz .LBB0_47
.Lgqa_tbl_skip:
	s_or_b64 exec, exec, s[0:1]
	s_add_i32 s11, s22, s10
	s_cmpk_gt_i32 s11, 0xbff
	s_cselect_b64 s[0:1], -1, 0
	s_cmpk_lt_i32 s11, 0xc00
	s_cbranch_scc0 .LBB0_74
	s_lshl_b32 s3, s11, 5
	s_and_b32 s24, s3, 0xffffff80
	s_cmp_lt_i32 s24, 0x8000
	s_movk_i32 s13, 0xf000
	s_movk_i32 s12, 0x1000
	s_cselect_b32 s13, s13, 0xfffff800
	s_cselect_b32 s12, s12, 0x800
	s_and_b32 s23, s13, s3
	s_add_i32 s18, s24, 0xffffff80
	s_add_i32 s35, s23, s12
	v_add_u32_e32 v0, s18, v123
	v_mov_b32_e32 v52, v1
	v_mov_b32_e32 v53, v1
	s_lshl_b32 s3, s11, 6
	v_cmp_le_i32_e64 s[12:13], s23, v0
	v_cmp_gt_i32_e32 vcc, s35, v0
	v_mov_b32_e32 v50, v1
	v_mov_b32_e32 v51, v1
	v_mov_b64_e32 v[56:57], v[52:53]
	s_and_b32 s3, s3, 0xc0
	s_and_b64 vcc, s[12:13], vcc
	v_lshlrev_b32_e32 v4, 1, v122
	v_mov_b64_e32 v[54:55], v[50:51]
	s_and_saveexec_b64 s[12:13], vcc
	s_cbranch_execz .LBB0_51
	v_readlane_b32 vcc_lo, v255, 38
	v_readlane_b32 vcc_hi, v255, 39
	s_movk_i32 s19, 0xa00
	s_lshl_b32 s20, s3, 1
	v_mov_b64_e32 v[2:3], vcc
	v_mad_i64_i32 v[2:3], vcc, v0, s19, v[2:3]
	v_lshl_add_u64 v[2:3], v[2:3], 0, s[20:21]
	v_mov_b32_e32 v5, v1
	v_lshl_add_u64 v[2:3], v[2:3], 0, v[4:5]
	global_load_dwordx4 v[54:57], v[2:3], off offset:2048

; __device__ __forceinline__ void gqa_phase(const PP P, LAS unsigned char* lds, int tid, int cb, int G) {
;     ...
;         const int kvg = unit & 3, m0 = (unit >> 2) * 128;
;         int row0, L; if (m0 < M_P) { row0 = m0 & ~4095; L = 4096; } else { row0 = M_P + ((m0 - M_P) & ~2047); L = 2048; }
;         const int head = kvg * 4 + (wave >> 1);
;         { const float* tbg = (const float*)(P.ws() + WS_TB) + head * 257; for (int i = lane; i < 257; i += 64) tbl[i] = tbg[i] * LOG2E; }
;         if (unit + G < 3072) GQA_LOAD(unit + G);
;         __syncthreads();
;         const float sink2 = P.in(21)[head] * LOG2E;
.LBB0_74:
	s_lshl_b32 s3, s22, 5
	s_and_b32 s35, s3, 0xffffff80
	s_cmp_lt_i32 s35, 0x8000
	s_movk_i32 s12, 0xf000
	s_cselect_b32 s12, s12, 0xfffff800
	s_movk_i32 s13, 0x1000
	s_cselect_b32 s20, s13, 0x800
	s_and_b32 s3, s12, s3
	s_lshl_b32 s12, s22, 2
	s_waitcnt lgkmcnt(0)
	s_barrier
	s_load_dwordx2 s[22:23], s[38:39], 0xa8
	s_and_b32 s12, s12, 12
	s_add_i32 s12, s12, s16
	s_ashr_i32 s13, s12, 31
	s_lshl_b64 s[18:19], s[12:13], 2
	s_waitcnt lgkmcnt(0)
	s_add_u32 s18, s22, s18
	s_addc_u32 s19, s23, s19
	s_load_dword s24, s[18:19], 0x0
	s_lshl_b32 s12, s12, 6
	s_ashr_i32 s13, s12, 31
	s_lshl_b64 s[12:13], s[12:13], 1
	v_or_b32_e32 v197, s35, v164
	v_lshl_add_u64 v[142:143], v[124:125], 0, s[12:13]
	s_addk_i32 s35, 0xff80
	s_add_i32 s20, s3, s20
	v_lshl_add_u64 v[144:145], v[126:127], 0, s[12:13]
	s_mov_b32 s18, 0
	s_waitcnt lgkmcnt(0)
	v_mov_b32_e32 v0, s24
	s_mov_b64 s[24:25], -1
	v_mul_f32_e32 v196, 0x3fb8aa3b, v0
	s_branch .LBB0_79

; #define LAS __attribute__((address_space(3)))
; #define MFMA32(a, b, c) __builtin_amdgcn_mfma_f32_32x32x16_bf16((a), (b), (c), 0, 0, 0)
; __device__ __forceinline__ void gqa_phase(const PP P, LAS unsigned char* lds, int tid, int cb, int G) {
;     ...
;         for (int sub = 0; sub < 2; ++sub) {
;             const int qoff = ((wave & 1) * 2 + sub) * 32;
;             const bf16_t* qp = Z + (size_t)(m0 + qoff + r32) * ZLD1 + head * 64 + hi * 8;
;             bf16x8 qr[4];
; #pragma unroll
;             for (int ds = 0; ds < 4; ++ds) qr[ds] = *(const bf16x8*)(qp + ds * 16);
;             float m = sink2, l = hi ? 0.f : 1.f;
;             f32x16 o0 = {}, o1 = {};
;             for (int t = 0; t < 9; ++t) {
;                 const int kr0 = qoff + 32 * t, tok0 = m0 - 128 + kr0;
;                 if (tok0 < row0 || tok0 >= row0 + L) continue;
;                 bf16x8 kf[4];
; #pragma unroll
;                 for (int ds = 0; ds < 4; ++ds) kf[ds] = *(const LAS bf16x8*)(lds + GQ_K + (kr0 + r32) * GK_PITCH + (16 * ds + 8 * hi) * 2);
;                 bf16x8 vf[2][2];
; #pragma unroll
;                 for (int dh = 0; dh < 2; ++dh)
; #pragma unroll
;                     for (int s = 0; s < 2; ++s) { const LAS s16x4* vp = (const LAS s16x4*)(lds + GQ_V + (dh * 32 + r32) * GV_PITCH + (kr0 + 16 * s + 4 * hi) * 2);
;                         const s16x4 a = vp[0], c2 = vp[2]; vf[dh][s] = (bf16x8){a[0], a[1], a[2], a[3], c2[0], c2[1], c2[2], c2[3]}; }
;                 f32x16 sc = {};
; #pragma unroll
;                 for (int ds = 0; ds < 4; ++ds) sc = MFMA32(kf[ds], qr[ds], sc);
;                 const int ib = 32 * t - r32 + 4 * hi;
.LBB0_79:
	s_or_b32 s22, s18, s17
	v_or_b32_e32 v146, s22, v197
	s_cmp_eq_u32 s18, 0
	s_cbranch_scc1 .Lgqa_q_ready
	v_mov_b32_e32 v98, v210
	v_mov_b32_e32 v99, v211
	v_mov_b32_e32 v100, v212
	v_mov_b32_e32 v101, v213
	v_mov_b32_e32 v102, v214
	v_mov_b32_e32 v103, v215
	v_mov_b32_e32 v104, v216
	v_mov_b32_e32 v105, v217
	v_mov_b32_e32 v106, v218
	v_mov_b32_e32 v107, v219
	v_mov_b32_e32 v108, v220
	v_mov_b32_e32 v109, v221
	v_mov_b32_e32 v110, v222
	v_mov_b32_e32 v111, v223
	v_mov_b32_e32 v112, v224
	v_mov_b32_e32 v113, v225
.Lgqa_q_ready:
	s_or_b32 s18, s35, s22
	s_cmp_ge_i32 s18, s3
	s_cselect_b64 s[12:13], -1, 0
	s_cmp_lt_i32 s18, s20
	s_cselect_b64 s[18:19], -1, 0
	s_and_b64 s[12:13], s[12:13], s[18:19]
	s_andn2_b64 vcc, exec, s[12:13]
	s_cbranch_vccnz .LBB0_113
	v_or_b32_e32 v0, s22, v164
	v_mad_u32_u24 v0, v0, s26, v166
	ds_read_b128 v[2:5], v0
	ds_read_b128 v[18:21], v0 offset:32
	s_lshl_b32 s12, s22, 1
	s_waitcnt lgkmcnt(1)
	v_mfma_f32_32x32x16_bf16 v[2:17], v[2:5], v[110:113], 0
	s_waitcnt lgkmcnt(0)
	v_mfma_f32_32x32x16_bf16 v[2:17], v[18:21], v[106:109], v[2:17]
	ds_read_b128 v[18:21], v0 offset:64
	ds_read_b128 v[22:25], v0 offset:96
	v_add_u32_e32 v0, s12, v179
	v_add_u32_e32 v0, 0xd800, v0
	ds_read2_b64 v[46:49], v0 offset1:2
	ds_read2_b64 v[42:45], v0 offset0:4 offset1:6
	v_add_u32_e32 v0, s12, v180
	v_add_u32_e32 v0, 0x6000, v0
	ds_read2_b64 v[38:41], v0 offset0:32 offset1:34
	ds_read2_b64 v[34:37], v0 offset0:36 offset1:38
	s_waitcnt lgkmcnt(5)
	v_mfma_f32_32x32x16_bf16 v[2:17], v[18:21], v[102:105], v[2:17]
	v_mov_b32_e32 v0, 0xf149f2ca
	v_mov_b32_e32 v18, 0xf149f2ca
	s_waitcnt lgkmcnt(4)
	v_mfma_f32_32x32x16_bf16 v[2:17], v[22:25], v[98:101], v[2:17]
	s_and_saveexec_b64 s[12:13], s[40:41]
	s_cbranch_execz .LBB0_82
	ds_read_b32 v18, v181
	s_waitcnt lgkmcnt(0)
	s_nop 7
	v_fmac_f32_e32 v18, 0x3e38aa3b, v2

; #define LAS __attribute__((address_space(3)))
; __device__ __forceinline__ void softmax2_pv(f32x16& sc, float& m, float& l, f32x16& o0, f32x16& o1, const bf16x8 (&vf)[2][2]) {
;     float tm = fmaxf(fmaxf(sc[0], sc[1]), fmaxf(sc[2], sc[3]));
; #pragma unroll
;     for (int i = 4; i < 16; i += 4) tm = fmaxf(tm, fmaxf(fmaxf(sc[i], sc[i + 1]), fmaxf(sc[i + 2], sc[i + 3])));
;     tm = fmaxf(tm, __shfl_xor(tm, 32));
;     const float mn = fmaxf(m, tm);
;     if (__builtin_amdgcn_ballot_w64(mn > m)) {
;         const float alpha = __builtin_amdgcn_exp2f(m - mn);
;         l *= alpha;
; #pragma unroll
;         for (int i = 0; i < 16; ++i) { o0[i] *= alpha; o1[i] *= alpha; }
;         m = mn;
;     }
; __device__ __forceinline__ void gqa_phase(const PP P, LAS unsigned char* lds, int tid, int cb, int G) {
;     ...
;             for (int t = 0; t < 9; ++t) {
;                 const int kr0 = qoff + 32 * t, tok0 = m0 - 128 + kr0;
;                 if (tok0 < row0 || tok0 >= row0 + L) continue;
;                 bf16x8 kf[4];
; #pragma unroll
;                 for (int ds = 0; ds < 4; ++ds) kf[ds] = *(const LAS bf16x8*)(lds + GQ_K + (kr0 + r32) * GK_PITCH + (16 * ds + 8 * hi) * 2);
;                 bf16x8 vf[2][2];
; #pragma unroll
;                 for (int dh = 0; dh < 2; ++dh)
; #pragma unroll
;                     for (int s = 0; s < 2; ++s) { const LAS s16x4* vp = (const LAS s16x4*)(lds + GQ_V + (dh * 32 + r32) * GV_PITCH + (kr0 + 16 * s + 4 * hi) * 2);
;                         const s16x4 a = vp[0], c2 = vp[2]; vf[dh][s] = (bf16x8){a[0], a[1], a[2], a[3], c2[0], c2[1], c2[2], c2[3]}; }
;                 f32x16 sc = {};
; #pragma unroll
;                 for (int ds = 0; ds < 4; ++ds) sc = MFMA32(kf[ds], qr[ds], sc);
;                 const int ib = 32 * t - r32 + 4 * hi;
;                 if (t == 0 || t == 8) {
; #pragma unroll
;                     for (int i = 0; i < 16; ++i) { const int ix = ib + (i & 3) + 8 * (i >> 2); const bool valid = ix >= 0 && ix <= 256; const float bb = tbl[valid ? ix : 0];
;                         sc[i] = valid ? sc[i] * (0.125f * LOG2E) + bb : NEGBIG; }
;                 } else {
; #pragma unroll
;                     for (int i = 0; i < 16; ++i) sc[i] = sc[i] * (0.125f * LOG2E) + tbl[ib + (i & 3) + 8 * (i >> 2)];
;                 }
;                 softmax2_pv(sc, m, l, o0, o1, vf);
.LBB0_114:
	s_add_i32 s18, s22, 32
	s_xor_b64 s[12:13], s[24:25], -1
	s_add_i32 s19, s35, s18
	s_cmp_ge_i32 s19, s3
	s_cselect_b64 s[24:25], -1, 0
	s_cmp_lt_i32 s19, s20
	s_cselect_b64 vcc, -1, 0
	s_and_b64 s[24:25], s[24:25], vcc
	v_ashrrev_i32_e32 v147, 31, v146
	s_andn2_b64 vcc, exec, s[24:25]
	s_cbranch_vccnz .LBB0_120
	v_or_b32_e32 v34, s18, v164
	v_mad_u32_u24 v118, v34, s26, v166
	ds_read_b128 v[34:37], v118
	ds_read_b128 v[114:117], v118 offset:32
	s_lshl_b32 s18, s18, 1
	s_waitcnt lgkmcnt(1)
	v_mfma_f32_32x32x16_bf16 v[34:49], v[34:37], v[110:113], 0
	s_waitcnt lgkmcnt(0)
	v_mfma_f32_32x32x16_bf16 v[34:49], v[114:117], v[106:109], v[34:49]
	ds_read_b128 v[114:117], v118 offset:64
	ds_read2_b32 v[162:163], v181 offset0:32 offset1:33
	ds_read2_b32 v[160:161], v181 offset0:34 offset1:35
	ds_read2_b32 v[154:155], v181 offset0:40 offset1:41
	ds_read2_b32 v[150:151], v181 offset0:42 offset1:43
	ds_read_b128 v[206:209], v118 offset:96
	ds_read2_b32 v[156:157], v181 offset0:48 offset1:49
	ds_read2_b32 v[158:159], v181 offset0:50 offset1:51
	ds_read2_b32 v[152:153], v181 offset0:56 offset1:57
	ds_read2_b32 v[148:149], v181 offset0:58 offset1:59
	s_waitcnt lgkmcnt(9)
	v_mfma_f32_32x32x16_bf16 v[34:49], v[114:117], v[102:105], v[34:49]
	v_add_u32_e32 v114, s18, v179
	v_add_u32_e32 v114, 0xd800, v114
	ds_read2_b64 v[118:121], v114 offset1:2
	ds_read2_b64 v[114:117], v114 offset0:4 offset1:6
	s_waitcnt lgkmcnt(6)
	v_mfma_f32_32x32x16_bf16 v[34:49], v[206:209], v[98:101], v[34:49]
	s_nop 11
	v_fmamk_f32 v199, v36, 0x3e38aa3b, v160
	v_fmamk_f32 v160, v40, 0x3e38aa3b, v150
	v_fmac_f32_e32 v151, 0x3e38aa3b, v41
	v_fmamk_f32 v200, v34, 0x3e38aa3b, v162
	v_fmac_f32_e32 v163, 0x3e38aa3b, v35
	v_fmac_f32_e32 v161, 0x3e38aa3b, v37
	v_fmamk_f32 v162, v38, 0x3e38aa3b, v154
	v_fmac_f32_e32 v155, 0x3e38aa3b, v39
	s_waitcnt lgkmcnt(5)
	v_fmac_f32_e32 v157, 0x3e38aa3b, v43
	s_waitcnt lgkmcnt(4)
	v_fmamk_f32 v150, v44, 0x3e38aa3b, v158
	v_fmac_f32_e32 v159, 0x3e38aa3b, v45
	s_waitcnt lgkmcnt(2)
	v_fmamk_f32 v43, v48, 0x3e38aa3b, v148
	v_fmac_f32_e32 v149, 0x3e38aa3b, v49
	v_max_f32_e32 v36, v160, v151
	v_fmamk_f32 v154, v42, 0x3e38aa3b, v156
	v_fmamk_f32 v44, v46, 0x3e38aa3b, v152
	v_fmac_f32_e32 v153, 0x3e38aa3b, v47
	v_max_f32_e32 v34, v200, v163
	v_max_f32_e32 v35, v199, v161
	v_max_f32_e32 v37, v150, v159
	v_max_f32_e32 v38, v43, v149
	v_max3_f32 v36, v162, v155, v36
	v_max3_f32 v37, v154, v157, v37
	v_max3_f32 v34, v34, v35, v36
	v_max3_f32 v35, v44, v153, v38
	v_max3_f32 v42, v34, v37, v35
	ds_bpermute_b32 v45, v167, v42
	v_add_u32_e32 v34, s18, v180
	v_add_u32_e32 v34, 0x6000, v34
	ds_read2_b64 v[38:41], v34 offset0:32 offset1:34
	ds_read2_b64 v[34:37], v34 offset0:36 offset1:38
	s_waitcnt lgkmcnt(2)
	v_max3_f32 v42, v198, v42, v45
	v_cmp_gt_f32_e32 vcc, v42, v198
	s_cbranch_vccz .LBB0_118
	v_sub_f32_e32 v45, v198, v42
	v_exp_f32_e32 v46, v45
	v_mov_b32_e32 v198, v42
	v_mul_f32_e32 v0, v0, v46
	v_pk_mul_f32 v[32:33], v[32:33], v[46:47] op_sel_hi:[1,0]
	v_pk_mul_f32 v[30:31], v[30:31], v[46:47] op_sel_hi:[1,0]
	v_pk_mul_f32 v[28:29], v[28:29], v[46:47] op_sel_hi:[1,0]
	v_pk_mul_f32 v[26:27], v[26:27], v[46:47] op_sel_hi:[1,0]
	v_pk_mul_f32 v[24:25], v[24:25], v[46:47] op_sel_hi:[1,0]
	v_pk_mul_f32 v[22:23], v[22:23], v[46:47] op_sel_hi:[1,0]
	v_pk_mul_f32 v[20:21], v[20:21], v[46:47] op_sel_hi:[1,0]
	v_pk_mul_f32 v[18:19], v[18:19], v[46:47] op_sel_hi:[1,0]
	v_pk_mul_f32 v[16:17], v[16:17], v[46:47] op_sel_hi:[1,0]
	v_pk_mul_f32 v[14:15], v[14:15], v[46:47] op_sel_hi:[1,0]
	v_pk_mul_f32 v[12:13], v[12:13], v[46:47] op_sel_hi:[1,0]
	v_pk_mul_f32 v[10:11], v[10:11], v[46:47] op_sel_hi:[1,0]
	v_pk_mul_f32 v[8:9], v[8:9], v[46:47] op_sel_hi:[1,0]
	v_pk_mul_f32 v[6:7], v[6:7], v[46:47] op_sel_hi:[1,0]
	v_pk_mul_f32 v[4:5], v[4:5], v[46:47] op_sel_hi:[1,0]
	v_pk_mul_f32 v[2:3], v[2:3], v[46:47] op_sel_hi:[1,0]
	s_branch .LBB0_119

; #define LAS __attribute__((address_space(3)))
; __device__ __forceinline__ void softmax2_pv(f32x16& sc, float& m, float& l, f32x16& o0, f32x16& o1, const bf16x8 (&vf)[2][2]) {
;     float tm = fmaxf(fmaxf(sc[0], sc[1]), fmaxf(sc[2], sc[3]));
; #pragma unroll
;     for (int i = 4; i < 16; i += 4) tm = fmaxf(tm, fmaxf(fmaxf(sc[i], sc[i + 1]), fmaxf(sc[i + 2], sc[i + 3])));
;     tm = fmaxf(tm, __shfl_xor(tm, 32));
;     const float mn = fmaxf(m, tm);
;     if (__builtin_amdgcn_ballot_w64(mn > m)) {
;         const float alpha = __builtin_amdgcn_exp2f(m - mn);
;         l *= alpha;
; #pragma unroll
;         for (int i = 0; i < 16; ++i) { o0[i] *= alpha; o1[i] *= alpha; }
;         m = mn;
;     }
; __device__ __forceinline__ void gqa_phase(const PP P, LAS unsigned char* lds, int tid, int cb, int G) {
;     ...
;             for (int t = 0; t < 9; ++t) {
;                 const int kr0 = qoff + 32 * t, tok0 = m0 - 128 + kr0;
;                 if (tok0 < row0 || tok0 >= row0 + L) continue;
;                 bf16x8 kf[4];
; #pragma unroll
;                 for (int ds = 0; ds < 4; ++ds) kf[ds] = *(const LAS bf16x8*)(lds + GQ_K + (kr0 + r32) * GK_PITCH + (16 * ds + 8 * hi) * 2);
;                 bf16x8 vf[2][2];
; #pragma unroll
;                 for (int dh = 0; dh < 2; ++dh)
; #pragma unroll
;                     for (int s = 0; s < 2; ++s) { const LAS s16x4* vp = (const LAS s16x4*)(lds + GQ_V + (dh * 32 + r32) * GV_PITCH + (kr0 + 16 * s + 4 * hi) * 2);
;                         const s16x4 a = vp[0], c2 = vp[2]; vf[dh][s] = (bf16x8){a[0], a[1], a[2], a[3], c2[0], c2[1], c2[2], c2[3]}; }
;                 f32x16 sc = {};
; #pragma unroll
;                 for (int ds = 0; ds < 4; ++ds) sc = MFMA32(kf[ds], qr[ds], sc);
;                 const int ib = 32 * t - r32 + 4 * hi;
;                 if (t == 0 || t == 8) {
; #pragma unroll
;                     for (int i = 0; i < 16; ++i) { const int ix = ib + (i & 3) + 8 * (i >> 2); const bool valid = ix >= 0 && ix <= 256; const float bb = tbl[valid ? ix : 0];
;                         sc[i] = valid ? sc[i] * (0.125f * LOG2E) + bb : NEGBIG; }
;                 } else {
; #pragma unroll
;                     for (int i = 0; i < 16; ++i) sc[i] = sc[i] * (0.125f * LOG2E) + tbl[ib + (i & 3) + 8 * (i >> 2)];
;                 }
;                 softmax2_pv(sc, m, l, o0, o1, vf);
.LBB0_120:
	s_add_i32 s18, s22, 64
	s_add_i32 s19, s35, s18
	s_cmp_ge_i32 s19, s3
	s_cselect_b64 s[24:25], -1, 0
	s_cmp_lt_i32 s19, s20
	s_cselect_b64 vcc, -1, 0
	s_and_b64 s[24:25], s[24:25], vcc
	s_andn2_b64 vcc, exec, s[24:25]
	s_cbranch_vccnz .LBB0_125
	v_or_b32_e32 v34, s18, v164
	v_mad_u32_u24 v118, v34, s26, v166
	ds_read_b128 v[34:37], v118
	ds_read_b128 v[114:117], v118 offset:32
	s_lshl_b32 s18, s18, 1
	s_waitcnt lgkmcnt(1)
	v_mfma_f32_32x32x16_bf16 v[34:49], v[34:37], v[110:113], 0
	s_waitcnt lgkmcnt(0)
	v_mfma_f32_32x32x16_bf16 v[34:49], v[114:117], v[106:109], v[34:49]
	ds_read_b128 v[114:117], v118 offset:64
	ds_read2_b32 v[162:163], v181 offset0:64 offset1:65
	ds_read2_b32 v[160:161], v181 offset0:66 offset1:67
	ds_read2_b32 v[154:155], v181 offset0:72 offset1:73
	ds_read2_b32 v[150:151], v181 offset0:74 offset1:75
	ds_read_b128 v[206:209], v118 offset:96
	ds_read2_b32 v[156:157], v181 offset0:80 offset1:81
	ds_read2_b32 v[158:159], v181 offset0:82 offset1:83
	ds_read2_b32 v[152:153], v181 offset0:88 offset1:89
	ds_read2_b32 v[148:149], v181 offset0:90 offset1:91
	s_waitcnt lgkmcnt(9)
	v_mfma_f32_32x32x16_bf16 v[34:49], v[114:117], v[102:105], v[34:49]
	v_add_u32_e32 v114, s18, v179
	v_add_u32_e32 v114, 0xd800, v114
	ds_read2_b64 v[118:121], v114 offset1:2
	ds_read2_b64 v[114:117], v114 offset0:4 offset1:6
	s_waitcnt lgkmcnt(6)
	v_mfma_f32_32x32x16_bf16 v[34:49], v[206:209], v[98:101], v[34:49]
	s_nop 11
	v_fmamk_f32 v199, v36, 0x3e38aa3b, v160
	v_fmamk_f32 v160, v40, 0x3e38aa3b, v150
	v_fmac_f32_e32 v151, 0x3e38aa3b, v41
	v_fmamk_f32 v200, v34, 0x3e38aa3b, v162
	v_fmac_f32_e32 v163, 0x3e38aa3b, v35
	v_fmac_f32_e32 v161, 0x3e38aa3b, v37
	v_fmamk_f32 v162, v38, 0x3e38aa3b, v154
	v_fmac_f32_e32 v155, 0x3e38aa3b, v39
	s_waitcnt lgkmcnt(5)
	v_fmac_f32_e32 v157, 0x3e38aa3b, v43
	s_waitcnt lgkmcnt(4)
	v_fmamk_f32 v150, v44, 0x3e38aa3b, v158
	v_fmac_f32_e32 v159, 0x3e38aa3b, v45
	s_waitcnt lgkmcnt(2)
	v_fmamk_f32 v43, v48, 0x3e38aa3b, v148
	v_fmac_f32_e32 v149, 0x3e38aa3b, v49
	v_max_f32_e32 v36, v160, v151
	v_fmamk_f32 v154, v42, 0x3e38aa3b, v156
	v_fmamk_f32 v44, v46, 0x3e38aa3b, v152
	v_fmac_f32_e32 v153, 0x3e38aa3b, v47
	v_max_f32_e32 v34, v200, v163
	v_max_f32_e32 v35, v199, v161
	v_max_f32_e32 v37, v150, v159
	v_max_f32_e32 v38, v43, v149
	v_max3_f32 v36, v162, v155, v36
	v_max3_f32 v37, v154, v157, v37
	v_max3_f32 v34, v34, v35, v36
	v_max3_f32 v35, v44, v153, v38
	v_max3_f32 v42, v34, v37, v35
	ds_bpermute_b32 v45, v167, v42
	v_add_u32_e32 v34, s18, v180
	v_add_u32_e32 v34, 0x6000, v34
	ds_read2_b64 v[38:41], v34 offset0:32 offset1:34
	ds_read2_b64 v[34:37], v34 offset0:36 offset1:38
	s_waitcnt lgkmcnt(2)
	v_max3_f32 v42, v198, v42, v45
	v_cmp_gt_f32_e32 vcc, v42, v198
	s_cbranch_vccz .LBB0_123
	v_sub_f32_e32 v45, v198, v42
	v_exp_f32_e32 v46, v45
	v_mov_b32_e32 v198, v42
	v_mul_f32_e32 v0, v0, v46
	v_pk_mul_f32 v[32:33], v[32:33], v[46:47] op_sel_hi:[1,0]
	v_pk_mul_f32 v[30:31], v[30:31], v[46:47] op_sel_hi:[1,0]
	v_pk_mul_f32 v[28:29], v[28:29], v[46:47] op_sel_hi:[1,0]
	v_pk_mul_f32 v[26:27], v[26:27], v[46:47] op_sel_hi:[1,0]
	v_pk_mul_f32 v[24:25], v[24:25], v[46:47] op_sel_hi:[1,0]
	v_pk_mul_f32 v[22:23], v[22:23], v[46:47] op_sel_hi:[1,0]
	v_pk_mul_f32 v[20:21], v[20:21], v[46:47] op_sel_hi:[1,0]
	v_pk_mul_f32 v[18:19], v[18:19], v[46:47] op_sel_hi:[1,0]
	v_pk_mul_f32 v[16:17], v[16:17], v[46:47] op_sel_hi:[1,0]
	v_pk_mul_f32 v[14:15], v[14:15], v[46:47] op_sel_hi:[1,0]
	v_pk_mul_f32 v[12:13], v[12:13], v[46:47] op_sel_hi:[1,0]
	v_pk_mul_f32 v[10:11], v[10:11], v[46:47] op_sel_hi:[1,0]
	v_pk_mul_f32 v[8:9], v[8:9], v[46:47] op_sel_hi:[1,0]
	v_pk_mul_f32 v[6:7], v[6:7], v[46:47] op_sel_hi:[1,0]
	v_pk_mul_f32 v[4:5], v[4:5], v[46:47] op_sel_hi:[1,0]
	v_pk_mul_f32 v[2:3], v[2:3], v[46:47] op_sel_hi:[1,0]
	s_branch .LBB0_124

; #define LAS __attribute__((address_space(3)))
; __device__ __forceinline__ void softmax2_pv(f32x16& sc, float& m, float& l, f32x16& o0, f32x16& o1, const bf16x8 (&vf)[2][2]) {
;     float tm = fmaxf(fmaxf(sc[0], sc[1]), fmaxf(sc[2], sc[3]));
; #pragma unroll
;     for (int i = 4; i < 16; i += 4) tm = fmaxf(tm, fmaxf(fmaxf(sc[i], sc[i + 1]), fmaxf(sc[i + 2], sc[i + 3])));
;     tm = fmaxf(tm, __shfl_xor(tm, 32));
;     const float mn = fmaxf(m, tm);
;     if (__builtin_amdgcn_ballot_w64(mn > m)) {
;         const float alpha = __builtin_amdgcn_exp2f(m - mn);
;         l *= alpha;
; #pragma unroll
;         for (int i = 0; i < 16; ++i) { o0[i] *= alpha; o1[i] *= alpha; }
;         m = mn;
;     }
; __device__ __forceinline__ void gqa_phase(const PP P, LAS unsigned char* lds, int tid, int cb, int G) {
;     ...
;             for (int t = 0; t < 9; ++t) {
;                 const int kr0 = qoff + 32 * t, tok0 = m0 - 128 + kr0;
;                 if (tok0 < row0 || tok0 >= row0 + L) continue;
;                 bf16x8 kf[4];
; #pragma unroll
;                 for (int ds = 0; ds < 4; ++ds) kf[ds] = *(const LAS bf16x8*)(lds + GQ_K + (kr0 + r32) * GK_PITCH + (16 * ds + 8 * hi) * 2);
;                 bf16x8 vf[2][2];
; #pragma unroll
;                 for (int dh = 0; dh < 2; ++dh)
; #pragma unroll
;                     for (int s = 0; s < 2; ++s) { const LAS s16x4* vp = (const LAS s16x4*)(lds + GQ_V + (dh * 32 + r32) * GV_PITCH + (kr0 + 16 * s + 4 * hi) * 2);
;                         const s16x4 a = vp[0], c2 = vp[2]; vf[dh][s] = (bf16x8){a[0], a[1], a[2], a[3], c2[0], c2[1], c2[2], c2[3]}; }
;                 f32x16 sc = {};
; #pragma unroll
;                 for (int ds = 0; ds < 4; ++ds) sc = MFMA32(kf[ds], qr[ds], sc);
;                 const int ib = 32 * t - r32 + 4 * hi;
;                 if (t == 0 || t == 8) {
; #pragma unroll
;                     for (int i = 0; i < 16; ++i) { const int ix = ib + (i & 3) + 8 * (i >> 2); const bool valid = ix >= 0 && ix <= 256; const float bb = tbl[valid ? ix : 0];
;                         sc[i] = valid ? sc[i] * (0.125f * LOG2E) + bb : NEGBIG; }
;                 } else {
; #pragma unroll
;                     for (int i = 0; i < 16; ++i) sc[i] = sc[i] * (0.125f * LOG2E) + tbl[ib + (i & 3) + 8 * (i >> 2)];
;                 }
;                 softmax2_pv(sc, m, l, o0, o1, vf);
.LBB0_125:
	s_add_i32 s18, s22, 0x60
	s_add_i32 s19, s35, s18
	s_cmp_ge_i32 s19, s3
	s_cselect_b64 s[24:25], -1, 0
	s_cmp_lt_i32 s19, s20
	s_cselect_b64 vcc, -1, 0
	s_and_b64 s[24:25], s[24:25], vcc
	s_andn2_b64 vcc, exec, s[24:25]
	s_cbranch_vccnz .LBB0_130
	v_or_b32_e32 v34, s18, v164
	v_mad_u32_u24 v118, v34, s26, v166
	ds_read_b128 v[34:37], v118
	ds_read_b128 v[114:117], v118 offset:32
	s_lshl_b32 s18, s18, 1
	s_waitcnt lgkmcnt(1)
	v_mfma_f32_32x32x16_bf16 v[34:49], v[34:37], v[110:113], 0
	s_waitcnt lgkmcnt(0)
	v_mfma_f32_32x32x16_bf16 v[34:49], v[114:117], v[106:109], v[34:49]
	ds_read_b128 v[114:117], v118 offset:64
	ds_read2_b32 v[162:163], v181 offset0:96 offset1:97
	ds_read2_b32 v[160:161], v181 offset0:98 offset1:99
	ds_read2_b32 v[154:155], v181 offset0:104 offset1:105
	ds_read2_b32 v[150:151], v181 offset0:106 offset1:107
	ds_read_b128 v[206:209], v118 offset:96
	ds_read2_b32 v[156:157], v181 offset0:112 offset1:113
	ds_read2_b32 v[158:159], v181 offset0:114 offset1:115
	ds_read2_b32 v[152:153], v181 offset0:120 offset1:121
	ds_read2_b32 v[148:149], v181 offset0:122 offset1:123
	s_waitcnt lgkmcnt(9)
	v_mfma_f32_32x32x16_bf16 v[34:49], v[114:117], v[102:105], v[34:49]
	v_add_u32_e32 v114, s18, v179
	v_add_u32_e32 v114, 0xd800, v114
	ds_read2_b64 v[118:121], v114 offset1:2
	ds_read2_b64 v[114:117], v114 offset0:4 offset1:6
	s_waitcnt lgkmcnt(6)
	v_mfma_f32_32x32x16_bf16 v[34:49], v[206:209], v[98:101], v[34:49]
	s_nop 11
	v_fmamk_f32 v199, v36, 0x3e38aa3b, v160
	v_fmamk_f32 v160, v40, 0x3e38aa3b, v150
	v_fmac_f32_e32 v151, 0x3e38aa3b, v41
	v_fmamk_f32 v200, v34, 0x3e38aa3b, v162
	v_fmac_f32_e32 v163, 0x3e38aa3b, v35
	v_fmac_f32_e32 v161, 0x3e38aa3b, v37
	v_fmamk_f32 v162, v38, 0x3e38aa3b, v154
	v_fmac_f32_e32 v155, 0x3e38aa3b, v39
	s_waitcnt lgkmcnt(5)
	v_fmac_f32_e32 v157, 0x3e38aa3b, v43
	s_waitcnt lgkmcnt(4)
	v_fmamk_f32 v150, v44, 0x3e38aa3b, v158
	v_fmac_f32_e32 v159, 0x3e38aa3b, v45
	s_waitcnt lgkmcnt(2)
	v_fmamk_f32 v43, v48, 0x3e38aa3b, v148
	v_fmac_f32_e32 v149, 0x3e38aa3b, v49
	v_max_f32_e32 v36, v160, v151
	v_fmamk_f32 v154, v42, 0x3e38aa3b, v156
	v_fmamk_f32 v44, v46, 0x3e38aa3b, v152
	v_fmac_f32_e32 v153, 0x3e38aa3b, v47
	v_max_f32_e32 v34, v200, v163
	v_max_f32_e32 v35, v199, v161
	v_max_f32_e32 v37, v150, v159
	v_max_f32_e32 v38, v43, v149
	v_max3_f32 v36, v162, v155, v36
	v_max3_f32 v37, v154, v157, v37
	v_max3_f32 v34, v34, v35, v36
	v_max3_f32 v35, v44, v153, v38
	v_max3_f32 v42, v34, v37, v35
	ds_bpermute_b32 v45, v167, v42
	v_add_u32_e32 v34, s18, v180
	v_add_u32_e32 v34, 0x6000, v34
	ds_read2_b64 v[38:41], v34 offset0:32 offset1:34
	ds_read2_b64 v[34:37], v34 offset0:36 offset1:38
	s_waitcnt lgkmcnt(2)
	v_max3_f32 v42, v198, v42, v45
	v_cmp_gt_f32_e32 vcc, v42, v198
	s_cbranch_vccz .LBB0_128
	v_sub_f32_e32 v45, v198, v42
	v_exp_f32_e32 v46, v45
	v_mov_b32_e32 v198, v42
	v_mul_f32_e32 v0, v0, v46
	v_pk_mul_f32 v[32:33], v[32:33], v[46:47] op_sel_hi:[1,0]
	v_pk_mul_f32 v[30:31], v[30:31], v[46:47] op_sel_hi:[1,0]
	v_pk_mul_f32 v[28:29], v[28:29], v[46:47] op_sel_hi:[1,0]
	v_pk_mul_f32 v[26:27], v[26:27], v[46:47] op_sel_hi:[1,0]
	v_pk_mul_f32 v[24:25], v[24:25], v[46:47] op_sel_hi:[1,0]
	v_pk_mul_f32 v[22:23], v[22:23], v[46:47] op_sel_hi:[1,0]
	v_pk_mul_f32 v[20:21], v[20:21], v[46:47] op_sel_hi:[1,0]
	v_pk_mul_f32 v[18:19], v[18:19], v[46:47] op_sel_hi:[1,0]
	v_pk_mul_f32 v[16:17], v[16:17], v[46:47] op_sel_hi:[1,0]
	v_pk_mul_f32 v[14:15], v[14:15], v[46:47] op_sel_hi:[1,0]
	v_pk_mul_f32 v[12:13], v[12:13], v[46:47] op_sel_hi:[1,0]
	v_pk_mul_f32 v[10:11], v[10:11], v[46:47] op_sel_hi:[1,0]
	v_pk_mul_f32 v[8:9], v[8:9], v[46:47] op_sel_hi:[1,0]
	v_pk_mul_f32 v[6:7], v[6:7], v[46:47] op_sel_hi:[1,0]
	v_pk_mul_f32 v[4:5], v[4:5], v[46:47] op_sel_hi:[1,0]
	v_pk_mul_f32 v[2:3], v[2:3], v[46:47] op_sel_hi:[1,0]
	s_branch .LBB0_129

; #define LAS __attribute__((address_space(3)))
; __device__ __forceinline__ void softmax2_pv(f32x16& sc, float& m, float& l, f32x16& o0, f32x16& o1, const bf16x8 (&vf)[2][2]) {
;     float tm = fmaxf(fmaxf(sc[0], sc[1]), fmaxf(sc[2], sc[3]));
; #pragma unroll
;     for (int i = 4; i < 16; i += 4) tm = fmaxf(tm, fmaxf(fmaxf(sc[i], sc[i + 1]), fmaxf(sc[i + 2], sc[i + 3])));
;     tm = fmaxf(tm, __shfl_xor(tm, 32));
;     const float mn = fmaxf(m, tm);
;     if (__builtin_amdgcn_ballot_w64(mn > m)) {
;         const float alpha = __builtin_amdgcn_exp2f(m - mn);
;         l *= alpha;
; #pragma unroll
;         for (int i = 0; i < 16; ++i) { o0[i] *= alpha; o1[i] *= alpha; }
;         m = mn;
;     }
; __device__ __forceinline__ void gqa_phase(const PP P, LAS unsigned char* lds, int tid, int cb, int G) {
;     ...
;             for (int t = 0; t < 9; ++t) {
;                 const int kr0 = qoff + 32 * t, tok0 = m0 - 128 + kr0;
;                 if (tok0 < row0 || tok0 >= row0 + L) continue;
;                 bf16x8 kf[4];
; #pragma unroll
;                 for (int ds = 0; ds < 4; ++ds) kf[ds] = *(const LAS bf16x8*)(lds + GQ_K + (kr0 + r32) * GK_PITCH + (16 * ds + 8 * hi) * 2);
;                 bf16x8 vf[2][2];
; #pragma unroll
;                 for (int dh = 0; dh < 2; ++dh)
; #pragma unroll
;                     for (int s = 0; s < 2; ++s) { const LAS s16x4* vp = (const LAS s16x4*)(lds + GQ_V + (dh * 32 + r32) * GV_PITCH + (kr0 + 16 * s + 4 * hi) * 2);
;                         const s16x4 a = vp[0], c2 = vp[2]; vf[dh][s] = (bf16x8){a[0], a[1], a[2], a[3], c2[0], c2[1], c2[2], c2[3]}; }
;                 f32x16 sc = {};
; #pragma unroll
;                 for (int ds = 0; ds < 4; ++ds) sc = MFMA32(kf[ds], qr[ds], sc);
;                 const int ib = 32 * t - r32 + 4 * hi;
;                 if (t == 0 || t == 8) {
; #pragma unroll
;                     for (int i = 0; i < 16; ++i) { const int ix = ib + (i & 3) + 8 * (i >> 2); const bool valid = ix >= 0 && ix <= 256; const float bb = tbl[valid ? ix : 0];
;                         sc[i] = valid ? sc[i] * (0.125f * LOG2E) + bb : NEGBIG; }
;                 } else {
; #pragma unroll
;                     for (int i = 0; i < 16; ++i) sc[i] = sc[i] * (0.125f * LOG2E) + tbl[ib + (i & 3) + 8 * (i >> 2)];
;                 }
;                 softmax2_pv(sc, m, l, o0, o1, vf);
.LBB0_130:
	s_or_b32 s18, s22, 0x80
	s_add_i32 s19, s35, s18
	s_cmp_ge_i32 s19, s3
	s_cselect_b64 s[24:25], -1, 0
	s_cmp_lt_i32 s19, s20
	s_cselect_b64 vcc, -1, 0
	s_and_b64 s[24:25], s[24:25], vcc
	s_andn2_b64 vcc, exec, s[24:25]
	s_cbranch_vccnz .LBB0_135
	v_or_b32_e32 v34, s18, v164
	v_mad_u32_u24 v118, v34, s26, v166
	ds_read_b128 v[34:37], v118
	ds_read_b128 v[114:117], v118 offset:32
	s_lshl_b32 s18, s18, 1
	s_waitcnt lgkmcnt(1)
	v_mfma_f32_32x32x16_bf16 v[34:49], v[34:37], v[110:113], 0
	s_waitcnt lgkmcnt(0)
	v_mfma_f32_32x32x16_bf16 v[34:49], v[114:117], v[106:109], v[34:49]
	ds_read_b128 v[114:117], v118 offset:64
	ds_read2_b32 v[162:163], v181 offset0:128 offset1:129
	ds_read2_b32 v[160:161], v181 offset0:130 offset1:131
	ds_read2_b32 v[154:155], v181 offset0:136 offset1:137
	ds_read2_b32 v[150:151], v181 offset0:138 offset1:139
	ds_read_b128 v[206:209], v118 offset:96
	ds_read2_b32 v[156:157], v181 offset0:144 offset1:145
	ds_read2_b32 v[158:159], v181 offset0:146 offset1:147
	ds_read2_b32 v[152:153], v181 offset0:152 offset1:153
	ds_read2_b32 v[148:149], v181 offset0:154 offset1:155
	s_waitcnt lgkmcnt(9)
	v_mfma_f32_32x32x16_bf16 v[34:49], v[114:117], v[102:105], v[34:49]
	v_add_u32_e32 v114, s18, v179
	v_add_u32_e32 v114, 0xd800, v114
	ds_read2_b64 v[118:121], v114 offset1:2
	ds_read2_b64 v[114:117], v114 offset0:4 offset1:6
	s_waitcnt lgkmcnt(6)
	v_mfma_f32_32x32x16_bf16 v[34:49], v[206:209], v[98:101], v[34:49]
	s_nop 11
	v_fmamk_f32 v199, v36, 0x3e38aa3b, v160
	v_fmamk_f32 v160, v40, 0x3e38aa3b, v150
	v_fmac_f32_e32 v151, 0x3e38aa3b, v41
	v_fmamk_f32 v200, v34, 0x3e38aa3b, v162
	v_fmac_f32_e32 v163, 0x3e38aa3b, v35
	v_fmac_f32_e32 v161, 0x3e38aa3b, v37
	v_fmamk_f32 v162, v38, 0x3e38aa3b, v154
	v_fmac_f32_e32 v155, 0x3e38aa3b, v39
	s_waitcnt lgkmcnt(5)
	v_fmac_f32_e32 v157, 0x3e38aa3b, v43
	s_waitcnt lgkmcnt(4)
	v_fmamk_f32 v150, v44, 0x3e38aa3b, v158
	v_fmac_f32_e32 v159, 0x3e38aa3b, v45
	s_waitcnt lgkmcnt(2)
	v_fmamk_f32 v43, v48, 0x3e38aa3b, v148
	v_fmac_f32_e32 v149, 0x3e38aa3b, v49
	v_max_f32_e32 v36, v160, v151
	v_fmamk_f32 v154, v42, 0x3e38aa3b, v156
	v_fmamk_f32 v44, v46, 0x3e38aa3b, v152
	v_fmac_f32_e32 v153, 0x3e38aa3b, v47
	v_max_f32_e32 v34, v200, v163
	v_max_f32_e32 v35, v199, v161
	v_max_f32_e32 v37, v150, v159
	v_max_f32_e32 v38, v43, v149
	v_max3_f32 v36, v162, v155, v36
	v_max3_f32 v37, v154, v157, v37
	v_max3_f32 v34, v34, v35, v36
	v_max3_f32 v35, v44, v153, v38
	v_max3_f32 v42, v34, v37, v35
	ds_bpermute_b32 v45, v167, v42
	v_add_u32_e32 v34, s18, v180
	v_add_u32_e32 v34, 0x6000, v34
	ds_read2_b64 v[38:41], v34 offset0:32 offset1:34
	ds_read2_b64 v[34:37], v34 offset0:36 offset1:38
	s_waitcnt lgkmcnt(2)
	v_max3_f32 v42, v198, v42, v45
	v_cmp_gt_f32_e32 vcc, v42, v198
	s_cbranch_vccz .LBB0_133
	v_sub_f32_e32 v45, v198, v42
	v_exp_f32_e32 v46, v45
	v_mov_b32_e32 v198, v42
	v_mul_f32_e32 v0, v0, v46
	v_pk_mul_f32 v[32:33], v[32:33], v[46:47] op_sel_hi:[1,0]
	v_pk_mul_f32 v[30:31], v[30:31], v[46:47] op_sel_hi:[1,0]
	v_pk_mul_f32 v[28:29], v[28:29], v[46:47] op_sel_hi:[1,0]
	v_pk_mul_f32 v[26:27], v[26:27], v[46:47] op_sel_hi:[1,0]
	v_pk_mul_f32 v[24:25], v[24:25], v[46:47] op_sel_hi:[1,0]
	v_pk_mul_f32 v[22:23], v[22:23], v[46:47] op_sel_hi:[1,0]
	v_pk_mul_f32 v[20:21], v[20:21], v[46:47] op_sel_hi:[1,0]
	v_pk_mul_f32 v[18:19], v[18:19], v[46:47] op_sel_hi:[1,0]
	v_pk_mul_f32 v[16:17], v[16:17], v[46:47] op_sel_hi:[1,0]
	v_pk_mul_f32 v[14:15], v[14:15], v[46:47] op_sel_hi:[1,0]
	v_pk_mul_f32 v[12:13], v[12:13], v[46:47] op_sel_hi:[1,0]
	v_pk_mul_f32 v[10:11], v[10:11], v[46:47] op_sel_hi:[1,0]
	v_pk_mul_f32 v[8:9], v[8:9], v[46:47] op_sel_hi:[1,0]
	v_pk_mul_f32 v[6:7], v[6:7], v[46:47] op_sel_hi:[1,0]
	v_pk_mul_f32 v[4:5], v[4:5], v[46:47] op_sel_hi:[1,0]
	v_pk_mul_f32 v[2:3], v[2:3], v[46:47] op_sel_hi:[1,0]
	s_branch .LBB0_134

; #define LAS __attribute__((address_space(3)))
; __device__ __forceinline__ void softmax2_pv(f32x16& sc, float& m, float& l, f32x16& o0, f32x16& o1, const bf16x8 (&vf)[2][2]) {
;     float tm = fmaxf(fmaxf(sc[0], sc[1]), fmaxf(sc[2], sc[3]));
; #pragma unroll
;     for (int i = 4; i < 16; i += 4) tm = fmaxf(tm, fmaxf(fmaxf(sc[i], sc[i + 1]), fmaxf(sc[i + 2], sc[i + 3])));
;     tm = fmaxf(tm, __shfl_xor(tm, 32));
;     const float mn = fmaxf(m, tm);
;     if (__builtin_amdgcn_ballot_w64(mn > m)) {
;         const float alpha = __builtin_amdgcn_exp2f(m - mn);
;         l *= alpha;
; #pragma unroll
;         for (int i = 0; i < 16; ++i) { o0[i] *= alpha; o1[i] *= alpha; }
;         m = mn;
;     }
; __device__ __forceinline__ void gqa_phase(const PP P, LAS unsigned char* lds, int tid, int cb, int G) {
;     ...
;             for (int t = 0; t < 9; ++t) {
;                 const int kr0 = qoff + 32 * t, tok0 = m0 - 128 + kr0;
;                 if (tok0 < row0 || tok0 >= row0 + L) continue;
;                 bf16x8 kf[4];
; #pragma unroll
;                 for (int ds = 0; ds < 4; ++ds) kf[ds] = *(const LAS bf16x8*)(lds + GQ_K + (kr0 + r32) * GK_PITCH + (16 * ds + 8 * hi) * 2);
;                 bf16x8 vf[2][2];
; #pragma unroll
;                 for (int dh = 0; dh < 2; ++dh)
; #pragma unroll
;                     for (int s = 0; s < 2; ++s) { const LAS s16x4* vp = (const LAS s16x4*)(lds + GQ_V + (dh * 32 + r32) * GV_PITCH + (kr0 + 16 * s + 4 * hi) * 2);
;                         const s16x4 a = vp[0], c2 = vp[2]; vf[dh][s] = (bf16x8){a[0], a[1], a[2], a[3], c2[0], c2[1], c2[2], c2[3]}; }
;                 f32x16 sc = {};
; #pragma unroll
;                 for (int ds = 0; ds < 4; ++ds) sc = MFMA32(kf[ds], qr[ds], sc);
;                 const int ib = 32 * t - r32 + 4 * hi;
;                 if (t == 0 || t == 8) {
; #pragma unroll
;                     for (int i = 0; i < 16; ++i) { const int ix = ib + (i & 3) + 8 * (i >> 2); const bool valid = ix >= 0 && ix <= 256; const float bb = tbl[valid ? ix : 0];
;                         sc[i] = valid ? sc[i] * (0.125f * LOG2E) + bb : NEGBIG; }
;                 } else {
; #pragma unroll
;                     for (int i = 0; i < 16; ++i) sc[i] = sc[i] * (0.125f * LOG2E) + tbl[ib + (i & 3) + 8 * (i >> 2)];
;                 }
;                 softmax2_pv(sc, m, l, o0, o1, vf);
.LBB0_135:
	s_add_i32 s18, s22, 0xa0
	s_add_i32 s19, s35, s18
	s_cmp_ge_i32 s19, s3
	s_cselect_b64 s[24:25], -1, 0
	s_cmp_lt_i32 s19, s20
	s_cselect_b64 vcc, -1, 0
	s_and_b64 s[24:25], s[24:25], vcc
	s_andn2_b64 vcc, exec, s[24:25]
	s_cbranch_vccnz .LBB0_140
	v_or_b32_e32 v34, s18, v164
	v_mad_u32_u24 v118, v34, s26, v166
	ds_read_b128 v[34:37], v118
	ds_read_b128 v[114:117], v118 offset:32
	s_lshl_b32 s18, s18, 1
	s_waitcnt lgkmcnt(1)
	v_mfma_f32_32x32x16_bf16 v[34:49], v[34:37], v[110:113], 0
	s_waitcnt lgkmcnt(0)
	v_mfma_f32_32x32x16_bf16 v[34:49], v[114:117], v[106:109], v[34:49]
	ds_read_b128 v[114:117], v118 offset:64
	ds_read2_b32 v[162:163], v181 offset0:160 offset1:161
	ds_read2_b32 v[160:161], v181 offset0:162 offset1:163
	ds_read2_b32 v[154:155], v181 offset0:168 offset1:169
	ds_read2_b32 v[150:151], v181 offset0:170 offset1:171
	ds_read_b128 v[206:209], v118 offset:96
	ds_read2_b32 v[156:157], v181 offset0:176 offset1:177
	ds_read2_b32 v[158:159], v181 offset0:178 offset1:179
	ds_read2_b32 v[152:153], v181 offset0:184 offset1:185
	ds_read2_b32 v[148:149], v181 offset0:186 offset1:187
	s_waitcnt lgkmcnt(9)
	v_mfma_f32_32x32x16_bf16 v[34:49], v[114:117], v[102:105], v[34:49]
	v_add_u32_e32 v114, s18, v179
	v_add_u32_e32 v114, 0xd800, v114
	ds_read2_b64 v[118:121], v114 offset1:2
	ds_read2_b64 v[114:117], v114 offset0:4 offset1:6
	s_waitcnt lgkmcnt(6)
	v_mfma_f32_32x32x16_bf16 v[34:49], v[206:209], v[98:101], v[34:49]
	s_nop 11
	v_fmamk_f32 v199, v36, 0x3e38aa3b, v160
	v_fmamk_f32 v160, v40, 0x3e38aa3b, v150
	v_fmac_f32_e32 v151, 0x3e38aa3b, v41
	v_fmamk_f32 v200, v34, 0x3e38aa3b, v162
	v_fmac_f32_e32 v163, 0x3e38aa3b, v35
	v_fmac_f32_e32 v161, 0x3e38aa3b, v37
	v_fmamk_f32 v162, v38, 0x3e38aa3b, v154
	v_fmac_f32_e32 v155, 0x3e38aa3b, v39
	s_waitcnt lgkmcnt(5)
	v_fmac_f32_e32 v157, 0x3e38aa3b, v43
	s_waitcnt lgkmcnt(4)
	v_fmamk_f32 v150, v44, 0x3e38aa3b, v158
	v_fmac_f32_e32 v159, 0x3e38aa3b, v45
	s_waitcnt lgkmcnt(2)
	v_fmamk_f32 v43, v48, 0x3e38aa3b, v148
	v_fmac_f32_e32 v149, 0x3e38aa3b, v49
	v_max_f32_e32 v36, v160, v151
	v_fmamk_f32 v154, v42, 0x3e38aa3b, v156
	v_fmamk_f32 v44, v46, 0x3e38aa3b, v152
	v_fmac_f32_e32 v153, 0x3e38aa3b, v47
	v_max_f32_e32 v34, v200, v163
	v_max_f32_e32 v35, v199, v161
	v_max_f32_e32 v37, v150, v159
	v_max_f32_e32 v38, v43, v149
	v_max3_f32 v36, v162, v155, v36
	v_max3_f32 v37, v154, v157, v37
	v_max3_f32 v34, v34, v35, v36
	v_max3_f32 v35, v44, v153, v38
	v_max3_f32 v42, v34, v37, v35
	ds_bpermute_b32 v45, v167, v42
	v_add_u32_e32 v34, s18, v180
	v_add_u32_e32 v34, 0x6000, v34
	ds_read2_b64 v[38:41], v34 offset0:32 offset1:34
	ds_read2_b64 v[34:37], v34 offset0:36 offset1:38
	s_waitcnt lgkmcnt(2)
	v_max3_f32 v42, v198, v42, v45
	v_cmp_gt_f32_e32 vcc, v42, v198
	s_cbranch_vccz .LBB0_138
	v_sub_f32_e32 v45, v198, v42
	v_exp_f32_e32 v46, v45
	v_mov_b32_e32 v198, v42
	v_mul_f32_e32 v0, v0, v46
	v_pk_mul_f32 v[32:33], v[32:33], v[46:47] op_sel_hi:[1,0]
	v_pk_mul_f32 v[30:31], v[30:31], v[46:47] op_sel_hi:[1,0]
	v_pk_mul_f32 v[28:29], v[28:29], v[46:47] op_sel_hi:[1,0]
	v_pk_mul_f32 v[26:27], v[26:27], v[46:47] op_sel_hi:[1,0]
	v_pk_mul_f32 v[24:25], v[24:25], v[46:47] op_sel_hi:[1,0]
	v_pk_mul_f32 v[22:23], v[22:23], v[46:47] op_sel_hi:[1,0]
	v_pk_mul_f32 v[20:21], v[20:21], v[46:47] op_sel_hi:[1,0]
	v_pk_mul_f32 v[18:19], v[18:19], v[46:47] op_sel_hi:[1,0]
	v_pk_mul_f32 v[16:17], v[16:17], v[46:47] op_sel_hi:[1,0]
	v_pk_mul_f32 v[14:15], v[14:15], v[46:47] op_sel_hi:[1,0]
	v_pk_mul_f32 v[12:13], v[12:13], v[46:47] op_sel_hi:[1,0]
	v_pk_mul_f32 v[10:11], v[10:11], v[46:47] op_sel_hi:[1,0]
	v_pk_mul_f32 v[8:9], v[8:9], v[46:47] op_sel_hi:[1,0]
	v_pk_mul_f32 v[6:7], v[6:7], v[46:47] op_sel_hi:[1,0]
	v_pk_mul_f32 v[4:5], v[4:5], v[46:47] op_sel_hi:[1,0]
	v_pk_mul_f32 v[2:3], v[2:3], v[46:47] op_sel_hi:[1,0]
	s_branch .LBB0_139

; #define LAS __attribute__((address_space(3)))
; __device__ __forceinline__ void softmax2_pv(f32x16& sc, float& m, float& l, f32x16& o0, f32x16& o1, const bf16x8 (&vf)[2][2]) {
;     float tm = fmaxf(fmaxf(sc[0], sc[1]), fmaxf(sc[2], sc[3]));
; #pragma unroll
;     for (int i = 4; i < 16; i += 4) tm = fmaxf(tm, fmaxf(fmaxf(sc[i], sc[i + 1]), fmaxf(sc[i + 2], sc[i + 3])));
;     tm = fmaxf(tm, __shfl_xor(tm, 32));
;     const float mn = fmaxf(m, tm);
;     if (__builtin_amdgcn_ballot_w64(mn > m)) {
;         const float alpha = __builtin_amdgcn_exp2f(m - mn);
;         l *= alpha;
; #pragma unroll
;         for (int i = 0; i < 16; ++i) { o0[i] *= alpha; o1[i] *= alpha; }
;         m = mn;
;     }
; __device__ __forceinline__ void gqa_phase(const PP P, LAS unsigned char* lds, int tid, int cb, int G) {
;     ...
;             for (int t = 0; t < 9; ++t) {
;                 const int kr0 = qoff + 32 * t, tok0 = m0 - 128 + kr0;
;                 if (tok0 < row0 || tok0 >= row0 + L) continue;
;                 bf16x8 kf[4];
; #pragma unroll
;                 for (int ds = 0; ds < 4; ++ds) kf[ds] = *(const LAS bf16x8*)(lds + GQ_K + (kr0 + r32) * GK_PITCH + (16 * ds + 8 * hi) * 2);
;                 bf16x8 vf[2][2];
; #pragma unroll
;                 for (int dh = 0; dh < 2; ++dh)
; #pragma unroll
;                     for (int s = 0; s < 2; ++s) { const LAS s16x4* vp = (const LAS s16x4*)(lds + GQ_V + (dh * 32 + r32) * GV_PITCH + (kr0 + 16 * s + 4 * hi) * 2);
;                         const s16x4 a = vp[0], c2 = vp[2]; vf[dh][s] = (bf16x8){a[0], a[1], a[2], a[3], c2[0], c2[1], c2[2], c2[3]}; }
;                 f32x16 sc = {};
; #pragma unroll
;                 for (int ds = 0; ds < 4; ++ds) sc = MFMA32(kf[ds], qr[ds], sc);
;                 const int ib = 32 * t - r32 + 4 * hi;
;                 if (t == 0 || t == 8) {
; #pragma unroll
;                     for (int i = 0; i < 16; ++i) { const int ix = ib + (i & 3) + 8 * (i >> 2); const bool valid = ix >= 0 && ix <= 256; const float bb = tbl[valid ? ix : 0];
;                         sc[i] = valid ? sc[i] * (0.125f * LOG2E) + bb : NEGBIG; }
;                 } else {
; #pragma unroll
;                     for (int i = 0; i < 16; ++i) sc[i] = sc[i] * (0.125f * LOG2E) + tbl[ib + (i & 3) + 8 * (i >> 2)];
;                 }
;                 softmax2_pv(sc, m, l, o0, o1, vf);
.LBB0_140:
	s_add_i32 s18, s22, 0xc0
	s_add_i32 s19, s35, s18
	s_cmp_ge_i32 s19, s3
	s_cselect_b64 s[24:25], -1, 0
	s_cmp_lt_i32 s19, s20
	s_cselect_b64 vcc, -1, 0
	s_and_b64 s[24:25], s[24:25], vcc
	s_andn2_b64 vcc, exec, s[24:25]
	s_cbranch_vccnz .LBB0_145
	v_or_b32_e32 v34, s18, v164
	v_mad_u32_u24 v118, v34, s26, v166
	ds_read_b128 v[34:37], v118
	ds_read_b128 v[114:117], v118 offset:32
	s_lshl_b32 s18, s18, 1
	s_waitcnt lgkmcnt(1)
	v_mfma_f32_32x32x16_bf16 v[34:49], v[34:37], v[110:113], 0
	s_waitcnt lgkmcnt(0)
	v_mfma_f32_32x32x16_bf16 v[34:49], v[114:117], v[106:109], v[34:49]
	ds_read_b128 v[114:117], v118 offset:64
	ds_read2_b32 v[162:163], v181 offset0:192 offset1:193
	ds_read2_b32 v[160:161], v181 offset0:194 offset1:195
	ds_read2_b32 v[154:155], v181 offset0:200 offset1:201
	ds_read2_b32 v[150:151], v181 offset0:202 offset1:203
	ds_read_b128 v[206:209], v118 offset:96
	ds_read2_b32 v[156:157], v181 offset0:208 offset1:209
	ds_read2_b32 v[158:159], v181 offset0:210 offset1:211
	ds_read2_b32 v[152:153], v181 offset0:216 offset1:217
	ds_read2_b32 v[148:149], v181 offset0:218 offset1:219
	s_waitcnt lgkmcnt(9)
	v_mfma_f32_32x32x16_bf16 v[34:49], v[114:117], v[102:105], v[34:49]
	v_add_u32_e32 v114, s18, v179
	v_add_u32_e32 v114, 0xd800, v114
	ds_read2_b64 v[118:121], v114 offset1:2
	ds_read2_b64 v[114:117], v114 offset0:4 offset1:6
	s_waitcnt lgkmcnt(6)
	v_mfma_f32_32x32x16_bf16 v[34:49], v[206:209], v[98:101], v[34:49]
	s_nop 11
	v_fmamk_f32 v199, v36, 0x3e38aa3b, v160
	v_fmamk_f32 v160, v40, 0x3e38aa3b, v150
	v_fmac_f32_e32 v151, 0x3e38aa3b, v41
	v_fmamk_f32 v200, v34, 0x3e38aa3b, v162
	v_fmac_f32_e32 v163, 0x3e38aa3b, v35
	v_fmac_f32_e32 v161, 0x3e38aa3b, v37
	v_fmamk_f32 v162, v38, 0x3e38aa3b, v154
	v_fmac_f32_e32 v155, 0x3e38aa3b, v39
	s_waitcnt lgkmcnt(5)
	v_fmac_f32_e32 v157, 0x3e38aa3b, v43
	s_waitcnt lgkmcnt(4)
	v_fmamk_f32 v150, v44, 0x3e38aa3b, v158
	v_fmac_f32_e32 v159, 0x3e38aa3b, v45
	s_waitcnt lgkmcnt(2)
	v_fmamk_f32 v43, v48, 0x3e38aa3b, v148
	v_fmac_f32_e32 v149, 0x3e38aa3b, v49
	v_max_f32_e32 v36, v160, v151
	v_fmamk_f32 v154, v42, 0x3e38aa3b, v156
	v_fmamk_f32 v44, v46, 0x3e38aa3b, v152
	v_fmac_f32_e32 v153, 0x3e38aa3b, v47
	v_max_f32_e32 v34, v200, v163
	v_max_f32_e32 v35, v199, v161
	v_max_f32_e32 v37, v150, v159
	v_max_f32_e32 v38, v43, v149
	v_max3_f32 v36, v162, v155, v36
	v_max3_f32 v37, v154, v157, v37
	v_max3_f32 v34, v34, v35, v36
	v_max3_f32 v35, v44, v153, v38
	v_max3_f32 v42, v34, v37, v35
	ds_bpermute_b32 v45, v167, v42
	v_add_u32_e32 v34, s18, v180
	v_add_u32_e32 v34, 0x6000, v34
	ds_read2_b64 v[38:41], v34 offset0:32 offset1:34
	ds_read2_b64 v[34:37], v34 offset0:36 offset1:38
	s_waitcnt lgkmcnt(2)
	v_max3_f32 v42, v198, v42, v45
	v_cmp_gt_f32_e32 vcc, v42, v198
	s_cbranch_vccz .LBB0_143
	v_sub_f32_e32 v45, v198, v42
	v_exp_f32_e32 v46, v45
	v_mov_b32_e32 v198, v42
	v_mul_f32_e32 v0, v0, v46
	v_pk_mul_f32 v[32:33], v[32:33], v[46:47] op_sel_hi:[1,0]
	v_pk_mul_f32 v[30:31], v[30:31], v[46:47] op_sel_hi:[1,0]
	v_pk_mul_f32 v[28:29], v[28:29], v[46:47] op_sel_hi:[1,0]
	v_pk_mul_f32 v[26:27], v[26:27], v[46:47] op_sel_hi:[1,0]
	v_pk_mul_f32 v[24:25], v[24:25], v[46:47] op_sel_hi:[1,0]
	v_pk_mul_f32 v[22:23], v[22:23], v[46:47] op_sel_hi:[1,0]
	v_pk_mul_f32 v[20:21], v[20:21], v[46:47] op_sel_hi:[1,0]
	v_pk_mul_f32 v[18:19], v[18:19], v[46:47] op_sel_hi:[1,0]
	v_pk_mul_f32 v[16:17], v[16:17], v[46:47] op_sel_hi:[1,0]
	v_pk_mul_f32 v[14:15], v[14:15], v[46:47] op_sel_hi:[1,0]
	v_pk_mul_f32 v[12:13], v[12:13], v[46:47] op_sel_hi:[1,0]
	v_pk_mul_f32 v[10:11], v[10:11], v[46:47] op_sel_hi:[1,0]
	v_pk_mul_f32 v[8:9], v[8:9], v[46:47] op_sel_hi:[1,0]
	v_pk_mul_f32 v[6:7], v[6:7], v[46:47] op_sel_hi:[1,0]
	v_pk_mul_f32 v[4:5], v[4:5], v[46:47] op_sel_hi:[1,0]
	v_pk_mul_f32 v[2:3], v[2:3], v[46:47] op_sel_hi:[1,0]
	s_branch .LBB0_144

; #define LAS __attribute__((address_space(3)))
; __device__ __forceinline__ void softmax2_pv(f32x16& sc, float& m, float& l, f32x16& o0, f32x16& o1, const bf16x8 (&vf)[2][2]) {
;     float tm = fmaxf(fmaxf(sc[0], sc[1]), fmaxf(sc[2], sc[3]));
; #pragma unroll
;     for (int i = 4; i < 16; i += 4) tm = fmaxf(tm, fmaxf(fmaxf(sc[i], sc[i + 1]), fmaxf(sc[i + 2], sc[i + 3])));
;     tm = fmaxf(tm, __shfl_xor(tm, 32));
;     const float mn = fmaxf(m, tm);
;     if (__builtin_amdgcn_ballot_w64(mn > m)) {
;         const float alpha = __builtin_amdgcn_exp2f(m - mn);
;         l *= alpha;
; #pragma unroll
;         for (int i = 0; i < 16; ++i) { o0[i] *= alpha; o1[i] *= alpha; }
;         m = mn;
;     }
; __device__ __forceinline__ void gqa_phase(const PP P, LAS unsigned char* lds, int tid, int cb, int G) {
;     ...
;             for (int t = 0; t < 9; ++t) {
;                 const int kr0 = qoff + 32 * t, tok0 = m0 - 128 + kr0;
;                 if (tok0 < row0 || tok0 >= row0 + L) continue;
;                 bf16x8 kf[4];
; #pragma unroll
;                 for (int ds = 0; ds < 4; ++ds) kf[ds] = *(const LAS bf16x8*)(lds + GQ_K + (kr0 + r32) * GK_PITCH + (16 * ds + 8 * hi) * 2);
;                 bf16x8 vf[2][2];
; #pragma unroll
;                 for (int dh = 0; dh < 2; ++dh)
; #pragma unroll
;                     for (int s = 0; s < 2; ++s) { const LAS s16x4* vp = (const LAS s16x4*)(lds + GQ_V + (dh * 32 + r32) * GV_PITCH + (kr0 + 16 * s + 4 * hi) * 2);
;                         const s16x4 a = vp[0], c2 = vp[2]; vf[dh][s] = (bf16x8){a[0], a[1], a[2], a[3], c2[0], c2[1], c2[2], c2[3]}; }
;                 f32x16 sc = {};
; #pragma unroll
;                 for (int ds = 0; ds < 4; ++ds) sc = MFMA32(kf[ds], qr[ds], sc);
;                 const int ib = 32 * t - r32 + 4 * hi;
;                 if (t == 0 || t == 8) {
; #pragma unroll
;                     for (int i = 0; i < 16; ++i) { const int ix = ib + (i & 3) + 8 * (i >> 2); const bool valid = ix >= 0 && ix <= 256; const float bb = tbl[valid ? ix : 0];
;                         sc[i] = valid ? sc[i] * (0.125f * LOG2E) + bb : NEGBIG; }
;                 } else {
; #pragma unroll
;                     for (int i = 0; i < 16; ++i) sc[i] = sc[i] * (0.125f * LOG2E) + tbl[ib + (i & 3) + 8 * (i >> 2)];
;                 }
;                 softmax2_pv(sc, m, l, o0, o1, vf);
.LBB0_145:
	s_add_i32 s18, s22, 0xe0
	s_add_i32 s19, s35, s18
	s_cmp_ge_i32 s19, s3
	s_cselect_b64 s[24:25], -1, 0
	s_cmp_lt_i32 s19, s20
	s_cselect_b64 vcc, -1, 0
	s_and_b64 s[24:25], s[24:25], vcc
	s_andn2_b64 vcc, exec, s[24:25]
	s_cbranch_vccnz .LBB0_150
	v_or_b32_e32 v34, s18, v164
	v_mad_u32_u24 v118, v34, s26, v166
	ds_read_b128 v[34:37], v118
	ds_read_b128 v[114:117], v118 offset:32
	s_lshl_b32 s18, s18, 1
	s_waitcnt lgkmcnt(1)
	v_mfma_f32_32x32x16_bf16 v[34:49], v[34:37], v[110:113], 0
	s_waitcnt lgkmcnt(0)
	v_mfma_f32_32x32x16_bf16 v[34:49], v[114:117], v[106:109], v[34:49]
	ds_read_b128 v[114:117], v118 offset:64
	ds_read2_b32 v[162:163], v181 offset0:224 offset1:225
	ds_read2_b32 v[160:161], v181 offset0:226 offset1:227
	ds_read2_b32 v[154:155], v181 offset0:232 offset1:233
	ds_read2_b32 v[150:151], v181 offset0:234 offset1:235
	ds_read_b128 v[206:209], v118 offset:96
	ds_read2_b32 v[156:157], v181 offset0:240 offset1:241
	ds_read2_b32 v[158:159], v181 offset0:242 offset1:243
	ds_read2_b32 v[152:153], v181 offset0:248 offset1:249
	ds_read2_b32 v[148:149], v181 offset0:250 offset1:251
	s_waitcnt lgkmcnt(9)
	v_mfma_f32_32x32x16_bf16 v[34:49], v[114:117], v[102:105], v[34:49]
	v_add_u32_e32 v114, s18, v179
	v_add_u32_e32 v114, 0xd800, v114
	ds_read2_b64 v[118:121], v114 offset1:2
	ds_read2_b64 v[114:117], v114 offset0:4 offset1:6
	s_waitcnt lgkmcnt(6)
	v_mfma_f32_32x32x16_bf16 v[34:49], v[206:209], v[98:101], v[34:49]
	s_nop 11
	v_fmamk_f32 v199, v36, 0x3e38aa3b, v160
	v_fmamk_f32 v160, v40, 0x3e38aa3b, v150
	v_fmac_f32_e32 v151, 0x3e38aa3b, v41
	v_fmamk_f32 v200, v34, 0x3e38aa3b, v162
	v_fmac_f32_e32 v163, 0x3e38aa3b, v35
	v_fmac_f32_e32 v161, 0x3e38aa3b, v37
	v_fmamk_f32 v162, v38, 0x3e38aa3b, v154
	v_fmac_f32_e32 v155, 0x3e38aa3b, v39
	s_waitcnt lgkmcnt(5)
	v_fmac_f32_e32 v157, 0x3e38aa3b, v43
	s_waitcnt lgkmcnt(4)
	v_fmamk_f32 v150, v44, 0x3e38aa3b, v158
	v_fmac_f32_e32 v159, 0x3e38aa3b, v45
	s_waitcnt lgkmcnt(2)
	v_fmamk_f32 v43, v48, 0x3e38aa3b, v148
	v_fmac_f32_e32 v149, 0x3e38aa3b, v49
	v_max_f32_e32 v36, v160, v151
	v_fmamk_f32 v154, v42, 0x3e38aa3b, v156
	v_fmamk_f32 v44, v46, 0x3e38aa3b, v152
	v_fmac_f32_e32 v153, 0x3e38aa3b, v47
	v_max_f32_e32 v34, v200, v163
	v_max_f32_e32 v35, v199, v161
	v_max_f32_e32 v37, v150, v159
	v_max_f32_e32 v38, v43, v149
	v_max3_f32 v36, v162, v155, v36
	v_max3_f32 v37, v154, v157, v37
	v_max3_f32 v34, v34, v35, v36
	v_max3_f32 v35, v44, v153, v38
	v_max3_f32 v42, v34, v37, v35
	ds_bpermute_b32 v45, v167, v42
	v_add_u32_e32 v34, s18, v180
	v_add_u32_e32 v34, 0x6000, v34
	ds_read2_b64 v[38:41], v34 offset0:32 offset1:34
	ds_read2_b64 v[34:37], v34 offset0:36 offset1:38
	s_waitcnt lgkmcnt(2)
	v_max3_f32 v42, v198, v42, v45
	v_cmp_gt_f32_e32 vcc, v42, v198
	s_cbranch_vccz .LBB0_148
	v_sub_f32_e32 v45, v198, v42
	v_exp_f32_e32 v46, v45
	v_mov_b32_e32 v198, v42
	v_mul_f32_e32 v0, v0, v46
	v_pk_mul_f32 v[32:33], v[32:33], v[46:47] op_sel_hi:[1,0]
	v_pk_mul_f32 v[30:31], v[30:31], v[46:47] op_sel_hi:[1,0]
	v_pk_mul_f32 v[28:29], v[28:29], v[46:47] op_sel_hi:[1,0]
	v_pk_mul_f32 v[26:27], v[26:27], v[46:47] op_sel_hi:[1,0]
	v_pk_mul_f32 v[24:25], v[24:25], v[46:47] op_sel_hi:[1,0]
	v_pk_mul_f32 v[22:23], v[22:23], v[46:47] op_sel_hi:[1,0]
	v_pk_mul_f32 v[20:21], v[20:21], v[46:47] op_sel_hi:[1,0]
	v_pk_mul_f32 v[18:19], v[18:19], v[46:47] op_sel_hi:[1,0]
	v_pk_mul_f32 v[16:17], v[16:17], v[46:47] op_sel_hi:[1,0]
	v_pk_mul_f32 v[14:15], v[14:15], v[46:47] op_sel_hi:[1,0]
	v_pk_mul_f32 v[12:13], v[12:13], v[46:47] op_sel_hi:[1,0]
	v_pk_mul_f32 v[10:11], v[10:11], v[46:47] op_sel_hi:[1,0]
	v_pk_mul_f32 v[8:9], v[8:9], v[46:47] op_sel_hi:[1,0]
	v_pk_mul_f32 v[6:7], v[6:7], v[46:47] op_sel_hi:[1,0]
	v_pk_mul_f32 v[4:5], v[4:5], v[46:47] op_sel_hi:[1,0]
	v_pk_mul_f32 v[2:3], v[2:3], v[46:47] op_sel_hi:[1,0]
	s_branch .LBB0_149

; #define LAS __attribute__((address_space(3)))
; #define MFMA32(a, b, c) __builtin_amdgcn_mfma_f32_32x32x16_bf16((a), (b), (c), 0, 0, 0)
; __device__ __forceinline__ void gqa_phase(const PP P, LAS unsigned char* lds, int tid, int cb, int G) {
;     ...
;             for (int t = 0; t < 9; ++t) {
;                 const int kr0 = qoff + 32 * t, tok0 = m0 - 128 + kr0;
;                 if (tok0 < row0 || tok0 >= row0 + L) continue;
;                 bf16x8 kf[4];
; #pragma unroll
;                 for (int ds = 0; ds < 4; ++ds) kf[ds] = *(const LAS bf16x8*)(lds + GQ_K + (kr0 + r32) * GK_PITCH + (16 * ds + 8 * hi) * 2);
;                 bf16x8 vf[2][2];
; #pragma unroll
;                 for (int dh = 0; dh < 2; ++dh)
; #pragma unroll
;                     for (int s = 0; s < 2; ++s) { const LAS s16x4* vp = (const LAS s16x4*)(lds + GQ_V + (dh * 32 + r32) * GV_PITCH + (kr0 + 16 * s + 4 * hi) * 2);
;                         const s16x4 a = vp[0], c2 = vp[2]; vf[dh][s] = (bf16x8){a[0], a[1], a[2], a[3], c2[0], c2[1], c2[2], c2[3]}; }
;                 f32x16 sc = {};
; #pragma unroll
;                 for (int ds = 0; ds < 4; ++ds) sc = MFMA32(kf[ds], qr[ds], sc);
;                 const int ib = 32 * t - r32 + 4 * hi;
;                 if (t == 0 || t == 8) {
; #pragma unroll
;                     for (int i = 0; i < 16; ++i) { const int ix = ib + (i & 3) + 8 * (i >> 2); const bool valid = ix >= 0 && ix <= 256; const float bb = tbl[valid ? ix : 0];
;                         sc[i] = valid ? sc[i] * (0.125f * LOG2E) + bb : NEGBIG; }
.LBB0_150:
	s_bitset1_b32 s22, 8
	s_add_i32 s23, s35, s22
	s_cmp_ge_i32 s23, s3
	s_cselect_b64 s[18:19], -1, 0
	s_cmp_lt_i32 s23, s20
	s_cselect_b64 s[24:25], -1, 0
	s_and_b64 s[18:19], s[18:19], s[24:25]
	s_andn2_b64 vcc, exec, s[18:19]
	s_cbranch_vccnz .LBB0_78
	v_or_b32_e32 v34, s22, v164
	v_mad_u32_u24 v118, v34, s26, v166
	ds_read_b128 v[34:37], v118
	ds_read_b128 v[114:117], v118 offset:32
	s_lshl_b32 s18, s22, 1
	s_waitcnt lgkmcnt(1)
	v_mfma_f32_32x32x16_bf16 v[34:49], v[34:37], v[110:113], 0
	v_add_u32_e32 v110, s18, v179
	s_waitcnt lgkmcnt(0)
	v_mfma_f32_32x32x16_bf16 v[34:49], v[114:117], v[106:109], v[34:49]
	ds_read_b128 v[106:109], v118 offset:64
	ds_read_b128 v[118:121], v118 offset:96
	s_waitcnt lgkmcnt(1)
	v_mfma_f32_32x32x16_bf16 v[34:49], v[106:109], v[102:105], v[34:49]
	v_add_u32_e32 v102, 0xd800, v110
	ds_read2_b64 v[114:117], v102 offset1:2
	ds_read2_b64 v[110:113], v102 offset0:4 offset1:6
	v_add_u32_e32 v102, s18, v180
	v_add_u32_e32 v102, 0x6000, v102
	ds_read2_b64 v[106:109], v102 offset0:32 offset1:34
	ds_read2_b64 v[102:105], v102 offset0:36 offset1:38
	s_waitcnt lgkmcnt(4)
	v_mfma_f32_32x32x16_bf16 v[34:49], v[118:121], v[98:101], v[34:49]
	v_mov_b32_e32 v98, 0xf149f2ca
	v_mov_b32_e32 v99, 0xf149f2ca
	s_and_saveexec_b64 s[24:25], s[72:73]
	s_cbranch_execz .LBB0_153
	ds_read_b32 v99, v181 offset:1024
	s_waitcnt lgkmcnt(0)
	s_nop 5
	v_fmac_f32_e32 v99, 0x3e38aa3b, v34

; #define PG8_STAGE(bufoff, gbase, voff) do { _Pragma("unroll") for (int _i = 0; _i < 2; ++_i) \
;         __builtin_amdgcn_global_load_lds((const unsigned*)((const char*)(gbase) + (voff)[_i]), (PG8_LAS unsigned*)(lds + (bufoff) + ldsw + _i * 8192), 16, 0, 0); } while (0)
; #define PG8_LDA(dst, b, h) do { _Pragma("unroll") for (int m = 0; m < 4; ++m) _Pragma("unroll") for (int k = 0; k < 2; ++k) dst[m][k] = *(const PG8_LAS bf16x8*)(lds + PG8_SA(b, h) + aoff + m * 2048 + k * 1024); } while (0)
; #define PG8_LDB(dst, b, h) do { _Pragma("unroll") for (int n = 0; n < 2; ++n) _Pragma("unroll") for (int k = 0; k < 2; ++k) dst[n][k] = *(const PG8_LAS bf16x8*)(lds + PG8_SB(b, h) + boff + n * 2048 + k * 1024); } while (0)
; #define PG8_MMA(ai, bj, At, Bt) do { __builtin_amdgcn_s_setprio(1); _Pragma("unroll") for (int m = 0; m < 4; ++m) _Pragma("unroll") for (int n = 0; n < 2; ++n) _Pragma("unroll") for (int k = 0; k < 2; ++k) \
;         acc[ai][bj][m][n] = __builtin_amdgcn_mfma_f32_16x16x32_bf16(Bt[n][k], At[m][k], acc[ai][bj][m][n], 0, 0, 0); __builtin_amdgcn_s_setprio(0); } while (0)
; #define PG8_WAIT_V(n) asm volatile("s_waitcnt vmcnt(" #n ")" ::: "memory")
; #define PG8_WAIT_L(n) asm volatile("s_waitcnt lgkmcnt(" #n ")" ::: "memory")
; #define PG8_BAR __builtin_amdgcn_s_barrier()
; #define PG8_SCHED __builtin_amdgcn_sched_barrier(0)
; template <class Epi, class Sched, bool ALIGN_EPI = false, bool SP2 = false>
; __device__ __forceinline__ void gemm_phase(PG8_LAS unsigned char* lds, const Gemm g, const Sched& S, const Epi& E) {
;     ...
;             PG8_LDB(B0, 0, 0); PG8_LDB(B1, 0, 1); PG8_SCHED; PG8_LDA(At, 0, 0); PG8_STAGE(PG8_SA(1, 1), a1 + hstep, voffA);
;             PG8_WAIT_V(8); PG8_WAIT_L(0); PG8_BAR; PG8_MMA(0, 0, At, B0); PG8_MMA(0, 1, At, B1); PG8_BAR; PG8_SCHED;
;             PG8_LDA(At, 0, 1); PG8_STAGE(PG8_SB(0, 0), b2, voffB); PG8_STAGE(PG8_SB(0, 1), b2 + hstep, voffB); PG8_STAGE(PG8_SA(0, 0), a2, voffA);
;             PG8_WAIT_V(8); PG8_WAIT_L(0); PG8_BAR; PG8_MMA(1, 0, At, B0); PG8_MMA(1, 1, At, B1); PG8_BAR; PG8_SCHED;
.LBB0_199:
	s_add_u32 s24, s2, 0xfffe0080
	s_addc_u32 s25, s3, -1
	s_add_i32 s66, 0, 0x10000
	s_cmp_eq_u32 s65, 4
	s_cselect_b32 s51, s11, s25
	s_cselect_b32 s50, s16, s24
	s_cselect_b32 s25, s17, s35
	s_cselect_b32 s24, s19, s23
	s_add_i32 s68, 0, 0x14000
	v_add_u32_e32 v78, s66, v252
	v_add_u32_e32 v126, s68, v252
	ds_read_b128 v[42:45], v78
	ds_read_b128 v[54:57], v78 offset:1024
	ds_read_b128 v[66:69], v78 offset:2048
	ds_read_b128 v[78:81], v78 offset:3072
	ds_read_b128 v[90:93], v126
	ds_read_b128 v[102:105], v126 offset:1024
	ds_read_b128 v[114:117], v126 offset:2048
	ds_read_b128 v[126:129], v126 offset:3072
	v_lshl_add_u64 v[194:195], s[2:3], 0, v[212:213]
	s_add_i32 m0, s57, 0xc000
	ds_read_b128 v[138:141], v241
	ds_read_b128 v[142:145], v241 offset:1024
	ds_read_b128 v[146:149], v241 offset:2048
	ds_read_b128 v[158:161], v241 offset:3072
	ds_read_b128 v[170:173], v241 offset:4096
	ds_read_b128 v[182:185], v241 offset:5120
	ds_read_b128 v[186:189], v241 offset:6144
	ds_read_b128 v[190:193], v241 offset:7168
	global_load_lds_dwordx4 v[194:195], off
	v_lshl_add_u64 v[194:195], s[2:3], 0, v[214:215]
	s_add_i32 m0, s57, 0xe000
	s_nop 0
	global_load_lds_dwordx4 v[194:195], off
	s_waitcnt vmcnt(8)
	s_waitcnt lgkmcnt(0)
	s_barrier
	s_setprio 1
	v_mfma_f32_16x16x32_bf16 v[178:181], v[42:45], v[138:141], v[178:181]
	v_mfma_f32_16x16x32_bf16 v[174:177], v[66:69], v[138:141], v[174:177]
	v_mfma_f32_16x16x32_bf16 v[166:169], v[42:45], v[146:149], v[166:169]
	v_mfma_f32_16x16x32_bf16 v[162:165], v[66:69], v[146:149], v[162:165]
	v_mfma_f32_16x16x32_bf16 v[154:157], v[42:45], v[170:173], v[154:157]
	v_mfma_f32_16x16x32_bf16 v[150:153], v[66:69], v[170:173], v[150:153]
	v_mfma_f32_16x16x32_bf16 v[134:137], v[42:45], v[186:189], v[134:137]
	v_mfma_f32_16x16x32_bf16 v[130:133], v[66:69], v[186:189], v[130:133]
	v_mfma_f32_16x16x32_bf16 v[178:181], v[54:57], v[142:145], v[178:181]
	v_mfma_f32_16x16x32_bf16 v[174:177], v[78:81], v[142:145], v[174:177]
	v_mfma_f32_16x16x32_bf16 v[166:169], v[54:57], v[158:161], v[166:169]
	v_mfma_f32_16x16x32_bf16 v[162:165], v[78:81], v[158:161], v[162:165]
	v_mfma_f32_16x16x32_bf16 v[154:157], v[54:57], v[182:185], v[154:157]
	v_mfma_f32_16x16x32_bf16 v[150:153], v[78:81], v[182:185], v[150:153]
	v_mfma_f32_16x16x32_bf16 v[134:137], v[54:57], v[190:193], v[134:137]
	v_mfma_f32_16x16x32_bf16 v[130:133], v[78:81], v[190:193], v[130:133]
	v_mfma_f32_16x16x32_bf16 v[74:77], v[90:93], v[138:141], v[74:77]
	v_mfma_f32_16x16x32_bf16 v[70:73], v[114:117], v[138:141], v[70:73]
	v_mfma_f32_16x16x32_bf16 v[62:65], v[90:93], v[146:149], v[62:65]
	v_mfma_f32_16x16x32_bf16 v[58:61], v[114:117], v[146:149], v[58:61]
	v_mfma_f32_16x16x32_bf16 v[50:53], v[90:93], v[170:173], v[50:53]
	v_mfma_f32_16x16x32_bf16 v[46:49], v[114:117], v[170:173], v[46:49]
	v_mfma_f32_16x16x32_bf16 v[38:41], v[90:93], v[186:189], v[38:41]
	v_mfma_f32_16x16x32_bf16 v[34:37], v[114:117], v[186:189], v[34:37]
	v_mfma_f32_16x16x32_bf16 v[74:77], v[102:105], v[142:145], v[74:77]
	v_mfma_f32_16x16x32_bf16 v[70:73], v[126:129], v[142:145], v[70:73]
	v_mfma_f32_16x16x32_bf16 v[62:65], v[102:105], v[158:161], v[62:65]
	v_mfma_f32_16x16x32_bf16 v[58:61], v[126:129], v[158:161], v[58:61]
	v_mfma_f32_16x16x32_bf16 v[50:53], v[102:105], v[182:185], v[50:53]
	v_mfma_f32_16x16x32_bf16 v[46:49], v[126:129], v[182:185], v[46:49]
	v_mfma_f32_16x16x32_bf16 v[38:41], v[102:105], v[190:193], v[38:41]
	v_mfma_f32_16x16x32_bf16 v[34:37], v[126:129], v[190:193], v[34:37]
	s_setprio 0
	s_barrier
	s_add_i32 s66, s66, s55
	v_lshl_add_u64 v[198:199], s[24:25], 0, v[0:1]
	s_mov_b32 m0, s66
	ds_read_b128 v[138:141], v241 offset:16384
	ds_read_b128 v[142:145], v241 offset:17408
	ds_read_b128 v[146:149], v241 offset:18432
	ds_read_b128 v[158:161], v241 offset:19456
	ds_read_b128 v[170:173], v241 offset:20480
	ds_read_b128 v[182:185], v241 offset:21504
	ds_read_b128 v[186:189], v241 offset:22528
	ds_read_b128 v[190:193], v241 offset:23552
	global_load_lds_dwordx4 v[198:199], off
	s_add_i32 m0, s66, 0x2000
	s_add_u32 s66, s24, 0x20000
	v_lshl_add_u64 v[200:201], s[24:25], 0, v[206:207]
	s_addc_u32 s67, s25, 0
	s_add_i32 s68, s68, s55
	global_load_lds_dwordx4 v[200:201], off
	v_lshl_add_u64 v[194:195], s[66:67], 0, v[0:1]
	s_mov_b32 m0, s68
	v_lshl_add_u64 v[216:217], s[50:51], 0, v[210:211]
	global_load_lds_dwordx4 v[194:195], off
	v_lshl_add_u64 v[194:195], s[66:67], 0, v[206:207]
	s_add_i32 m0, s68, 0x2000
	v_lshl_add_u64 v[218:219], s[50:51], 0, v[208:209]
	global_load_lds_dwordx4 v[194:195], off
	s_mov_b32 m0, s57
	s_nop 0
	global_load_lds_dwordx4 v[216:217], off
	s_mov_b32 m0, s58
	s_nop 0
	global_load_lds_dwordx4 v[218:219], off
	s_waitcnt vmcnt(8)
	s_waitcnt lgkmcnt(0)
	s_barrier
; #define PG8_STAGE(bufoff, gbase, voff) do { _Pragma("unroll") for (int _i = 0; _i < 2; ++_i) \
;         __builtin_amdgcn_global_load_lds((const unsigned*)((const char*)(gbase) + (voff)[_i]), (PG8_LAS unsigned*)(lds + (bufoff) + ldsw + _i * 8192), 16, 0, 0); } while (0)
; #define PG8_LDA(dst, b, h) do { _Pragma("unroll") for (int m = 0; m < 4; ++m) _Pragma("unroll") for (int k = 0; k < 2; ++k) dst[m][k] = *(const PG8_LAS bf16x8*)(lds + PG8_SA(b, h) + aoff + m * 2048 + k * 1024); } while (0)
; #define PG8_LDB(dst, b, h) do { _Pragma("unroll") for (int n = 0; n < 2; ++n) _Pragma("unroll") for (int k = 0; k < 2; ++k) dst[n][k] = *(const PG8_LAS bf16x8*)(lds + PG8_SB(b, h) + boff + n * 2048 + k * 1024); } while (0)
; #define PG8_MMA(ai, bj, At, Bt) do { __builtin_amdgcn_s_setprio(1); _Pragma("unroll") for (int m = 0; m < 4; ++m) _Pragma("unroll") for (int n = 0; n < 2; ++n) _Pragma("unroll") for (int k = 0; k < 2; ++k) \
;         acc[ai][bj][m][n] = __builtin_amdgcn_mfma_f32_16x16x32_bf16(Bt[n][k], At[m][k], acc[ai][bj][m][n], 0, 0, 0); __builtin_amdgcn_s_setprio(0); } while (0)
; #define PG8_WAIT_V(n) asm volatile("s_waitcnt vmcnt(" #n ")" ::: "memory")
; #define PG8_WAIT_L(n) asm volatile("s_waitcnt lgkmcnt(" #n ")" ::: "memory")
; #define PG8_BAR __builtin_amdgcn_s_barrier()
; #define PG8_SCHED __builtin_amdgcn_sched_barrier(0)
; template <class Epi, class Sched, bool ALIGN_EPI = false, bool SP2 = false>
; __device__ __forceinline__ void gemm_phase(PG8_LAS unsigned char* lds, const Gemm g, const Sched& S, const Epi& E) {
;     ...
;             PG8_WAIT_V(8); PG8_WAIT_L(0); PG8_BAR; PG8_MMA(1, 0, At, B0); PG8_MMA(1, 1, At, B1); PG8_BAR; PG8_SCHED;
;             PG8_LDB(B0, 1, 0); PG8_LDB(B1, 1, 1); PG8_SCHED; PG8_LDA(At, 1, 0); PG8_STAGE(PG8_SA(0, 1), a2 + hstep, voffA);
;             PG8_WAIT_V(8); PG8_WAIT_L(0); PG8_BAR; PG8_MMA(0, 0, At, B0); PG8_MMA(0, 1, At, B1); PG8_BAR; PG8_SCHED;
	s_setprio 1
	v_mfma_f32_16x16x32_bf16 v[122:125], v[42:45], v[138:141], v[122:125]
	v_mfma_f32_16x16x32_bf16 v[118:121], v[66:69], v[138:141], v[118:121]
	v_mfma_f32_16x16x32_bf16 v[110:113], v[42:45], v[146:149], v[110:113]
	v_mfma_f32_16x16x32_bf16 v[106:109], v[66:69], v[146:149], v[106:109]
	v_mfma_f32_16x16x32_bf16 v[98:101], v[42:45], v[170:173], v[98:101]
	v_mfma_f32_16x16x32_bf16 v[94:97], v[66:69], v[170:173], v[94:97]
	v_mfma_f32_16x16x32_bf16 v[42:45], v[42:45], v[186:189], v[86:89]
	v_mfma_f32_16x16x32_bf16 v[122:125], v[54:57], v[142:145], v[122:125]
	v_mfma_f32_16x16x32_bf16 v[118:121], v[78:81], v[142:145], v[118:121]
	v_mfma_f32_16x16x32_bf16 v[110:113], v[54:57], v[158:161], v[110:113]
	v_mfma_f32_16x16x32_bf16 v[106:109], v[78:81], v[158:161], v[106:109]
	v_mfma_f32_16x16x32_bf16 v[98:101], v[54:57], v[182:185], v[98:101]
	v_mfma_f32_16x16x32_bf16 v[94:97], v[78:81], v[182:185], v[94:97]
	v_mfma_f32_16x16x32_bf16 v[42:45], v[54:57], v[190:193], v[42:45]
	v_mfma_f32_16x16x32_bf16 v[54:57], v[66:69], v[186:189], v[82:85]
	v_mfma_f32_16x16x32_bf16 v[54:57], v[78:81], v[190:193], v[54:57]
	v_mfma_f32_16x16x32_bf16 v[30:33], v[90:93], v[138:141], v[30:33]
	v_mfma_f32_16x16x32_bf16 v[26:29], v[114:117], v[138:141], v[26:29]
	v_mfma_f32_16x16x32_bf16 v[22:25], v[90:93], v[146:149], v[22:25]
	v_mfma_f32_16x16x32_bf16 v[18:21], v[114:117], v[146:149], v[18:21]
	v_mfma_f32_16x16x32_bf16 v[14:17], v[90:93], v[170:173], v[14:17]
	v_mfma_f32_16x16x32_bf16 v[10:13], v[114:117], v[170:173], v[10:13]
	v_mfma_f32_16x16x32_bf16 v[6:9], v[90:93], v[186:189], v[6:9]
	v_mfma_f32_16x16x32_bf16 v[2:5], v[114:117], v[186:189], v[2:5]
	v_mfma_f32_16x16x32_bf16 v[30:33], v[102:105], v[142:145], v[30:33]
	v_mfma_f32_16x16x32_bf16 v[26:29], v[126:129], v[142:145], v[26:29]
	v_mfma_f32_16x16x32_bf16 v[22:25], v[102:105], v[158:161], v[22:25]
	v_mfma_f32_16x16x32_bf16 v[18:21], v[126:129], v[158:161], v[18:21]
	v_mfma_f32_16x16x32_bf16 v[14:17], v[102:105], v[182:185], v[14:17]
	v_mfma_f32_16x16x32_bf16 v[10:13], v[126:129], v[182:185], v[10:13]
	v_mfma_f32_16x16x32_bf16 v[6:9], v[102:105], v[190:193], v[6:9]
	v_mfma_f32_16x16x32_bf16 v[2:5], v[126:129], v[190:193], v[2:5]
	s_setprio 0
	s_barrier
	s_add_i32 s66, 0, 0x18000
	v_add_u32_e32 v86, s66, v252
	s_add_i32 s67, 0, 0x1c000
	ds_read_b128 v[66:69], v86
	ds_read_b128 v[78:81], v86 offset:1024
	ds_read_b128 v[82:85], v86 offset:2048
	ds_read_b128 v[90:93], v86 offset:3072
	v_add_u32_e32 v86, s67, v252
	ds_read_b128 v[102:105], v86
	ds_read_b128 v[114:117], v86 offset:1024
	ds_read_b128 v[126:129], v86 offset:2048
	ds_read_b128 v[138:141], v86 offset:3072
	s_add_u32 s50, s50, 0x20000
	s_addc_u32 s51, s51, 0
	s_mov_b32 m0, s59
	v_lshl_add_u64 v[194:195], s[50:51], 0, v[210:211]
	ds_read_b128 v[86:89], v241 offset:32768
	ds_read_b128 v[142:145], v241 offset:33792
	ds_read_b128 v[146:149], v241 offset:34816
	ds_read_b128 v[158:161], v241 offset:35840
	ds_read_b128 v[170:173], v241 offset:36864
	ds_read_b128 v[182:185], v241 offset:37888
	ds_read_b128 v[186:189], v241 offset:38912
	ds_read_b128 v[190:193], v241 offset:39936
	global_load_lds_dwordx4 v[194:195], off
	v_lshl_add_u64 v[194:195], s[50:51], 0, v[208:209]
	s_mov_b32 m0, s60
	s_nop 0
	global_load_lds_dwordx4 v[194:195], off
	s_waitcnt vmcnt(8)
	s_waitcnt lgkmcnt(0)
	s_barrier
	s_setprio 1
	v_mfma_f32_16x16x32_bf16 v[178:181], v[66:69], v[86:89], v[178:181]
	v_mfma_f32_16x16x32_bf16 v[174:177], v[82:85], v[86:89], v[174:177]
	v_mfma_f32_16x16x32_bf16 v[166:169], v[66:69], v[146:149], v[166:169]
	v_mfma_f32_16x16x32_bf16 v[162:165], v[82:85], v[146:149], v[162:165]
	v_mfma_f32_16x16x32_bf16 v[154:157], v[66:69], v[170:173], v[154:157]
	v_mfma_f32_16x16x32_bf16 v[150:153], v[82:85], v[170:173], v[150:153]
	v_mfma_f32_16x16x32_bf16 v[134:137], v[66:69], v[186:189], v[134:137]
	v_mfma_f32_16x16x32_bf16 v[130:133], v[82:85], v[186:189], v[130:133]
	v_mfma_f32_16x16x32_bf16 v[178:181], v[78:81], v[142:145], v[178:181]
	v_mfma_f32_16x16x32_bf16 v[174:177], v[90:93], v[142:145], v[174:177]
	v_mfma_f32_16x16x32_bf16 v[166:169], v[78:81], v[158:161], v[166:169]
	v_mfma_f32_16x16x32_bf16 v[162:165], v[90:93], v[158:161], v[162:165]
	v_mfma_f32_16x16x32_bf16 v[154:157], v[78:81], v[182:185], v[154:157]
	v_mfma_f32_16x16x32_bf16 v[150:153], v[90:93], v[182:185], v[150:153]
	v_mfma_f32_16x16x32_bf16 v[134:137], v[78:81], v[190:193], v[134:137]
	v_mfma_f32_16x16x32_bf16 v[130:133], v[90:93], v[190:193], v[130:133]
	v_mfma_f32_16x16x32_bf16 v[74:77], v[102:105], v[86:89], v[74:77]
	v_mfma_f32_16x16x32_bf16 v[70:73], v[126:129], v[86:89], v[70:73]
	v_mfma_f32_16x16x32_bf16 v[62:65], v[102:105], v[146:149], v[62:65]
	v_mfma_f32_16x16x32_bf16 v[58:61], v[126:129], v[146:149], v[58:61]
	v_mfma_f32_16x16x32_bf16 v[50:53], v[102:105], v[170:173], v[50:53]
	v_mfma_f32_16x16x32_bf16 v[46:49], v[126:129], v[170:173], v[46:49]
	v_mfma_f32_16x16x32_bf16 v[38:41], v[102:105], v[186:189], v[38:41]
	v_mfma_f32_16x16x32_bf16 v[34:37], v[126:129], v[186:189], v[34:37]
	v_mfma_f32_16x16x32_bf16 v[74:77], v[114:117], v[142:145], v[74:77]
	v_mfma_f32_16x16x32_bf16 v[70:73], v[138:141], v[142:145], v[70:73]
	v_mfma_f32_16x16x32_bf16 v[62:65], v[114:117], v[158:161], v[62:65]
	v_mfma_f32_16x16x32_bf16 v[58:61], v[138:141], v[158:161], v[58:61]
	v_mfma_f32_16x16x32_bf16 v[50:53], v[114:117], v[182:185], v[50:53]
	v_mfma_f32_16x16x32_bf16 v[46:49], v[138:141], v[182:185], v[46:49]
	v_mfma_f32_16x16x32_bf16 v[38:41], v[114:117], v[190:193], v[38:41]
	v_mfma_f32_16x16x32_bf16 v[34:37], v[138:141], v[190:193], v[34:37]
	s_setprio 0
	s_barrier
; #define PG8_STAGE(bufoff, gbase, voff) do { _Pragma("unroll") for (int _i = 0; _i < 2; ++_i) \
;         __builtin_amdgcn_global_load_lds((const unsigned*)((const char*)(gbase) + (voff)[_i]), (PG8_LAS unsigned*)(lds + (bufoff) + ldsw + _i * 8192), 16, 0, 0); } while (0)
; #define PG8_LDA(dst, b, h) do { _Pragma("unroll") for (int m = 0; m < 4; ++m) _Pragma("unroll") for (int k = 0; k < 2; ++k) dst[m][k] = *(const PG8_LAS bf16x8*)(lds + PG8_SA(b, h) + aoff + m * 2048 + k * 1024); } while (0)
; #define PG8_MMA(ai, bj, At, Bt) do { __builtin_amdgcn_s_setprio(1); _Pragma("unroll") for (int m = 0; m < 4; ++m) _Pragma("unroll") for (int n = 0; n < 2; ++n) _Pragma("unroll") for (int k = 0; k < 2; ++k) \
;         acc[ai][bj][m][n] = __builtin_amdgcn_mfma_f32_16x16x32_bf16(Bt[n][k], At[m][k], acc[ai][bj][m][n], 0, 0, 0); __builtin_amdgcn_s_setprio(0); } while (0)
; #define PG8_WAIT_V(n) asm volatile("s_waitcnt vmcnt(" #n ")" ::: "memory")
; #define PG8_WAIT_L(n) asm volatile("s_waitcnt lgkmcnt(" #n ")" ::: "memory")
; #define PG8_BAR __builtin_amdgcn_s_barrier()
; #define PG8_SCHED __builtin_amdgcn_sched_barrier(0)
; template <class Epi, class Sched, bool ALIGN_EPI = false, bool SP2 = false>
; __device__ __forceinline__ void gemm_phase(PG8_LAS unsigned char* lds, const Gemm g, const Sched& S, const Epi& E) {
;     ...
;             PG8_LDA(At, 1, 1); PG8_STAGE(PG8_SB(1, 0), b3, voffB); PG8_STAGE(PG8_SB(1, 1), b3 + hstep, voffB); PG8_STAGE(PG8_SA(1, 0), a3, voffA);
;             PG8_WAIT_V(8); PG8_WAIT_L(0); PG8_BAR; PG8_MMA(1, 0, At, B0); PG8_MMA(1, 1, At, B1); PG8_BAR; PG8_SCHED;
	s_add_i32 s50, s66, s55
	v_lshl_add_u64 v[86:87], v[198:199], 0, s[28:29]
	s_mov_b32 m0, s50
	ds_read_b128 v[142:145], v241 offset:49152
	ds_read_b128 v[146:149], v241 offset:50176
	ds_read_b128 v[158:161], v241 offset:51200
	ds_read_b128 v[170:173], v241 offset:52224
	ds_read_b128 v[182:185], v241 offset:53248
	ds_read_b128 v[186:189], v241 offset:54272
	ds_read_b128 v[190:193], v241 offset:55296
	ds_read_b128 v[194:197], v241 offset:56320
	global_load_lds_dwordx4 v[86:87], off
	s_add_i32 m0, s50, 0x2000
	s_add_u32 s24, s24, 0x20080
	v_lshl_add_u64 v[86:87], v[200:201], 0, s[28:29]
	s_addc_u32 s25, s25, 0
	s_add_i32 s50, s67, s55
	global_load_lds_dwordx4 v[86:87], off
	v_lshl_add_u64 v[86:87], s[24:25], 0, v[0:1]
	s_mov_b32 m0, s50
	s_nop 0
	global_load_lds_dwordx4 v[86:87], off
	v_lshl_add_u64 v[86:87], s[24:25], 0, v[206:207]
	s_add_i32 m0, s50, 0x2000
	s_nop 0
	global_load_lds_dwordx4 v[86:87], off
	v_lshl_add_u64 v[86:87], v[216:217], 0, s[28:29]
	s_mov_b32 m0, s61
	s_nop 0
	global_load_lds_dwordx4 v[86:87], off
	v_lshl_add_u64 v[86:87], v[218:219], 0, s[28:29]
	s_mov_b32 m0, s62
	s_nop 0
	global_load_lds_dwordx4 v[86:87], off
	s_waitcnt vmcnt(8)
	s_waitcnt lgkmcnt(0)
	s_barrier
	s_setprio 1
	v_mfma_f32_16x16x32_bf16 v[86:89], v[66:69], v[142:145], v[122:125]
	v_mfma_f32_16x16x32_bf16 v[122:125], v[78:81], v[146:149], v[86:89]
	v_mfma_f32_16x16x32_bf16 v[86:89], v[82:85], v[142:145], v[118:121]
	v_mfma_f32_16x16x32_bf16 v[118:121], v[90:93], v[146:149], v[86:89]
	v_mfma_f32_16x16x32_bf16 v[86:89], v[66:69], v[158:161], v[110:113]
	v_mfma_f32_16x16x32_bf16 v[110:113], v[78:81], v[170:173], v[86:89]
	v_mfma_f32_16x16x32_bf16 v[86:89], v[82:85], v[158:161], v[106:109]
	v_mfma_f32_16x16x32_bf16 v[106:109], v[90:93], v[170:173], v[86:89]
	v_mfma_f32_16x16x32_bf16 v[86:89], v[66:69], v[182:185], v[98:101]
	v_mfma_f32_16x16x32_bf16 v[98:101], v[78:81], v[186:189], v[86:89]
	v_mfma_f32_16x16x32_bf16 v[86:89], v[82:85], v[182:185], v[94:97]
	v_mfma_f32_16x16x32_bf16 v[42:45], v[66:69], v[190:193], v[42:45]
	v_mfma_f32_16x16x32_bf16 v[94:97], v[90:93], v[186:189], v[86:89]
	v_mfma_f32_16x16x32_bf16 v[86:89], v[78:81], v[194:197], v[42:45]
	v_mfma_f32_16x16x32_bf16 v[42:45], v[82:85], v[190:193], v[54:57]
	v_mfma_f32_16x16x32_bf16 v[82:85], v[90:93], v[194:197], v[42:45]
	v_mfma_f32_16x16x32_bf16 v[30:33], v[102:105], v[142:145], v[30:33]
	v_mfma_f32_16x16x32_bf16 v[26:29], v[126:129], v[142:145], v[26:29]
	v_mfma_f32_16x16x32_bf16 v[22:25], v[102:105], v[158:161], v[22:25]
	v_mfma_f32_16x16x32_bf16 v[18:21], v[126:129], v[158:161], v[18:21]
	v_mfma_f32_16x16x32_bf16 v[14:17], v[102:105], v[182:185], v[14:17]
	v_mfma_f32_16x16x32_bf16 v[10:13], v[126:129], v[182:185], v[10:13]
	v_mfma_f32_16x16x32_bf16 v[6:9], v[102:105], v[190:193], v[6:9]
	v_mfma_f32_16x16x32_bf16 v[2:5], v[126:129], v[190:193], v[2:5]
	v_mfma_f32_16x16x32_bf16 v[30:33], v[114:117], v[146:149], v[30:33]
	v_mfma_f32_16x16x32_bf16 v[26:29], v[138:141], v[146:149], v[26:29]
	v_mfma_f32_16x16x32_bf16 v[22:25], v[114:117], v[170:173], v[22:25]
	v_mfma_f32_16x16x32_bf16 v[18:21], v[138:141], v[170:173], v[18:21]
	v_mfma_f32_16x16x32_bf16 v[14:17], v[114:117], v[186:189], v[14:17]
	v_mfma_f32_16x16x32_bf16 v[10:13], v[138:141], v[186:189], v[10:13]
	v_mfma_f32_16x16x32_bf16 v[6:9], v[114:117], v[194:197], v[6:9]
	v_mfma_f32_16x16x32_bf16 v[2:5], v[138:141], v[194:197], v[2:5]
	s_setprio 0
	s_barrier
	s_add_i32 s65, s65, 2
	s_add_u32 s2, s2, 0x100
	s_addc_u32 s3, s3, 0
	s_add_u32 s23, s23, 0x100
	s_addc_u32 s35, s35, 0
	s_cmp_gt_u32 s65, 5
	s_cbranch_scc0 .LBB0_199
	s_and_b64 vcc, exec, s[44:45]
	s_cbranch_vccz .LBB0_202
	s_barrier

; #define LAS __attribute__((address_space(3)))
; __device__ __forceinline__ void na_fill_table(const PP P, int h, LAS float* tbl, int lane) {
;     const float* rpb = P.in(18) + h * 465;
; #pragma unroll
;     for (int k = 0; k < 16; ++k) {
;         const int e = lane + 64 * k, row = e >> 6, col = e & 63, off = col - 32;
;         float v = 0.f;
;         if (row == 15) v = NEGBIG;
;         else if (off >= -15 && off <= 15) v = rpb[row * 31 + off + 15] * LOG2E;
;         tbl[e] = v;
;     }
; }
; __global__ void __launch_bounds__(NTHREADS, 2) mk_fwd(Params Pk) {
;     ...
;                         t0 = (unsigned)__builtin_amdgcn_readfirstlane((int)t0);
;                         if (t0 >= 1536u) break;
;                         const int tk = (int)(q * 1536u + t0);
;                         na_fill_table(P, (tk >> 2) & 7, (LAS float*)(wl + 9216), lane);
.LBB0_310:
	s_or_b64 exec, exec, s[24:25]
	v_readfirstlane_b32 s35, v2
	s_cmpk_gt_u32 s35, 0x5ff
	s_mov_b64 s[24:25], -1
	s_cbranch_scc1 .LBB0_305
	s_load_dwordx2 s[24:25], s[38:39], 0x90
	s_bfe_u32 s20, s35, 0x30002
	s_mulk_i32 s20, 0x744
	v_lshlrev_b32_e32 v2, 2, v202
	s_waitcnt lgkmcnt(0)
	s_add_u32 s24, s24, s20
	s_addc_u32 s25, s25, 0
	v_mov_b32_e32 v3, 0
	v_mov_b32_e32 v4, 0
	v_mov_b32_e32 v5, 0
	v_mov_b32_e32 v6, 0
	v_mov_b32_e32 v7, 0
	v_mov_b32_e32 v8, 0
	v_mov_b32_e32 v9, 0
	v_mov_b32_e32 v10, 0
	v_mov_b32_e32 v11, 0
	v_mov_b32_e32 v12, 0
	v_mov_b32_e32 v13, 0
	v_mov_b32_e32 v14, 0
	v_mov_b32_e32 v15, 0
	v_mov_b32_e32 v16, 0
	v_mov_b32_e32 v17, 0
	s_and_saveexec_b64 s[40:41], s[6:7]
	global_load_dword v3, v2, s[24:25] offset:-68
	global_load_dword v4, v2, s[24:25] offset:56
	global_load_dword v5, v2, s[24:25] offset:180
	global_load_dword v6, v2, s[24:25] offset:304
	global_load_dword v7, v2, s[24:25] offset:428
	global_load_dword v8, v2, s[24:25] offset:552
	global_load_dword v9, v2, s[24:25] offset:676
	global_load_dword v10, v2, s[24:25] offset:800
	global_load_dword v11, v2, s[24:25] offset:924
	global_load_dword v12, v2, s[24:25] offset:1048
	global_load_dword v13, v2, s[24:25] offset:1172
	global_load_dword v14, v2, s[24:25] offset:1296
	global_load_dword v15, v2, s[24:25] offset:1420
	global_load_dword v16, v2, s[24:25] offset:1544
	global_load_dword v17, v2, s[24:25] offset:1668
	s_waitcnt vmcnt(0)
	v_mul_f32_e32 v3, 0x3fb8aa3b, v3
	v_mul_f32_e32 v4, 0x3fb8aa3b, v4
	v_mul_f32_e32 v5, 0x3fb8aa3b, v5
	v_mul_f32_e32 v6, 0x3fb8aa3b, v6
	v_mul_f32_e32 v7, 0x3fb8aa3b, v7
	v_mul_f32_e32 v8, 0x3fb8aa3b, v8
	v_mul_f32_e32 v9, 0x3fb8aa3b, v9
	v_mul_f32_e32 v10, 0x3fb8aa3b, v10
	v_mul_f32_e32 v11, 0x3fb8aa3b, v11
	v_mul_f32_e32 v12, 0x3fb8aa3b, v12
	v_mul_f32_e32 v13, 0x3fb8aa3b, v13
	v_mul_f32_e32 v14, 0x3fb8aa3b, v14
	v_mul_f32_e32 v15, 0x3fb8aa3b, v15
	v_mul_f32_e32 v16, 0x3fb8aa3b, v16
	v_mul_f32_e32 v17, 0x3fb8aa3b, v17
	s_or_b64 exec, exec, s[40:41]
	ds_write2st64_b32 v190, v3, v4 offset0:36 offset1:37
	ds_write2st64_b32 v190, v5, v6 offset0:38 offset1:39
	ds_write2st64_b32 v190, v7, v8 offset0:40 offset1:41
	ds_write2st64_b32 v190, v9, v10 offset0:42 offset1:43
	ds_write2st64_b32 v190, v11, v12 offset0:44 offset1:45
	ds_write2st64_b32 v190, v13, v14 offset0:46 offset1:47
	ds_write2st64_b32 v190, v15, v16 offset0:48 offset1:49
	ds_write2st64_b32 v190, v17, v239 offset0:50 offset1:51
	v_and_b32_e32 v3, 64, v242
	v_xor_b32_e32 v2, 32, v242
	v_add_u32_e32 v3, 64, v3
	v_cmp_lt_i32_e32 vcc, v2, v3
	s_add_i32 s35, s35, s17
	s_mov_b32 s40, 0
	v_cndmask_b32_e32 v2, v242, v2, vcc
	v_lshlrev_b32_e32 v189, 2, v2
	s_mov_b64 s[44:45], -1
	s_branch .LBB0_340

; #define PG8_STAGE(bufoff, gbase, voff) do { _Pragma("unroll") for (int _i = 0; _i < 2; ++_i) \
;         __builtin_amdgcn_global_load_lds((const unsigned*)((const char*)(gbase) + (voff)[_i]), (PG8_LAS unsigned*)(lds + (bufoff) + ldsw + _i * 8192), 16, 0, 0); } while (0)
; #define PG8_LDA(dst, b, h) do { _Pragma("unroll") for (int m = 0; m < 4; ++m) _Pragma("unroll") for (int k = 0; k < 2; ++k) dst[m][k] = *(const PG8_LAS bf16x8*)(lds + PG8_SA(b, h) + aoff + m * 2048 + k * 1024); } while (0)
; #define PG8_LDB(dst, b, h) do { _Pragma("unroll") for (int n = 0; n < 2; ++n) _Pragma("unroll") for (int k = 0; k < 2; ++k) dst[n][k] = *(const PG8_LAS bf16x8*)(lds + PG8_SB(b, h) + boff + n * 2048 + k * 1024); } while (0)
; #define PG8_MMA(ai, bj, At, Bt) do { __builtin_amdgcn_s_setprio(1); _Pragma("unroll") for (int m = 0; m < 4; ++m) _Pragma("unroll") for (int n = 0; n < 2; ++n) _Pragma("unroll") for (int k = 0; k < 2; ++k) \
;         acc[ai][bj][m][n] = __builtin_amdgcn_mfma_f32_16x16x32_bf16(Bt[n][k], At[m][k], acc[ai][bj][m][n], 0, 0, 0); __builtin_amdgcn_s_setprio(0); } while (0)
; #define PG8_WAIT_V(n) asm volatile("s_waitcnt vmcnt(" #n ")" ::: "memory")
; #define PG8_WAIT_L(n) asm volatile("s_waitcnt lgkmcnt(" #n ")" ::: "memory")
; #define PG8_BAR __builtin_amdgcn_s_barrier()
; #define PG8_SCHED __builtin_amdgcn_sched_barrier(0)
; template <class Epi, class Sched, bool ALIGN_EPI = false, bool SP2 = false>
; __device__ __forceinline__ void gemm_phase(PG8_LAS unsigned char* lds, const Gemm g, const Sched& S, const Epi& E) {
;     ...
;             PG8_LDB(B0, 0, 0); PG8_LDB(B1, 0, 1); PG8_SCHED; PG8_LDA(At, 0, 0); PG8_STAGE(PG8_SA(1, 1), a1 + hstep, voffA);
;             PG8_WAIT_V(8); PG8_WAIT_L(0); PG8_BAR; PG8_MMA(0, 0, At, B0); PG8_MMA(0, 1, At, B1); PG8_BAR; PG8_SCHED;
;             PG8_LDA(At, 0, 1); PG8_STAGE(PG8_SB(0, 0), b2, voffB); PG8_STAGE(PG8_SB(0, 1), b2 + hstep, voffB); PG8_STAGE(PG8_SA(0, 0), a2, voffA);
;             PG8_WAIT_V(8); PG8_WAIT_L(0); PG8_BAR; PG8_MMA(1, 0, At, B0); PG8_MMA(1, 1, At, B1); PG8_BAR; PG8_SCHED;
.LBB0_371:
	s_add_u32 s24, s50, 0xfffc0080
	s_addc_u32 s25, s51, -1
	s_add_i32 s88, 0, 0x10000
	s_cmp_eq_u32 s87, 12
	s_cselect_b32 s53, s1, s25
	s_cselect_b32 s52, s11, s24
	s_cselect_b32 s25, s19, s86
	s_cselect_b32 s24, s23, s35
	s_add_i32 s90, 0, 0x14000
	v_add_u32_e32 v142, s88, v191
	v_add_u32_e32 v170, s90, v191
	ds_read_b128 v[130:133], v142
	ds_read_b128 v[134:137], v142 offset:1024
	ds_read_b128 v[138:141], v142 offset:2048
	ds_read_b128 v[142:145], v142 offset:3072
	ds_read_b128 v[146:149], v170
	ds_read_b128 v[150:153], v170 offset:1024
	ds_read_b128 v[166:169], v170 offset:2048
	ds_read_b128 v[170:173], v170 offset:3072
	v_lshl_add_u64 v[186:187], s[50:51], 0, v[162:163]
	s_add_i32 m0, s3, 0xc000
	ds_read_b128 v[174:177], v195
	ds_read_b128 v[178:181], v195 offset:1024
	ds_read_b128 v[182:185], v195 offset:2048
	ds_read_b128 v[196:199], v195 offset:3072
	ds_read_b128 v[206:209], v195 offset:4096
	ds_read_b128 v[210:213], v195 offset:5120
	ds_read_b128 v[214:217], v195 offset:6144
	ds_read_b128 v[218:221], v195 offset:7168
	global_load_lds_dwordx4 v[186:187], off
	v_lshl_add_u64 v[186:187], s[50:51], 0, v[164:165]
	s_add_i32 m0, s3, 0xe000
	s_nop 0
	global_load_lds_dwordx4 v[186:187], off
	s_waitcnt vmcnt(8)
	s_waitcnt lgkmcnt(0)
	s_barrier
	s_setprio 1
	v_mfma_f32_16x16x32_bf16 v[126:129], v[130:133], v[174:177], v[126:129]
	v_mfma_f32_16x16x32_bf16 v[122:125], v[138:141], v[174:177], v[122:125]
	v_mfma_f32_16x16x32_bf16 v[110:113], v[130:133], v[182:185], v[110:113]
	v_mfma_f32_16x16x32_bf16 v[106:109], v[138:141], v[182:185], v[106:109]
	v_mfma_f32_16x16x32_bf16 v[94:97], v[130:133], v[206:209], v[94:97]
	v_mfma_f32_16x16x32_bf16 v[90:93], v[138:141], v[206:209], v[90:93]
	v_mfma_f32_16x16x32_bf16 v[78:81], v[130:133], v[214:217], v[78:81]
	v_mfma_f32_16x16x32_bf16 v[74:77], v[138:141], v[214:217], v[74:77]
	v_mfma_f32_16x16x32_bf16 v[126:129], v[134:137], v[178:181], v[126:129]
	v_mfma_f32_16x16x32_bf16 v[122:125], v[142:145], v[178:181], v[122:125]
	v_mfma_f32_16x16x32_bf16 v[110:113], v[134:137], v[196:199], v[110:113]
	v_mfma_f32_16x16x32_bf16 v[106:109], v[142:145], v[196:199], v[106:109]
	v_mfma_f32_16x16x32_bf16 v[94:97], v[134:137], v[210:213], v[94:97]
	v_mfma_f32_16x16x32_bf16 v[90:93], v[142:145], v[210:213], v[90:93]
	v_mfma_f32_16x16x32_bf16 v[78:81], v[134:137], v[218:221], v[78:81]
	v_mfma_f32_16x16x32_bf16 v[74:77], v[142:145], v[218:221], v[74:77]
	v_mfma_f32_16x16x32_bf16 v[118:121], v[146:149], v[174:177], v[118:121]
	v_mfma_f32_16x16x32_bf16 v[114:117], v[166:169], v[174:177], v[114:117]
	v_mfma_f32_16x16x32_bf16 v[102:105], v[146:149], v[182:185], v[102:105]
	v_mfma_f32_16x16x32_bf16 v[98:101], v[166:169], v[182:185], v[98:101]
	v_mfma_f32_16x16x32_bf16 v[86:89], v[146:149], v[206:209], v[86:89]
	v_mfma_f32_16x16x32_bf16 v[82:85], v[166:169], v[206:209], v[82:85]
	v_mfma_f32_16x16x32_bf16 v[70:73], v[146:149], v[214:217], v[70:73]
	v_mfma_f32_16x16x32_bf16 v[66:69], v[166:169], v[214:217], v[66:69]
	v_mfma_f32_16x16x32_bf16 v[118:121], v[150:153], v[178:181], v[118:121]
	v_mfma_f32_16x16x32_bf16 v[114:117], v[170:173], v[178:181], v[114:117]
	v_mfma_f32_16x16x32_bf16 v[102:105], v[150:153], v[196:199], v[102:105]
	v_mfma_f32_16x16x32_bf16 v[98:101], v[170:173], v[196:199], v[98:101]
	v_mfma_f32_16x16x32_bf16 v[86:89], v[150:153], v[210:213], v[86:89]
	v_mfma_f32_16x16x32_bf16 v[82:85], v[170:173], v[210:213], v[82:85]
	v_mfma_f32_16x16x32_bf16 v[70:73], v[150:153], v[218:221], v[70:73]
	v_mfma_f32_16x16x32_bf16 v[66:69], v[170:173], v[218:221], v[66:69]
	s_setprio 0
	s_barrier
	s_add_i32 s88, s88, s76
	v_lshl_add_u64 v[186:187], s[24:25], 0, v[0:1]
	s_mov_b32 m0, s88
	ds_read_b128 v[174:177], v195 offset:16384
	ds_read_b128 v[178:181], v195 offset:17408
	ds_read_b128 v[182:185], v195 offset:18432
	ds_read_b128 v[196:199], v195 offset:19456
	ds_read_b128 v[206:209], v195 offset:20480
	ds_read_b128 v[210:213], v195 offset:21504
	ds_read_b128 v[214:217], v195 offset:22528
	ds_read_b128 v[218:221], v195 offset:23552
	global_load_lds_dwordx4 v[186:187], off
	s_add_i32 m0, s88, 0x2000
	s_add_u32 s88, s24, 0x40000
	v_lshl_add_u64 v[200:201], s[24:25], 0, v[158:159]
	s_addc_u32 s89, s25, 0
	s_add_i32 s90, s90, s76
	global_load_lds_dwordx4 v[200:201], off
	v_lshl_add_u64 v[222:223], s[88:89], 0, v[0:1]
	s_mov_b32 m0, s90
	v_lshl_add_u64 v[224:225], s[52:53], 0, v[156:157]
	global_load_lds_dwordx4 v[222:223], off
	v_lshl_add_u64 v[222:223], s[88:89], 0, v[158:159]
	s_add_i32 m0, s90, 0x2000
	s_nop 0
	global_load_lds_dwordx4 v[222:223], off
	v_lshl_add_u64 v[222:223], s[52:53], 0, v[154:155]
	s_mov_b32 m0, s3
	s_nop 0
	global_load_lds_dwordx4 v[222:223], off
	s_mov_b32 m0, s79
	s_nop 0
	global_load_lds_dwordx4 v[224:225], off
	s_waitcnt vmcnt(8)
	s_waitcnt lgkmcnt(0)
	s_barrier
; #define PG8_STAGE(bufoff, gbase, voff) do { _Pragma("unroll") for (int _i = 0; _i < 2; ++_i) \
;         __builtin_amdgcn_global_load_lds((const unsigned*)((const char*)(gbase) + (voff)[_i]), (PG8_LAS unsigned*)(lds + (bufoff) + ldsw + _i * 8192), 16, 0, 0); } while (0)
; #define PG8_LDA(dst, b, h) do { _Pragma("unroll") for (int m = 0; m < 4; ++m) _Pragma("unroll") for (int k = 0; k < 2; ++k) dst[m][k] = *(const PG8_LAS bf16x8*)(lds + PG8_SA(b, h) + aoff + m * 2048 + k * 1024); } while (0)
; #define PG8_LDB(dst, b, h) do { _Pragma("unroll") for (int n = 0; n < 2; ++n) _Pragma("unroll") for (int k = 0; k < 2; ++k) dst[n][k] = *(const PG8_LAS bf16x8*)(lds + PG8_SB(b, h) + boff + n * 2048 + k * 1024); } while (0)
; #define PG8_MMA(ai, bj, At, Bt) do { __builtin_amdgcn_s_setprio(1); _Pragma("unroll") for (int m = 0; m < 4; ++m) _Pragma("unroll") for (int n = 0; n < 2; ++n) _Pragma("unroll") for (int k = 0; k < 2; ++k) \
;         acc[ai][bj][m][n] = __builtin_amdgcn_mfma_f32_16x16x32_bf16(Bt[n][k], At[m][k], acc[ai][bj][m][n], 0, 0, 0); __builtin_amdgcn_s_setprio(0); } while (0)
; #define PG8_WAIT_V(n) asm volatile("s_waitcnt vmcnt(" #n ")" ::: "memory")
; #define PG8_WAIT_L(n) asm volatile("s_waitcnt lgkmcnt(" #n ")" ::: "memory")
; #define PG8_BAR __builtin_amdgcn_s_barrier()
; #define PG8_SCHED __builtin_amdgcn_sched_barrier(0)
; template <class Epi, class Sched, bool ALIGN_EPI = false, bool SP2 = false>
; __device__ __forceinline__ void gemm_phase(PG8_LAS unsigned char* lds, const Gemm g, const Sched& S, const Epi& E) {
;     ...
;             PG8_WAIT_V(8); PG8_WAIT_L(0); PG8_BAR; PG8_MMA(1, 0, At, B0); PG8_MMA(1, 1, At, B1); PG8_BAR; PG8_SCHED;
;             PG8_LDB(B0, 1, 0); PG8_LDB(B1, 1, 1); PG8_SCHED; PG8_LDA(At, 1, 0); PG8_STAGE(PG8_SA(0, 1), a2 + hstep, voffA);
;             PG8_WAIT_V(8); PG8_WAIT_L(0); PG8_BAR; PG8_MMA(0, 0, At, B0); PG8_MMA(0, 1, At, B1); PG8_BAR; PG8_SCHED;
	s_setprio 1
	v_mfma_f32_16x16x32_bf16 v[62:65], v[130:133], v[174:177], v[62:65]
	v_mfma_f32_16x16x32_bf16 v[58:61], v[138:141], v[174:177], v[58:61]
	v_mfma_f32_16x16x32_bf16 v[46:49], v[130:133], v[182:185], v[46:49]
	v_mfma_f32_16x16x32_bf16 v[42:45], v[138:141], v[182:185], v[42:45]
	v_mfma_f32_16x16x32_bf16 v[30:33], v[130:133], v[206:209], v[30:33]
	v_mfma_f32_16x16x32_bf16 v[26:29], v[138:141], v[206:209], v[26:29]
	v_mfma_f32_16x16x32_bf16 v[14:17], v[130:133], v[214:217], v[14:17]
	v_mfma_f32_16x16x32_bf16 v[10:13], v[138:141], v[214:217], v[10:13]
	v_mfma_f32_16x16x32_bf16 v[62:65], v[134:137], v[178:181], v[62:65]
	v_mfma_f32_16x16x32_bf16 v[58:61], v[142:145], v[178:181], v[58:61]
	v_mfma_f32_16x16x32_bf16 v[46:49], v[134:137], v[196:199], v[46:49]
	v_mfma_f32_16x16x32_bf16 v[42:45], v[142:145], v[196:199], v[42:45]
	v_mfma_f32_16x16x32_bf16 v[30:33], v[134:137], v[210:213], v[30:33]
	v_mfma_f32_16x16x32_bf16 v[26:29], v[142:145], v[210:213], v[26:29]
	v_mfma_f32_16x16x32_bf16 v[14:17], v[134:137], v[218:221], v[14:17]
	v_mfma_f32_16x16x32_bf16 v[10:13], v[142:145], v[218:221], v[10:13]
	v_mfma_f32_16x16x32_bf16 v[54:57], v[146:149], v[174:177], v[54:57]
	v_mfma_f32_16x16x32_bf16 v[50:53], v[166:169], v[174:177], v[50:53]
	v_mfma_f32_16x16x32_bf16 v[38:41], v[146:149], v[182:185], v[38:41]
	v_mfma_f32_16x16x32_bf16 v[34:37], v[166:169], v[182:185], v[34:37]
	v_mfma_f32_16x16x32_bf16 v[22:25], v[146:149], v[206:209], v[22:25]
	v_mfma_f32_16x16x32_bf16 v[18:21], v[166:169], v[206:209], v[18:21]
	v_mfma_f32_16x16x32_bf16 v[6:9], v[146:149], v[214:217], v[6:9]
	v_mfma_f32_16x16x32_bf16 v[2:5], v[166:169], v[214:217], v[2:5]
	v_mfma_f32_16x16x32_bf16 v[54:57], v[150:153], v[178:181], v[54:57]
	v_mfma_f32_16x16x32_bf16 v[50:53], v[170:173], v[178:181], v[50:53]
	v_mfma_f32_16x16x32_bf16 v[38:41], v[150:153], v[196:199], v[38:41]
	v_mfma_f32_16x16x32_bf16 v[34:37], v[170:173], v[196:199], v[34:37]
	v_mfma_f32_16x16x32_bf16 v[22:25], v[150:153], v[210:213], v[22:25]
	v_mfma_f32_16x16x32_bf16 v[18:21], v[170:173], v[210:213], v[18:21]
	v_mfma_f32_16x16x32_bf16 v[6:9], v[150:153], v[218:221], v[6:9]
	v_mfma_f32_16x16x32_bf16 v[2:5], v[170:173], v[218:221], v[2:5]
	s_setprio 0
	s_barrier
	s_add_i32 s88, 0, 0x18000
	s_add_i32 s89, 0, 0x1c000
	v_add_u32_e32 v142, s88, v191
	v_add_u32_e32 v170, s89, v191
	ds_read_b128 v[130:133], v142
	ds_read_b128 v[134:137], v142 offset:1024
	ds_read_b128 v[138:141], v142 offset:2048
	ds_read_b128 v[142:145], v142 offset:3072
	ds_read_b128 v[146:149], v170
	ds_read_b128 v[150:153], v170 offset:1024
	ds_read_b128 v[166:169], v170 offset:2048
	ds_read_b128 v[170:173], v170 offset:3072
	s_add_u32 s52, s52, 0x40000
	s_addc_u32 s53, s53, 0
	s_mov_b32 m0, s80
	v_lshl_add_u64 v[226:227], s[52:53], 0, v[154:155]
	ds_read_b128 v[174:177], v195 offset:32768
	ds_read_b128 v[178:181], v195 offset:33792
	ds_read_b128 v[182:185], v195 offset:34816
	ds_read_b128 v[196:199], v195 offset:35840
	ds_read_b128 v[206:209], v195 offset:36864
	ds_read_b128 v[210:213], v195 offset:37888
	ds_read_b128 v[214:217], v195 offset:38912
	ds_read_b128 v[218:221], v195 offset:39936
	global_load_lds_dwordx4 v[226:227], off
	v_lshl_add_u64 v[226:227], s[52:53], 0, v[156:157]
	s_mov_b32 m0, s81
	s_nop 0
	global_load_lds_dwordx4 v[226:227], off
	s_waitcnt vmcnt(8)
	s_waitcnt lgkmcnt(0)
	s_barrier
	s_setprio 1
	v_mfma_f32_16x16x32_bf16 v[126:129], v[130:133], v[174:177], v[126:129]
	v_mfma_f32_16x16x32_bf16 v[122:125], v[138:141], v[174:177], v[122:125]
	v_mfma_f32_16x16x32_bf16 v[110:113], v[130:133], v[182:185], v[110:113]
	v_mfma_f32_16x16x32_bf16 v[106:109], v[138:141], v[182:185], v[106:109]
	v_mfma_f32_16x16x32_bf16 v[94:97], v[130:133], v[206:209], v[94:97]
	v_mfma_f32_16x16x32_bf16 v[90:93], v[138:141], v[206:209], v[90:93]
	v_mfma_f32_16x16x32_bf16 v[78:81], v[130:133], v[214:217], v[78:81]
	v_mfma_f32_16x16x32_bf16 v[74:77], v[138:141], v[214:217], v[74:77]
	v_mfma_f32_16x16x32_bf16 v[126:129], v[134:137], v[178:181], v[126:129]
	v_mfma_f32_16x16x32_bf16 v[122:125], v[142:145], v[178:181], v[122:125]
	v_mfma_f32_16x16x32_bf16 v[110:113], v[134:137], v[196:199], v[110:113]
	v_mfma_f32_16x16x32_bf16 v[106:109], v[142:145], v[196:199], v[106:109]
	v_mfma_f32_16x16x32_bf16 v[94:97], v[134:137], v[210:213], v[94:97]
	v_mfma_f32_16x16x32_bf16 v[90:93], v[142:145], v[210:213], v[90:93]
	v_mfma_f32_16x16x32_bf16 v[78:81], v[134:137], v[218:221], v[78:81]
	v_mfma_f32_16x16x32_bf16 v[74:77], v[142:145], v[218:221], v[74:77]
	v_mfma_f32_16x16x32_bf16 v[118:121], v[146:149], v[174:177], v[118:121]
	v_mfma_f32_16x16x32_bf16 v[114:117], v[166:169], v[174:177], v[114:117]
	v_mfma_f32_16x16x32_bf16 v[102:105], v[146:149], v[182:185], v[102:105]
	v_mfma_f32_16x16x32_bf16 v[98:101], v[166:169], v[182:185], v[98:101]
	v_mfma_f32_16x16x32_bf16 v[86:89], v[146:149], v[206:209], v[86:89]
	v_mfma_f32_16x16x32_bf16 v[82:85], v[166:169], v[206:209], v[82:85]
	v_mfma_f32_16x16x32_bf16 v[70:73], v[146:149], v[214:217], v[70:73]
	v_mfma_f32_16x16x32_bf16 v[66:69], v[166:169], v[214:217], v[66:69]
	v_mfma_f32_16x16x32_bf16 v[118:121], v[150:153], v[178:181], v[118:121]
	v_mfma_f32_16x16x32_bf16 v[114:117], v[170:173], v[178:181], v[114:117]
	v_mfma_f32_16x16x32_bf16 v[102:105], v[150:153], v[196:199], v[102:105]
	v_mfma_f32_16x16x32_bf16 v[98:101], v[170:173], v[196:199], v[98:101]
	v_mfma_f32_16x16x32_bf16 v[86:89], v[150:153], v[210:213], v[86:89]
	v_mfma_f32_16x16x32_bf16 v[82:85], v[170:173], v[210:213], v[82:85]
	v_mfma_f32_16x16x32_bf16 v[70:73], v[150:153], v[218:221], v[70:73]
	v_mfma_f32_16x16x32_bf16 v[66:69], v[170:173], v[218:221], v[66:69]
	s_setprio 0
	s_barrier
; #define PG8_STAGE(bufoff, gbase, voff) do { _Pragma("unroll") for (int _i = 0; _i < 2; ++_i) \
;         __builtin_amdgcn_global_load_lds((const unsigned*)((const char*)(gbase) + (voff)[_i]), (PG8_LAS unsigned*)(lds + (bufoff) + ldsw + _i * 8192), 16, 0, 0); } while (0)
; #define PG8_LDA(dst, b, h) do { _Pragma("unroll") for (int m = 0; m < 4; ++m) _Pragma("unroll") for (int k = 0; k < 2; ++k) dst[m][k] = *(const PG8_LAS bf16x8*)(lds + PG8_SA(b, h) + aoff + m * 2048 + k * 1024); } while (0)
; #define PG8_MMA(ai, bj, At, Bt) do { __builtin_amdgcn_s_setprio(1); _Pragma("unroll") for (int m = 0; m < 4; ++m) _Pragma("unroll") for (int n = 0; n < 2; ++n) _Pragma("unroll") for (int k = 0; k < 2; ++k) \
;         acc[ai][bj][m][n] = __builtin_amdgcn_mfma_f32_16x16x32_bf16(Bt[n][k], At[m][k], acc[ai][bj][m][n], 0, 0, 0); __builtin_amdgcn_s_setprio(0); } while (0)
; #define PG8_WAIT_V(n) asm volatile("s_waitcnt vmcnt(" #n ")" ::: "memory")
; #define PG8_WAIT_L(n) asm volatile("s_waitcnt lgkmcnt(" #n ")" ::: "memory")
; #define PG8_BAR __builtin_amdgcn_s_barrier()
; #define PG8_SCHED __builtin_amdgcn_sched_barrier(0)
; template <class Epi, class Sched, bool ALIGN_EPI = false, bool SP2 = false>
; __device__ __forceinline__ void gemm_phase(PG8_LAS unsigned char* lds, const Gemm g, const Sched& S, const Epi& E) {
;     ...
;             PG8_LDA(At, 1, 1); PG8_STAGE(PG8_SB(1, 0), b3, voffB); PG8_STAGE(PG8_SB(1, 1), b3 + hstep, voffB); PG8_STAGE(PG8_SA(1, 0), a3, voffA);
;             PG8_WAIT_V(8); PG8_WAIT_L(0); PG8_BAR; PG8_MMA(1, 0, At, B0); PG8_MMA(1, 1, At, B1); PG8_BAR; PG8_SCHED;
	s_add_i32 s52, s88, s76
	v_lshl_add_u64 v[186:187], v[186:187], 0, s[28:29]
	s_mov_b32 m0, s52
	ds_read_b128 v[174:177], v195 offset:49152
	ds_read_b128 v[178:181], v195 offset:50176
	ds_read_b128 v[182:185], v195 offset:51200
	ds_read_b128 v[196:199], v195 offset:52224
	ds_read_b128 v[206:209], v195 offset:53248
	ds_read_b128 v[210:213], v195 offset:54272
	ds_read_b128 v[214:217], v195 offset:55296
	ds_read_b128 v[218:221], v195 offset:56320
	global_load_lds_dwordx4 v[186:187], off
	s_add_i32 m0, s52, 0x2000
	s_add_u32 s24, s24, 0x40080
	v_lshl_add_u64 v[186:187], v[200:201], 0, s[28:29]
	s_addc_u32 s25, s25, 0
	s_add_i32 s52, s89, s76
	global_load_lds_dwordx4 v[186:187], off
	v_lshl_add_u64 v[186:187], s[24:25], 0, v[0:1]
	s_mov_b32 m0, s52
	s_nop 0
	global_load_lds_dwordx4 v[186:187], off
	v_lshl_add_u64 v[186:187], s[24:25], 0, v[158:159]
	s_add_i32 m0, s52, 0x2000
	s_nop 0
	global_load_lds_dwordx4 v[186:187], off
	v_lshl_add_u64 v[186:187], v[222:223], 0, s[28:29]
	s_mov_b32 m0, s83
	s_nop 0
	global_load_lds_dwordx4 v[186:187], off
	v_lshl_add_u64 v[186:187], v[224:225], 0, s[28:29]
	s_mov_b32 m0, s84
	s_nop 0
	global_load_lds_dwordx4 v[186:187], off
	s_waitcnt vmcnt(8)
	s_waitcnt lgkmcnt(0)
	s_barrier
	s_setprio 1
	v_mfma_f32_16x16x32_bf16 v[62:65], v[130:133], v[174:177], v[62:65]
	v_mfma_f32_16x16x32_bf16 v[58:61], v[138:141], v[174:177], v[58:61]
	v_mfma_f32_16x16x32_bf16 v[46:49], v[130:133], v[182:185], v[46:49]
	v_mfma_f32_16x16x32_bf16 v[42:45], v[138:141], v[182:185], v[42:45]
	v_mfma_f32_16x16x32_bf16 v[30:33], v[130:133], v[206:209], v[30:33]
	v_mfma_f32_16x16x32_bf16 v[26:29], v[138:141], v[206:209], v[26:29]
	v_mfma_f32_16x16x32_bf16 v[14:17], v[130:133], v[214:217], v[14:17]
	v_mfma_f32_16x16x32_bf16 v[10:13], v[138:141], v[214:217], v[10:13]
	v_mfma_f32_16x16x32_bf16 v[62:65], v[134:137], v[178:181], v[62:65]
	v_mfma_f32_16x16x32_bf16 v[58:61], v[142:145], v[178:181], v[58:61]
	v_mfma_f32_16x16x32_bf16 v[46:49], v[134:137], v[196:199], v[46:49]
	v_mfma_f32_16x16x32_bf16 v[42:45], v[142:145], v[196:199], v[42:45]
	v_mfma_f32_16x16x32_bf16 v[30:33], v[134:137], v[210:213], v[30:33]
	v_mfma_f32_16x16x32_bf16 v[26:29], v[142:145], v[210:213], v[26:29]
	v_mfma_f32_16x16x32_bf16 v[14:17], v[134:137], v[218:221], v[14:17]
	v_mfma_f32_16x16x32_bf16 v[10:13], v[142:145], v[218:221], v[10:13]
	v_mfma_f32_16x16x32_bf16 v[54:57], v[146:149], v[174:177], v[54:57]
	v_mfma_f32_16x16x32_bf16 v[50:53], v[166:169], v[174:177], v[50:53]
	v_mfma_f32_16x16x32_bf16 v[38:41], v[146:149], v[182:185], v[38:41]
	v_mfma_f32_16x16x32_bf16 v[34:37], v[166:169], v[182:185], v[34:37]
	v_mfma_f32_16x16x32_bf16 v[22:25], v[146:149], v[206:209], v[22:25]
	v_mfma_f32_16x16x32_bf16 v[18:21], v[166:169], v[206:209], v[18:21]
	v_mfma_f32_16x16x32_bf16 v[6:9], v[146:149], v[214:217], v[6:9]
	v_mfma_f32_16x16x32_bf16 v[2:5], v[166:169], v[214:217], v[2:5]
	v_mfma_f32_16x16x32_bf16 v[54:57], v[150:153], v[178:181], v[54:57]
	v_mfma_f32_16x16x32_bf16 v[50:53], v[170:173], v[178:181], v[50:53]
	v_mfma_f32_16x16x32_bf16 v[38:41], v[150:153], v[196:199], v[38:41]
	v_mfma_f32_16x16x32_bf16 v[34:37], v[170:173], v[196:199], v[34:37]
	v_mfma_f32_16x16x32_bf16 v[22:25], v[150:153], v[210:213], v[22:25]
	v_mfma_f32_16x16x32_bf16 v[18:21], v[170:173], v[210:213], v[18:21]
	v_mfma_f32_16x16x32_bf16 v[6:9], v[150:153], v[218:221], v[6:9]
	v_mfma_f32_16x16x32_bf16 v[2:5], v[170:173], v[218:221], v[2:5]
	s_setprio 0
	s_barrier
	s_add_i32 s87, s87, 2
	s_add_u32 s50, s50, 0x100
	s_addc_u32 s51, s51, 0
	s_add_u32 s35, s35, 0x100
	s_addc_u32 s86, s86, 0
	s_cmp_gt_u32 s87, 13
	s_cbranch_scc0 .LBB0_371
	s_and_b64 vcc, exec, s[44:45]
	s_cbranch_vccz .LBB0_374
	s_barrier

; #define PG8_STAGE(bufoff, gbase, voff) do { _Pragma("unroll") for (int _i = 0; _i < 2; ++_i) \
;         __builtin_amdgcn_global_load_lds((const unsigned*)((const char*)(gbase) + (voff)[_i]), (PG8_LAS unsigned*)(lds + (bufoff) + ldsw + _i * 8192), 16, 0, 0); } while (0)
; #define PG8_LDA(dst, b, h) do { _Pragma("unroll") for (int m = 0; m < 4; ++m) _Pragma("unroll") for (int k = 0; k < 2; ++k) dst[m][k] = *(const PG8_LAS bf16x8*)(lds + PG8_SA(b, h) + aoff + m * 2048 + k * 1024); } while (0)
; #define PG8_LDB(dst, b, h) do { _Pragma("unroll") for (int n = 0; n < 2; ++n) _Pragma("unroll") for (int k = 0; k < 2; ++k) dst[n][k] = *(const PG8_LAS bf16x8*)(lds + PG8_SB(b, h) + boff + n * 2048 + k * 1024); } while (0)
; #define PG8_MMA(ai, bj, At, Bt) do { __builtin_amdgcn_s_setprio(1); _Pragma("unroll") for (int m = 0; m < 4; ++m) _Pragma("unroll") for (int n = 0; n < 2; ++n) _Pragma("unroll") for (int k = 0; k < 2; ++k) \
;         acc[ai][bj][m][n] = __builtin_amdgcn_mfma_f32_16x16x32_bf16(Bt[n][k], At[m][k], acc[ai][bj][m][n], 0, 0, 0); __builtin_amdgcn_s_setprio(0); } while (0)
; #define PG8_WAIT_V(n) asm volatile("s_waitcnt vmcnt(" #n ")" ::: "memory")
; #define PG8_WAIT_L(n) asm volatile("s_waitcnt lgkmcnt(" #n ")" ::: "memory")
; #define PG8_BAR __builtin_amdgcn_s_barrier()
; #define PG8_SCHED __builtin_amdgcn_sched_barrier(0)
; template <class Epi, class Sched, bool ALIGN_EPI = false, bool SP2 = false>
; __device__ __forceinline__ void gemm_phase(PG8_LAS unsigned char* lds, const Gemm g, const Sched& S, const Epi& E) {
;     ...
;             PG8_LDB(B0, 0, 0); PG8_LDB(B1, 0, 1); PG8_SCHED; PG8_LDA(At, 0, 0); PG8_STAGE(PG8_SA(1, 1), a1 + hstep, voffA);
;             PG8_WAIT_V(8); PG8_WAIT_L(0); PG8_BAR; PG8_MMA(0, 0, At, B0); PG8_MMA(0, 1, At, B1); PG8_BAR; PG8_SCHED;
;             PG8_LDA(At, 0, 1); PG8_STAGE(PG8_SB(0, 0), b2, voffB); PG8_STAGE(PG8_SB(0, 1), b2 + hstep, voffB); PG8_STAGE(PG8_SA(0, 0), a2, voffA);
;             PG8_WAIT_V(8); PG8_WAIT_L(0); PG8_BAR; PG8_MMA(1, 0, At, B0); PG8_MMA(1, 1, At, B1); PG8_BAR; PG8_SCHED;
.LBB0_419:
	s_add_i32 s65, s24, 2
	s_add_u32 s66, s44, 0x80
	s_addc_u32 s25, s45, 0
	s_add_i32 s68, 0, 0x10000
	s_cmp_eq_u32 s58, s24
	s_cselect_b32 s25, s9, s25
	s_cselect_b32 s24, s8, s66
	s_cselect_b32 s67, s41, s64
	s_cselect_b32 s66, s40, s63
	s_add_i32 s69, 0, 0x14000
	v_add_u32_e32 v142, s68, v210
	v_add_u32_e32 v158, s69, v210
	ds_read_b128 v[130:133], v142
	ds_read_b128 v[134:137], v142 offset:1024
	ds_read_b128 v[138:141], v142 offset:2048
	ds_read_b128 v[142:145], v142 offset:3072
	ds_read_b128 v[146:149], v158
	ds_read_b128 v[150:153], v158 offset:1024
	ds_read_b128 v[154:157], v158 offset:2048
	ds_read_b128 v[158:161], v158 offset:3072
	v_lshl_add_u64 v[216:217], s[44:45], 0, v[198:199]
	s_add_i32 m0, s17, 0xc000
	ds_read_b128 v[162:165], v211
	ds_read_b128 v[166:169], v211 offset:1024
	ds_read_b128 v[170:173], v211 offset:2048
	ds_read_b128 v[174:177], v211 offset:3072
	ds_read_b128 v[178:181], v211 offset:4096
	ds_read_b128 v[182:185], v211 offset:5120
	ds_read_b128 v[206:209], v211 offset:6144
	ds_read_b128 v[212:215], v211 offset:7168
	global_load_lds_dwordx4 v[216:217], off
	v_lshl_add_u64 v[216:217], s[44:45], 0, v[200:201]
	s_add_i32 m0, s17, 0xe000
	s_nop 0
	global_load_lds_dwordx4 v[216:217], off
	s_waitcnt vmcnt(8)
	s_waitcnt lgkmcnt(0)
	s_barrier
	s_setprio 1
	v_mfma_f32_16x16x32_bf16 v[118:121], v[130:133], v[162:165], v[118:121]
	v_mfma_f32_16x16x32_bf16 v[114:117], v[138:141], v[162:165], v[114:117]
	v_mfma_f32_16x16x32_bf16 v[110:113], v[130:133], v[170:173], v[110:113]
	v_mfma_f32_16x16x32_bf16 v[106:109], v[138:141], v[170:173], v[106:109]
	v_mfma_f32_16x16x32_bf16 v[94:97], v[130:133], v[178:181], v[94:97]
	v_mfma_f32_16x16x32_bf16 v[90:93], v[138:141], v[178:181], v[90:93]
	v_mfma_f32_16x16x32_bf16 v[78:81], v[130:133], v[206:209], v[78:81]
	v_mfma_f32_16x16x32_bf16 v[74:77], v[138:141], v[206:209], v[74:77]
	v_mfma_f32_16x16x32_bf16 v[118:121], v[134:137], v[166:169], v[118:121]
	v_mfma_f32_16x16x32_bf16 v[114:117], v[142:145], v[166:169], v[114:117]
	v_mfma_f32_16x16x32_bf16 v[110:113], v[134:137], v[174:177], v[110:113]
	v_mfma_f32_16x16x32_bf16 v[106:109], v[142:145], v[174:177], v[106:109]
	v_mfma_f32_16x16x32_bf16 v[94:97], v[134:137], v[182:185], v[94:97]
	v_mfma_f32_16x16x32_bf16 v[90:93], v[142:145], v[182:185], v[90:93]
	v_mfma_f32_16x16x32_bf16 v[78:81], v[134:137], v[212:215], v[78:81]
	v_mfma_f32_16x16x32_bf16 v[74:77], v[142:145], v[212:215], v[74:77]
	v_mfma_f32_16x16x32_bf16 v[126:129], v[146:149], v[162:165], v[126:129]
	v_mfma_f32_16x16x32_bf16 v[122:125], v[154:157], v[162:165], v[122:125]
	v_mfma_f32_16x16x32_bf16 v[102:105], v[146:149], v[170:173], v[102:105]
	v_mfma_f32_16x16x32_bf16 v[98:101], v[154:157], v[170:173], v[98:101]
	v_mfma_f32_16x16x32_bf16 v[86:89], v[146:149], v[178:181], v[86:89]
	v_mfma_f32_16x16x32_bf16 v[82:85], v[154:157], v[178:181], v[82:85]
	v_mfma_f32_16x16x32_bf16 v[70:73], v[146:149], v[206:209], v[70:73]
	v_mfma_f32_16x16x32_bf16 v[66:69], v[154:157], v[206:209], v[66:69]
	v_mfma_f32_16x16x32_bf16 v[126:129], v[150:153], v[166:169], v[126:129]
	v_mfma_f32_16x16x32_bf16 v[122:125], v[158:161], v[166:169], v[122:125]
	v_mfma_f32_16x16x32_bf16 v[102:105], v[150:153], v[174:177], v[102:105]
	v_mfma_f32_16x16x32_bf16 v[98:101], v[158:161], v[174:177], v[98:101]
	v_mfma_f32_16x16x32_bf16 v[86:89], v[150:153], v[182:185], v[86:89]
	v_mfma_f32_16x16x32_bf16 v[82:85], v[158:161], v[182:185], v[82:85]
	v_mfma_f32_16x16x32_bf16 v[70:73], v[150:153], v[212:215], v[70:73]
	v_mfma_f32_16x16x32_bf16 v[66:69], v[158:161], v[212:215], v[66:69]
	s_setprio 0
	s_barrier
	s_add_i32 s68, s68, s16
	v_lshl_add_u64 v[216:217], s[66:67], 0, v[0:1]
	s_mov_b32 m0, s68
	ds_read_b128 v[162:165], v211 offset:16384
	ds_read_b128 v[166:169], v211 offset:17408
	ds_read_b128 v[170:173], v211 offset:18432
	ds_read_b128 v[174:177], v211 offset:19456
	ds_read_b128 v[178:181], v211 offset:20480
	ds_read_b128 v[182:185], v211 offset:21504
	ds_read_b128 v[206:209], v211 offset:22528
	ds_read_b128 v[212:215], v211 offset:23552
	global_load_lds_dwordx4 v[216:217], off
	s_add_i32 m0, s68, 0x2000
	v_lshl_add_u64 v[218:219], s[66:67], 0, v[190:191]
	s_add_u32 s66, s66, s0
	s_addc_u32 s67, s67, 0
	s_add_i32 s68, s69, s16
	global_load_lds_dwordx4 v[218:219], off
	v_lshl_add_u64 v[220:221], s[66:67], 0, v[0:1]
	s_mov_b32 m0, s68
	v_lshl_add_u64 v[222:223], s[66:67], 0, v[190:191]
	global_load_lds_dwordx4 v[220:221], off
	s_add_i32 m0, s68, 0x2000
	v_lshl_add_u64 v[224:225], s[24:25], 0, v[186:187]
	global_load_lds_dwordx4 v[222:223], off
	s_mov_b32 m0, s17
	v_lshl_add_u64 v[226:227], s[24:25], 0, v[188:189]
	global_load_lds_dwordx4 v[224:225], off
	s_mov_b32 m0, s35
	s_nop 0
	global_load_lds_dwordx4 v[226:227], off
	s_waitcnt vmcnt(8)
	s_waitcnt lgkmcnt(0)
	s_barrier
; #define PG8_STAGE(bufoff, gbase, voff) do { _Pragma("unroll") for (int _i = 0; _i < 2; ++_i) \
;         __builtin_amdgcn_global_load_lds((const unsigned*)((const char*)(gbase) + (voff)[_i]), (PG8_LAS unsigned*)(lds + (bufoff) + ldsw + _i * 8192), 16, 0, 0); } while (0)
; #define PG8_LDA(dst, b, h) do { _Pragma("unroll") for (int m = 0; m < 4; ++m) _Pragma("unroll") for (int k = 0; k < 2; ++k) dst[m][k] = *(const PG8_LAS bf16x8*)(lds + PG8_SA(b, h) + aoff + m * 2048 + k * 1024); } while (0)
; #define PG8_LDB(dst, b, h) do { _Pragma("unroll") for (int n = 0; n < 2; ++n) _Pragma("unroll") for (int k = 0; k < 2; ++k) dst[n][k] = *(const PG8_LAS bf16x8*)(lds + PG8_SB(b, h) + boff + n * 2048 + k * 1024); } while (0)
; #define PG8_MMA(ai, bj, At, Bt) do { __builtin_amdgcn_s_setprio(1); _Pragma("unroll") for (int m = 0; m < 4; ++m) _Pragma("unroll") for (int n = 0; n < 2; ++n) _Pragma("unroll") for (int k = 0; k < 2; ++k) \
;         acc[ai][bj][m][n] = __builtin_amdgcn_mfma_f32_16x16x32_bf16(Bt[n][k], At[m][k], acc[ai][bj][m][n], 0, 0, 0); __builtin_amdgcn_s_setprio(0); } while (0)
; #define PG8_WAIT_V(n) asm volatile("s_waitcnt vmcnt(" #n ")" ::: "memory")
; #define PG8_WAIT_L(n) asm volatile("s_waitcnt lgkmcnt(" #n ")" ::: "memory")
; #define PG8_BAR __builtin_amdgcn_s_barrier()
; #define PG8_SCHED __builtin_amdgcn_sched_barrier(0)
; template <class Epi, class Sched, bool ALIGN_EPI = false, bool SP2 = false>
; __device__ __forceinline__ void gemm_phase(PG8_LAS unsigned char* lds, const Gemm g, const Sched& S, const Epi& E) {
;     ...
;             PG8_WAIT_V(8); PG8_WAIT_L(0); PG8_BAR; PG8_MMA(1, 0, At, B0); PG8_MMA(1, 1, At, B1); PG8_BAR; PG8_SCHED;
;             PG8_LDB(B0, 1, 0); PG8_LDB(B1, 1, 1); PG8_SCHED; PG8_LDA(At, 1, 0); PG8_STAGE(PG8_SA(0, 1), a2 + hstep, voffA);
;             PG8_WAIT_V(8); PG8_WAIT_L(0); PG8_BAR; PG8_MMA(0, 0, At, B0); PG8_MMA(0, 1, At, B1); PG8_BAR; PG8_SCHED;
	s_setprio 1
	v_mfma_f32_16x16x32_bf16 v[62:65], v[130:133], v[162:165], v[62:65]
	v_mfma_f32_16x16x32_bf16 v[58:61], v[138:141], v[162:165], v[58:61]
	v_mfma_f32_16x16x32_bf16 v[46:49], v[130:133], v[170:173], v[46:49]
	v_mfma_f32_16x16x32_bf16 v[42:45], v[138:141], v[170:173], v[42:45]
	v_mfma_f32_16x16x32_bf16 v[30:33], v[130:133], v[178:181], v[30:33]
	v_mfma_f32_16x16x32_bf16 v[26:29], v[138:141], v[178:181], v[26:29]
	v_mfma_f32_16x16x32_bf16 v[14:17], v[130:133], v[206:209], v[14:17]
	v_mfma_f32_16x16x32_bf16 v[10:13], v[138:141], v[206:209], v[10:13]
	v_mfma_f32_16x16x32_bf16 v[62:65], v[134:137], v[166:169], v[62:65]
	v_mfma_f32_16x16x32_bf16 v[58:61], v[142:145], v[166:169], v[58:61]
	v_mfma_f32_16x16x32_bf16 v[46:49], v[134:137], v[174:177], v[46:49]
	v_mfma_f32_16x16x32_bf16 v[42:45], v[142:145], v[174:177], v[42:45]
	v_mfma_f32_16x16x32_bf16 v[30:33], v[134:137], v[182:185], v[30:33]
	v_mfma_f32_16x16x32_bf16 v[26:29], v[142:145], v[182:185], v[26:29]
	v_mfma_f32_16x16x32_bf16 v[14:17], v[134:137], v[212:215], v[14:17]
	v_mfma_f32_16x16x32_bf16 v[10:13], v[142:145], v[212:215], v[10:13]
	v_mfma_f32_16x16x32_bf16 v[54:57], v[146:149], v[162:165], v[54:57]
	v_mfma_f32_16x16x32_bf16 v[50:53], v[154:157], v[162:165], v[50:53]
	v_mfma_f32_16x16x32_bf16 v[38:41], v[146:149], v[170:173], v[38:41]
	v_mfma_f32_16x16x32_bf16 v[34:37], v[154:157], v[170:173], v[34:37]
	v_mfma_f32_16x16x32_bf16 v[22:25], v[146:149], v[178:181], v[22:25]
	v_mfma_f32_16x16x32_bf16 v[18:21], v[154:157], v[178:181], v[18:21]
	v_mfma_f32_16x16x32_bf16 v[6:9], v[146:149], v[206:209], v[6:9]
	v_mfma_f32_16x16x32_bf16 v[2:5], v[154:157], v[206:209], v[2:5]
	v_mfma_f32_16x16x32_bf16 v[54:57], v[150:153], v[166:169], v[54:57]
	v_mfma_f32_16x16x32_bf16 v[50:53], v[158:161], v[166:169], v[50:53]
	v_mfma_f32_16x16x32_bf16 v[38:41], v[150:153], v[174:177], v[38:41]
	v_mfma_f32_16x16x32_bf16 v[34:37], v[158:161], v[174:177], v[34:37]
	v_mfma_f32_16x16x32_bf16 v[22:25], v[150:153], v[182:185], v[22:25]
	v_mfma_f32_16x16x32_bf16 v[18:21], v[158:161], v[182:185], v[18:21]
	v_mfma_f32_16x16x32_bf16 v[6:9], v[150:153], v[212:215], v[6:9]
	v_mfma_f32_16x16x32_bf16 v[2:5], v[158:161], v[212:215], v[2:5]
	s_setprio 0
	s_barrier
	s_add_i32 s66, 0, 0x18000
	s_add_i32 s67, 0, 0x1c000
	v_add_u32_e32 v142, s66, v210
	v_add_u32_e32 v158, s67, v210
	ds_read_b128 v[130:133], v142
	ds_read_b128 v[134:137], v142 offset:1024
	ds_read_b128 v[138:141], v142 offset:2048
	ds_read_b128 v[142:145], v142 offset:3072
	ds_read_b128 v[146:149], v158
	ds_read_b128 v[150:153], v158 offset:1024
	ds_read_b128 v[154:157], v158 offset:2048
	ds_read_b128 v[158:161], v158 offset:3072
	s_add_u32 s24, s24, s0
	s_addc_u32 s25, s25, 0
	s_mov_b32 m0, s46
	v_lshl_add_u64 v[228:229], s[24:25], 0, v[186:187]
	ds_read_b128 v[162:165], v211 offset:32768
	ds_read_b128 v[166:169], v211 offset:33792
	ds_read_b128 v[170:173], v211 offset:34816
	ds_read_b128 v[174:177], v211 offset:35840
	ds_read_b128 v[178:181], v211 offset:36864
	ds_read_b128 v[182:185], v211 offset:37888
	ds_read_b128 v[206:209], v211 offset:38912
	ds_read_b128 v[212:215], v211 offset:39936
	global_load_lds_dwordx4 v[228:229], off
	v_lshl_add_u64 v[228:229], s[24:25], 0, v[188:189]
	s_mov_b32 m0, s47
	s_nop 0
	global_load_lds_dwordx4 v[228:229], off
	s_waitcnt vmcnt(8)
	s_waitcnt lgkmcnt(0)
	s_barrier
	s_setprio 1
	v_mfma_f32_16x16x32_bf16 v[118:121], v[130:133], v[162:165], v[118:121]
	v_mfma_f32_16x16x32_bf16 v[114:117], v[138:141], v[162:165], v[114:117]
	v_mfma_f32_16x16x32_bf16 v[110:113], v[130:133], v[170:173], v[110:113]
	v_mfma_f32_16x16x32_bf16 v[106:109], v[138:141], v[170:173], v[106:109]
	v_mfma_f32_16x16x32_bf16 v[94:97], v[130:133], v[178:181], v[94:97]
	v_mfma_f32_16x16x32_bf16 v[90:93], v[138:141], v[178:181], v[90:93]
	v_mfma_f32_16x16x32_bf16 v[78:81], v[130:133], v[206:209], v[78:81]
	v_mfma_f32_16x16x32_bf16 v[74:77], v[138:141], v[206:209], v[74:77]
	v_mfma_f32_16x16x32_bf16 v[118:121], v[134:137], v[166:169], v[118:121]
	v_mfma_f32_16x16x32_bf16 v[114:117], v[142:145], v[166:169], v[114:117]
	v_mfma_f32_16x16x32_bf16 v[110:113], v[134:137], v[174:177], v[110:113]
	v_mfma_f32_16x16x32_bf16 v[106:109], v[142:145], v[174:177], v[106:109]
	v_mfma_f32_16x16x32_bf16 v[94:97], v[134:137], v[182:185], v[94:97]
	v_mfma_f32_16x16x32_bf16 v[90:93], v[142:145], v[182:185], v[90:93]
	v_mfma_f32_16x16x32_bf16 v[78:81], v[134:137], v[212:215], v[78:81]
	v_mfma_f32_16x16x32_bf16 v[74:77], v[142:145], v[212:215], v[74:77]
	v_mfma_f32_16x16x32_bf16 v[126:129], v[146:149], v[162:165], v[126:129]
	v_mfma_f32_16x16x32_bf16 v[122:125], v[154:157], v[162:165], v[122:125]
	v_mfma_f32_16x16x32_bf16 v[102:105], v[146:149], v[170:173], v[102:105]
	v_mfma_f32_16x16x32_bf16 v[98:101], v[154:157], v[170:173], v[98:101]
	v_mfma_f32_16x16x32_bf16 v[86:89], v[146:149], v[178:181], v[86:89]
	v_mfma_f32_16x16x32_bf16 v[82:85], v[154:157], v[178:181], v[82:85]
	v_mfma_f32_16x16x32_bf16 v[70:73], v[146:149], v[206:209], v[70:73]
	v_mfma_f32_16x16x32_bf16 v[66:69], v[154:157], v[206:209], v[66:69]
	v_mfma_f32_16x16x32_bf16 v[126:129], v[150:153], v[166:169], v[126:129]
	v_mfma_f32_16x16x32_bf16 v[122:125], v[158:161], v[166:169], v[122:125]
	v_mfma_f32_16x16x32_bf16 v[102:105], v[150:153], v[174:177], v[102:105]
	v_mfma_f32_16x16x32_bf16 v[98:101], v[158:161], v[174:177], v[98:101]
	v_mfma_f32_16x16x32_bf16 v[86:89], v[150:153], v[182:185], v[86:89]
	v_mfma_f32_16x16x32_bf16 v[82:85], v[158:161], v[182:185], v[82:85]
	v_mfma_f32_16x16x32_bf16 v[70:73], v[150:153], v[212:215], v[70:73]
	v_mfma_f32_16x16x32_bf16 v[66:69], v[158:161], v[212:215], v[66:69]
	s_setprio 0
	s_barrier
; #define PG8_STAGE(bufoff, gbase, voff) do { _Pragma("unroll") for (int _i = 0; _i < 2; ++_i) \
;         __builtin_amdgcn_global_load_lds((const unsigned*)((const char*)(gbase) + (voff)[_i]), (PG8_LAS unsigned*)(lds + (bufoff) + ldsw + _i * 8192), 16, 0, 0); } while (0)
; #define PG8_LDA(dst, b, h) do { _Pragma("unroll") for (int m = 0; m < 4; ++m) _Pragma("unroll") for (int k = 0; k < 2; ++k) dst[m][k] = *(const PG8_LAS bf16x8*)(lds + PG8_SA(b, h) + aoff + m * 2048 + k * 1024); } while (0)
; #define PG8_MMA(ai, bj, At, Bt) do { __builtin_amdgcn_s_setprio(1); _Pragma("unroll") for (int m = 0; m < 4; ++m) _Pragma("unroll") for (int n = 0; n < 2; ++n) _Pragma("unroll") for (int k = 0; k < 2; ++k) \
;         acc[ai][bj][m][n] = __builtin_amdgcn_mfma_f32_16x16x32_bf16(Bt[n][k], At[m][k], acc[ai][bj][m][n], 0, 0, 0); __builtin_amdgcn_s_setprio(0); } while (0)
; #define PG8_WAIT_V(n) asm volatile("s_waitcnt vmcnt(" #n ")" ::: "memory")
; #define PG8_WAIT_L(n) asm volatile("s_waitcnt lgkmcnt(" #n ")" ::: "memory")
; #define PG8_BAR __builtin_amdgcn_s_barrier()
; #define PG8_SCHED __builtin_amdgcn_sched_barrier(0)
; template <class Epi, class Sched, bool ALIGN_EPI = false, bool SP2 = false>
; __device__ __forceinline__ void gemm_phase(PG8_LAS unsigned char* lds, const Gemm g, const Sched& S, const Epi& E) {
;     ...
;             PG8_LDA(At, 1, 1); PG8_STAGE(PG8_SB(1, 0), b3, voffB); PG8_STAGE(PG8_SB(1, 1), b3 + hstep, voffB); PG8_STAGE(PG8_SA(1, 0), a3, voffA);
;             PG8_WAIT_V(8); PG8_WAIT_L(0); PG8_BAR; PG8_MMA(1, 0, At, B0); PG8_MMA(1, 1, At, B1); PG8_BAR; PG8_SCHED;
	s_add_i32 s24, s66, s16
	v_lshl_add_u64 v[216:217], v[216:217], 0, s[28:29]
	s_mov_b32 m0, s24
	ds_read_b128 v[162:165], v211 offset:49152
	ds_read_b128 v[166:169], v211 offset:50176
	ds_read_b128 v[170:173], v211 offset:51200
	ds_read_b128 v[174:177], v211 offset:52224
	ds_read_b128 v[178:181], v211 offset:53248
	ds_read_b128 v[182:185], v211 offset:54272
	ds_read_b128 v[206:209], v211 offset:55296
	ds_read_b128 v[212:215], v211 offset:56320
	global_load_lds_dwordx4 v[216:217], off
	v_lshl_add_u64 v[216:217], v[218:219], 0, s[28:29]
	s_add_i32 m0, s24, 0x2000
	s_add_i32 s24, s67, s16
	global_load_lds_dwordx4 v[216:217], off
	v_lshl_add_u64 v[216:217], v[220:221], 0, s[28:29]
	s_mov_b32 m0, s24
	s_nop 0
	global_load_lds_dwordx4 v[216:217], off
	v_lshl_add_u64 v[216:217], v[222:223], 0, s[28:29]
	s_add_i32 m0, s24, 0x2000
	s_nop 0
	global_load_lds_dwordx4 v[216:217], off
	v_lshl_add_u64 v[216:217], v[224:225], 0, s[28:29]
	s_mov_b32 m0, s50
	s_nop 0
	global_load_lds_dwordx4 v[216:217], off
	v_lshl_add_u64 v[216:217], v[226:227], 0, s[28:29]
	s_mov_b32 m0, s51
	s_nop 0
	global_load_lds_dwordx4 v[216:217], off
	s_waitcnt vmcnt(8)
	s_waitcnt lgkmcnt(0)
	s_barrier
	s_setprio 1
	v_mfma_f32_16x16x32_bf16 v[62:65], v[130:133], v[162:165], v[62:65]
	v_mfma_f32_16x16x32_bf16 v[58:61], v[138:141], v[162:165], v[58:61]
	v_mfma_f32_16x16x32_bf16 v[46:49], v[130:133], v[170:173], v[46:49]
	v_mfma_f32_16x16x32_bf16 v[42:45], v[138:141], v[170:173], v[42:45]
	v_mfma_f32_16x16x32_bf16 v[30:33], v[130:133], v[178:181], v[30:33]
	v_mfma_f32_16x16x32_bf16 v[26:29], v[138:141], v[178:181], v[26:29]
	v_mfma_f32_16x16x32_bf16 v[14:17], v[130:133], v[206:209], v[14:17]
	v_mfma_f32_16x16x32_bf16 v[10:13], v[138:141], v[206:209], v[10:13]
	v_mfma_f32_16x16x32_bf16 v[62:65], v[134:137], v[166:169], v[62:65]
	v_mfma_f32_16x16x32_bf16 v[58:61], v[142:145], v[166:169], v[58:61]
	v_mfma_f32_16x16x32_bf16 v[46:49], v[134:137], v[174:177], v[46:49]
	v_mfma_f32_16x16x32_bf16 v[42:45], v[142:145], v[174:177], v[42:45]
	v_mfma_f32_16x16x32_bf16 v[30:33], v[134:137], v[182:185], v[30:33]
	v_mfma_f32_16x16x32_bf16 v[26:29], v[142:145], v[182:185], v[26:29]
	v_mfma_f32_16x16x32_bf16 v[14:17], v[134:137], v[212:215], v[14:17]
	v_mfma_f32_16x16x32_bf16 v[10:13], v[142:145], v[212:215], v[10:13]
	v_mfma_f32_16x16x32_bf16 v[54:57], v[146:149], v[162:165], v[54:57]
	v_mfma_f32_16x16x32_bf16 v[50:53], v[154:157], v[162:165], v[50:53]
	v_mfma_f32_16x16x32_bf16 v[38:41], v[146:149], v[170:173], v[38:41]
	v_mfma_f32_16x16x32_bf16 v[34:37], v[154:157], v[170:173], v[34:37]
	v_mfma_f32_16x16x32_bf16 v[22:25], v[146:149], v[178:181], v[22:25]
	v_mfma_f32_16x16x32_bf16 v[18:21], v[154:157], v[178:181], v[18:21]
	v_mfma_f32_16x16x32_bf16 v[6:9], v[146:149], v[206:209], v[6:9]
	v_mfma_f32_16x16x32_bf16 v[2:5], v[154:157], v[206:209], v[2:5]
	v_mfma_f32_16x16x32_bf16 v[54:57], v[150:153], v[166:169], v[54:57]
	v_mfma_f32_16x16x32_bf16 v[50:53], v[158:161], v[166:169], v[50:53]
	v_mfma_f32_16x16x32_bf16 v[38:41], v[150:153], v[174:177], v[38:41]
	v_mfma_f32_16x16x32_bf16 v[34:37], v[158:161], v[174:177], v[34:37]
	v_mfma_f32_16x16x32_bf16 v[22:25], v[150:153], v[182:185], v[22:25]
	v_mfma_f32_16x16x32_bf16 v[18:21], v[158:161], v[182:185], v[18:21]
	v_mfma_f32_16x16x32_bf16 v[6:9], v[150:153], v[212:215], v[6:9]
	v_mfma_f32_16x16x32_bf16 v[2:5], v[158:161], v[212:215], v[2:5]
	s_setprio 0
	s_barrier
	s_add_u32 s44, s44, 0x100
	s_addc_u32 s45, s45, 0
	s_add_u32 s63, s63, 0x100
	s_addc_u32 s64, s64, 0
	s_cmp_ge_u32 s65, s56
	s_mov_b32 s24, s65
	s_cbranch_scc0 .LBB0_419
	s_and_b64 vcc, exec, s[22:23]
	s_cbranch_vccz .LBB0_422
	s_barrier

; #define PG8_STAGE(bufoff, gbase, voff) do { _Pragma("unroll") for (int _i = 0; _i < 2; ++_i) \
;         __builtin_amdgcn_global_load_lds((const unsigned*)((const char*)(gbase) + (voff)[_i]), (PG8_LAS unsigned*)(lds + (bufoff) + ldsw + _i * 8192), 16, 0, 0); } while (0)
; #define PG8_LDA(dst, b, h) do { _Pragma("unroll") for (int m = 0; m < 4; ++m) _Pragma("unroll") for (int k = 0; k < 2; ++k) dst[m][k] = *(const PG8_LAS bf16x8*)(lds + PG8_SA(b, h) + aoff + m * 2048 + k * 1024); } while (0)
; #define PG8_LDB(dst, b, h) do { _Pragma("unroll") for (int n = 0; n < 2; ++n) _Pragma("unroll") for (int k = 0; k < 2; ++k) dst[n][k] = *(const PG8_LAS bf16x8*)(lds + PG8_SB(b, h) + boff + n * 2048 + k * 1024); } while (0)
; #define PG8_MMA(ai, bj, At, Bt) do { __builtin_amdgcn_s_setprio(1); _Pragma("unroll") for (int m = 0; m < 4; ++m) _Pragma("unroll") for (int n = 0; n < 2; ++n) _Pragma("unroll") for (int k = 0; k < 2; ++k) \
;         acc[ai][bj][m][n] = __builtin_amdgcn_mfma_f32_16x16x32_bf16(Bt[n][k], At[m][k], acc[ai][bj][m][n], 0, 0, 0); __builtin_amdgcn_s_setprio(0); } while (0)
; #define PG8_WAIT_V(n) asm volatile("s_waitcnt vmcnt(" #n ")" ::: "memory")
; #define PG8_WAIT_L(n) asm volatile("s_waitcnt lgkmcnt(" #n ")" ::: "memory")
; #define PG8_BAR __builtin_amdgcn_s_barrier()
; #define PG8_SCHED __builtin_amdgcn_sched_barrier(0)
; template <class Epi, class Sched, bool ALIGN_EPI = false, bool SP2 = false>
; __device__ __forceinline__ void gemm_phase(PG8_LAS unsigned char* lds, const Gemm g, const Sched& S, const Epi& E) {
;     ...
;             PG8_LDB(B0, 0, 0); PG8_LDB(B1, 0, 1); PG8_SCHED; PG8_LDA(At, 0, 0); PG8_STAGE(PG8_SA(1, 1), a1 + hstep, voffA);
;             PG8_WAIT_V(8); PG8_WAIT_L(0); PG8_BAR; PG8_MMA(0, 0, At, B0); PG8_MMA(0, 1, At, B1); PG8_BAR; PG8_SCHED;
;             PG8_LDA(At, 0, 1); PG8_STAGE(PG8_SB(0, 0), b2, voffB); PG8_STAGE(PG8_SB(0, 1), b2 + hstep, voffB); PG8_STAGE(PG8_SA(0, 0), a2, voffA);
;             PG8_WAIT_V(8); PG8_WAIT_L(0); PG8_BAR; PG8_MMA(1, 0, At, B0); PG8_MMA(1, 1, At, B1); PG8_BAR; PG8_SCHED;
.LBB0_457:
	s_add_u32 s24, s46, 0xfffc0080
	s_addc_u32 s25, s47, -1
	s_add_i32 s65, 0, 0x10000
	s_cmp_eq_u32 s64, 12
	s_cselect_b32 s49, s19, s25
	s_cselect_b32 s48, s60, s24
	s_cselect_b32 s25, s17, s63
	s_cselect_b32 s24, s61, s62
	s_add_i32 s68, 0, 0x14000
	v_add_u32_e32 v142, s65, v189
	v_add_u32_e32 v170, s68, v189
	ds_read_b128 v[130:133], v142
	ds_read_b128 v[134:137], v142 offset:1024
	ds_read_b128 v[138:141], v142 offset:2048
	ds_read_b128 v[142:145], v142 offset:3072
	ds_read_b128 v[146:149], v170
	ds_read_b128 v[150:153], v170 offset:1024
	ds_read_b128 v[154:157], v170 offset:2048
	ds_read_b128 v[170:173], v170 offset:3072
	v_lshl_add_u64 v[186:187], s[46:47], 0, v[166:167]
	s_add_i32 m0, s43, 0xc000
	ds_read_b128 v[174:177], v192
	ds_read_b128 v[178:181], v192 offset:1024
	ds_read_b128 v[182:185], v192 offset:2048
	ds_read_b128 v[194:197], v192 offset:3072
	ds_read_b128 v[198:201], v192 offset:4096
	ds_read_b128 v[206:209], v192 offset:5120
	ds_read_b128 v[210:213], v192 offset:6144
	ds_read_b128 v[214:217], v192 offset:7168
	global_load_lds_dwordx4 v[186:187], off
	v_lshl_add_u64 v[186:187], s[46:47], 0, v[168:169]
	s_add_i32 m0, s43, 0xe000
	s_nop 0
	global_load_lds_dwordx4 v[186:187], off
	s_waitcnt vmcnt(8)
	s_waitcnt lgkmcnt(0)
	s_barrier
	s_setprio 1
	v_mfma_f32_16x16x32_bf16 v[126:129], v[130:133], v[174:177], v[126:129]
	v_mfma_f32_16x16x32_bf16 v[122:125], v[138:141], v[174:177], v[122:125]
	v_mfma_f32_16x16x32_bf16 v[110:113], v[130:133], v[182:185], v[110:113]
	v_mfma_f32_16x16x32_bf16 v[106:109], v[138:141], v[182:185], v[106:109]
	v_mfma_f32_16x16x32_bf16 v[94:97], v[130:133], v[198:201], v[94:97]
	v_mfma_f32_16x16x32_bf16 v[90:93], v[138:141], v[198:201], v[90:93]
	v_mfma_f32_16x16x32_bf16 v[78:81], v[130:133], v[210:213], v[78:81]
	v_mfma_f32_16x16x32_bf16 v[74:77], v[138:141], v[210:213], v[74:77]
	v_mfma_f32_16x16x32_bf16 v[126:129], v[134:137], v[178:181], v[126:129]
	v_mfma_f32_16x16x32_bf16 v[122:125], v[142:145], v[178:181], v[122:125]
	v_mfma_f32_16x16x32_bf16 v[110:113], v[134:137], v[194:197], v[110:113]
	v_mfma_f32_16x16x32_bf16 v[106:109], v[142:145], v[194:197], v[106:109]
	v_mfma_f32_16x16x32_bf16 v[94:97], v[134:137], v[206:209], v[94:97]
	v_mfma_f32_16x16x32_bf16 v[90:93], v[142:145], v[206:209], v[90:93]
	v_mfma_f32_16x16x32_bf16 v[78:81], v[134:137], v[214:217], v[78:81]
	v_mfma_f32_16x16x32_bf16 v[74:77], v[142:145], v[214:217], v[74:77]
	v_mfma_f32_16x16x32_bf16 v[118:121], v[146:149], v[174:177], v[118:121]
	v_mfma_f32_16x16x32_bf16 v[114:117], v[154:157], v[174:177], v[114:117]
	v_mfma_f32_16x16x32_bf16 v[102:105], v[146:149], v[182:185], v[102:105]
	v_mfma_f32_16x16x32_bf16 v[98:101], v[154:157], v[182:185], v[98:101]
	v_mfma_f32_16x16x32_bf16 v[86:89], v[146:149], v[198:201], v[86:89]
	v_mfma_f32_16x16x32_bf16 v[82:85], v[154:157], v[198:201], v[82:85]
	v_mfma_f32_16x16x32_bf16 v[70:73], v[146:149], v[210:213], v[70:73]
	v_mfma_f32_16x16x32_bf16 v[66:69], v[154:157], v[210:213], v[66:69]
	v_mfma_f32_16x16x32_bf16 v[118:121], v[150:153], v[178:181], v[118:121]
	v_mfma_f32_16x16x32_bf16 v[114:117], v[170:173], v[178:181], v[114:117]
	v_mfma_f32_16x16x32_bf16 v[102:105], v[150:153], v[194:197], v[102:105]
	v_mfma_f32_16x16x32_bf16 v[98:101], v[170:173], v[194:197], v[98:101]
	v_mfma_f32_16x16x32_bf16 v[86:89], v[150:153], v[206:209], v[86:89]
	v_mfma_f32_16x16x32_bf16 v[82:85], v[170:173], v[206:209], v[82:85]
	v_mfma_f32_16x16x32_bf16 v[70:73], v[150:153], v[214:217], v[70:73]
	v_mfma_f32_16x16x32_bf16 v[66:69], v[170:173], v[214:217], v[66:69]
	s_setprio 0
	s_barrier
	s_add_i32 s65, s65, s11
	v_lshl_add_u64 v[186:187], s[24:25], 0, v[0:1]
	s_mov_b32 m0, s65
	ds_read_b128 v[174:177], v192 offset:16384
	ds_read_b128 v[178:181], v192 offset:17408
	ds_read_b128 v[182:185], v192 offset:18432
	ds_read_b128 v[194:197], v192 offset:19456
	ds_read_b128 v[198:201], v192 offset:20480
	ds_read_b128 v[206:209], v192 offset:21504
	ds_read_b128 v[210:213], v192 offset:22528
	ds_read_b128 v[214:217], v192 offset:23552
	global_load_lds_dwordx4 v[186:187], off
	s_add_i32 m0, s65, 0x2000
	s_add_u32 s66, s24, 0x40000
	v_lshl_add_u64 v[218:219], s[24:25], 0, v[162:163]
	s_addc_u32 s67, s25, 0
	s_add_i32 s65, s68, s11
	global_load_lds_dwordx4 v[218:219], off
	v_lshl_add_u64 v[220:221], s[66:67], 0, v[0:1]
	s_mov_b32 m0, s65
	v_lshl_add_u64 v[222:223], s[48:49], 0, v[160:161]
	global_load_lds_dwordx4 v[220:221], off
	v_lshl_add_u64 v[220:221], s[66:67], 0, v[162:163]
	s_add_i32 m0, s65, 0x2000
	s_nop 0
	global_load_lds_dwordx4 v[220:221], off
	v_lshl_add_u64 v[220:221], s[48:49], 0, v[158:159]
	s_mov_b32 m0, s43
	s_nop 0
	global_load_lds_dwordx4 v[220:221], off
	s_mov_b32 m0, s45
	s_nop 0
	global_load_lds_dwordx4 v[222:223], off
	s_waitcnt vmcnt(8)
	s_waitcnt lgkmcnt(0)
	s_barrier
; #define PG8_STAGE(bufoff, gbase, voff) do { _Pragma("unroll") for (int _i = 0; _i < 2; ++_i) \
;         __builtin_amdgcn_global_load_lds((const unsigned*)((const char*)(gbase) + (voff)[_i]), (PG8_LAS unsigned*)(lds + (bufoff) + ldsw + _i * 8192), 16, 0, 0); } while (0)
; #define PG8_LDA(dst, b, h) do { _Pragma("unroll") for (int m = 0; m < 4; ++m) _Pragma("unroll") for (int k = 0; k < 2; ++k) dst[m][k] = *(const PG8_LAS bf16x8*)(lds + PG8_SA(b, h) + aoff + m * 2048 + k * 1024); } while (0)
; #define PG8_LDB(dst, b, h) do { _Pragma("unroll") for (int n = 0; n < 2; ++n) _Pragma("unroll") for (int k = 0; k < 2; ++k) dst[n][k] = *(const PG8_LAS bf16x8*)(lds + PG8_SB(b, h) + boff + n * 2048 + k * 1024); } while (0)
; #define PG8_MMA(ai, bj, At, Bt) do { __builtin_amdgcn_s_setprio(1); _Pragma("unroll") for (int m = 0; m < 4; ++m) _Pragma("unroll") for (int n = 0; n < 2; ++n) _Pragma("unroll") for (int k = 0; k < 2; ++k) \
;         acc[ai][bj][m][n] = __builtin_amdgcn_mfma_f32_16x16x32_bf16(Bt[n][k], At[m][k], acc[ai][bj][m][n], 0, 0, 0); __builtin_amdgcn_s_setprio(0); } while (0)
; #define PG8_WAIT_V(n) asm volatile("s_waitcnt vmcnt(" #n ")" ::: "memory")
; #define PG8_WAIT_L(n) asm volatile("s_waitcnt lgkmcnt(" #n ")" ::: "memory")
; #define PG8_BAR __builtin_amdgcn_s_barrier()
; #define PG8_SCHED __builtin_amdgcn_sched_barrier(0)
; template <class Epi, class Sched, bool ALIGN_EPI = false, bool SP2 = false>
; __device__ __forceinline__ void gemm_phase(PG8_LAS unsigned char* lds, const Gemm g, const Sched& S, const Epi& E) {
;     ...
;             PG8_WAIT_V(8); PG8_WAIT_L(0); PG8_BAR; PG8_MMA(1, 0, At, B0); PG8_MMA(1, 1, At, B1); PG8_BAR; PG8_SCHED;
;             PG8_LDB(B0, 1, 0); PG8_LDB(B1, 1, 1); PG8_SCHED; PG8_LDA(At, 1, 0); PG8_STAGE(PG8_SA(0, 1), a2 + hstep, voffA);
;             PG8_WAIT_V(8); PG8_WAIT_L(0); PG8_BAR; PG8_MMA(0, 0, At, B0); PG8_MMA(0, 1, At, B1); PG8_BAR; PG8_SCHED;
	s_setprio 1
	v_mfma_f32_16x16x32_bf16 v[62:65], v[130:133], v[174:177], v[62:65]
	v_mfma_f32_16x16x32_bf16 v[58:61], v[138:141], v[174:177], v[58:61]
	v_mfma_f32_16x16x32_bf16 v[46:49], v[130:133], v[182:185], v[46:49]
	v_mfma_f32_16x16x32_bf16 v[42:45], v[138:141], v[182:185], v[42:45]
	v_mfma_f32_16x16x32_bf16 v[30:33], v[130:133], v[198:201], v[30:33]
	v_mfma_f32_16x16x32_bf16 v[26:29], v[138:141], v[198:201], v[26:29]
	v_mfma_f32_16x16x32_bf16 v[14:17], v[130:133], v[210:213], v[14:17]
	v_mfma_f32_16x16x32_bf16 v[10:13], v[138:141], v[210:213], v[10:13]
	v_mfma_f32_16x16x32_bf16 v[62:65], v[134:137], v[178:181], v[62:65]
	v_mfma_f32_16x16x32_bf16 v[58:61], v[142:145], v[178:181], v[58:61]
	v_mfma_f32_16x16x32_bf16 v[46:49], v[134:137], v[194:197], v[46:49]
	v_mfma_f32_16x16x32_bf16 v[42:45], v[142:145], v[194:197], v[42:45]
	v_mfma_f32_16x16x32_bf16 v[30:33], v[134:137], v[206:209], v[30:33]
	v_mfma_f32_16x16x32_bf16 v[26:29], v[142:145], v[206:209], v[26:29]
	v_mfma_f32_16x16x32_bf16 v[14:17], v[134:137], v[214:217], v[14:17]
	v_mfma_f32_16x16x32_bf16 v[10:13], v[142:145], v[214:217], v[10:13]
	v_mfma_f32_16x16x32_bf16 v[54:57], v[146:149], v[174:177], v[54:57]
	v_mfma_f32_16x16x32_bf16 v[50:53], v[154:157], v[174:177], v[50:53]
	v_mfma_f32_16x16x32_bf16 v[38:41], v[146:149], v[182:185], v[38:41]
	v_mfma_f32_16x16x32_bf16 v[34:37], v[154:157], v[182:185], v[34:37]
	v_mfma_f32_16x16x32_bf16 v[22:25], v[146:149], v[198:201], v[22:25]
	v_mfma_f32_16x16x32_bf16 v[18:21], v[154:157], v[198:201], v[18:21]
	v_mfma_f32_16x16x32_bf16 v[6:9], v[146:149], v[210:213], v[6:9]
	v_mfma_f32_16x16x32_bf16 v[2:5], v[154:157], v[210:213], v[2:5]
	v_mfma_f32_16x16x32_bf16 v[54:57], v[150:153], v[178:181], v[54:57]
	v_mfma_f32_16x16x32_bf16 v[50:53], v[170:173], v[178:181], v[50:53]
	v_mfma_f32_16x16x32_bf16 v[38:41], v[150:153], v[194:197], v[38:41]
	v_mfma_f32_16x16x32_bf16 v[34:37], v[170:173], v[194:197], v[34:37]
	v_mfma_f32_16x16x32_bf16 v[22:25], v[150:153], v[206:209], v[22:25]
	v_mfma_f32_16x16x32_bf16 v[18:21], v[170:173], v[206:209], v[18:21]
	v_mfma_f32_16x16x32_bf16 v[6:9], v[150:153], v[214:217], v[6:9]
	v_mfma_f32_16x16x32_bf16 v[2:5], v[170:173], v[214:217], v[2:5]
	s_setprio 0
	s_barrier
	s_add_i32 s65, 0, 0x18000
	s_add_i32 s66, 0, 0x1c000
	v_add_u32_e32 v142, s65, v189
	v_add_u32_e32 v170, s66, v189
	ds_read_b128 v[130:133], v142
	ds_read_b128 v[134:137], v142 offset:1024
	ds_read_b128 v[138:141], v142 offset:2048
	ds_read_b128 v[142:145], v142 offset:3072
	ds_read_b128 v[146:149], v170
	ds_read_b128 v[150:153], v170 offset:1024
	ds_read_b128 v[154:157], v170 offset:2048
	ds_read_b128 v[170:173], v170 offset:3072
	s_add_u32 s48, s48, 0x40000
	s_addc_u32 s49, s49, 0
	s_mov_b32 m0, s52
	v_lshl_add_u64 v[224:225], s[48:49], 0, v[158:159]
	ds_read_b128 v[174:177], v192 offset:32768
	ds_read_b128 v[178:181], v192 offset:33792
	ds_read_b128 v[182:185], v192 offset:34816
	ds_read_b128 v[194:197], v192 offset:35840
	ds_read_b128 v[198:201], v192 offset:36864
	ds_read_b128 v[206:209], v192 offset:37888
	ds_read_b128 v[210:213], v192 offset:38912
	ds_read_b128 v[214:217], v192 offset:39936
	global_load_lds_dwordx4 v[224:225], off
	v_lshl_add_u64 v[224:225], s[48:49], 0, v[160:161]
	s_mov_b32 m0, s53
	s_nop 0
	global_load_lds_dwordx4 v[224:225], off
	s_waitcnt vmcnt(8)
	s_waitcnt lgkmcnt(0)
	s_barrier
	s_setprio 1
	v_mfma_f32_16x16x32_bf16 v[126:129], v[130:133], v[174:177], v[126:129]
	v_mfma_f32_16x16x32_bf16 v[122:125], v[138:141], v[174:177], v[122:125]
	v_mfma_f32_16x16x32_bf16 v[110:113], v[130:133], v[182:185], v[110:113]
	v_mfma_f32_16x16x32_bf16 v[106:109], v[138:141], v[182:185], v[106:109]
	v_mfma_f32_16x16x32_bf16 v[94:97], v[130:133], v[198:201], v[94:97]
	v_mfma_f32_16x16x32_bf16 v[90:93], v[138:141], v[198:201], v[90:93]
	v_mfma_f32_16x16x32_bf16 v[78:81], v[130:133], v[210:213], v[78:81]
	v_mfma_f32_16x16x32_bf16 v[74:77], v[138:141], v[210:213], v[74:77]
	v_mfma_f32_16x16x32_bf16 v[126:129], v[134:137], v[178:181], v[126:129]
	v_mfma_f32_16x16x32_bf16 v[122:125], v[142:145], v[178:181], v[122:125]
	v_mfma_f32_16x16x32_bf16 v[110:113], v[134:137], v[194:197], v[110:113]
	v_mfma_f32_16x16x32_bf16 v[106:109], v[142:145], v[194:197], v[106:109]
	v_mfma_f32_16x16x32_bf16 v[94:97], v[134:137], v[206:209], v[94:97]
	v_mfma_f32_16x16x32_bf16 v[90:93], v[142:145], v[206:209], v[90:93]
	v_mfma_f32_16x16x32_bf16 v[78:81], v[134:137], v[214:217], v[78:81]
	v_mfma_f32_16x16x32_bf16 v[74:77], v[142:145], v[214:217], v[74:77]
	v_mfma_f32_16x16x32_bf16 v[118:121], v[146:149], v[174:177], v[118:121]
	v_mfma_f32_16x16x32_bf16 v[114:117], v[154:157], v[174:177], v[114:117]
	v_mfma_f32_16x16x32_bf16 v[102:105], v[146:149], v[182:185], v[102:105]
	v_mfma_f32_16x16x32_bf16 v[98:101], v[154:157], v[182:185], v[98:101]
	v_mfma_f32_16x16x32_bf16 v[86:89], v[146:149], v[198:201], v[86:89]
	v_mfma_f32_16x16x32_bf16 v[82:85], v[154:157], v[198:201], v[82:85]
	v_mfma_f32_16x16x32_bf16 v[70:73], v[146:149], v[210:213], v[70:73]
	v_mfma_f32_16x16x32_bf16 v[66:69], v[154:157], v[210:213], v[66:69]
	v_mfma_f32_16x16x32_bf16 v[118:121], v[150:153], v[178:181], v[118:121]
	v_mfma_f32_16x16x32_bf16 v[114:117], v[170:173], v[178:181], v[114:117]
	v_mfma_f32_16x16x32_bf16 v[102:105], v[150:153], v[194:197], v[102:105]
	v_mfma_f32_16x16x32_bf16 v[98:101], v[170:173], v[194:197], v[98:101]
	v_mfma_f32_16x16x32_bf16 v[86:89], v[150:153], v[206:209], v[86:89]
	v_mfma_f32_16x16x32_bf16 v[82:85], v[170:173], v[206:209], v[82:85]
	v_mfma_f32_16x16x32_bf16 v[70:73], v[150:153], v[214:217], v[70:73]
	v_mfma_f32_16x16x32_bf16 v[66:69], v[170:173], v[214:217], v[66:69]
	s_setprio 0
	s_barrier
; #define PG8_STAGE(bufoff, gbase, voff) do { _Pragma("unroll") for (int _i = 0; _i < 2; ++_i) \
;         __builtin_amdgcn_global_load_lds((const unsigned*)((const char*)(gbase) + (voff)[_i]), (PG8_LAS unsigned*)(lds + (bufoff) + ldsw + _i * 8192), 16, 0, 0); } while (0)
; #define PG8_LDA(dst, b, h) do { _Pragma("unroll") for (int m = 0; m < 4; ++m) _Pragma("unroll") for (int k = 0; k < 2; ++k) dst[m][k] = *(const PG8_LAS bf16x8*)(lds + PG8_SA(b, h) + aoff + m * 2048 + k * 1024); } while (0)
; #define PG8_MMA(ai, bj, At, Bt) do { __builtin_amdgcn_s_setprio(1); _Pragma("unroll") for (int m = 0; m < 4; ++m) _Pragma("unroll") for (int n = 0; n < 2; ++n) _Pragma("unroll") for (int k = 0; k < 2; ++k) \
;         acc[ai][bj][m][n] = __builtin_amdgcn_mfma_f32_16x16x32_bf16(Bt[n][k], At[m][k], acc[ai][bj][m][n], 0, 0, 0); __builtin_amdgcn_s_setprio(0); } while (0)
; #define PG8_WAIT_V(n) asm volatile("s_waitcnt vmcnt(" #n ")" ::: "memory")
; #define PG8_WAIT_L(n) asm volatile("s_waitcnt lgkmcnt(" #n ")" ::: "memory")
; #define PG8_BAR __builtin_amdgcn_s_barrier()
; #define PG8_SCHED __builtin_amdgcn_sched_barrier(0)
; template <class Epi, class Sched, bool ALIGN_EPI = false, bool SP2 = false>
; __device__ __forceinline__ void gemm_phase(PG8_LAS unsigned char* lds, const Gemm g, const Sched& S, const Epi& E) {
;     ...
;             PG8_LDA(At, 1, 1); PG8_STAGE(PG8_SB(1, 0), b3, voffB); PG8_STAGE(PG8_SB(1, 1), b3 + hstep, voffB); PG8_STAGE(PG8_SA(1, 0), a3, voffA);
;             PG8_WAIT_V(8); PG8_WAIT_L(0); PG8_BAR; PG8_MMA(1, 0, At, B0); PG8_MMA(1, 1, At, B1); PG8_BAR; PG8_SCHED;
	s_add_i32 s48, s65, s11
	v_lshl_add_u64 v[186:187], v[186:187], 0, s[28:29]
	s_mov_b32 m0, s48
	ds_read_b128 v[174:177], v192 offset:49152
	ds_read_b128 v[178:181], v192 offset:50176
	ds_read_b128 v[182:185], v192 offset:51200
	ds_read_b128 v[194:197], v192 offset:52224
	ds_read_b128 v[198:201], v192 offset:53248
	ds_read_b128 v[206:209], v192 offset:54272
	ds_read_b128 v[210:213], v192 offset:55296
	ds_read_b128 v[214:217], v192 offset:56320
	global_load_lds_dwordx4 v[186:187], off
	s_add_i32 m0, s48, 0x2000
	s_add_u32 s24, s24, 0x40080
	v_lshl_add_u64 v[186:187], v[218:219], 0, s[28:29]
	s_addc_u32 s25, s25, 0
	s_add_i32 s48, s66, s11
	global_load_lds_dwordx4 v[186:187], off
	v_lshl_add_u64 v[186:187], s[24:25], 0, v[0:1]
	s_mov_b32 m0, s48
	s_nop 0
	global_load_lds_dwordx4 v[186:187], off
	v_lshl_add_u64 v[186:187], s[24:25], 0, v[162:163]
	s_add_i32 m0, s48, 0x2000
	s_nop 0
	global_load_lds_dwordx4 v[186:187], off
	v_lshl_add_u64 v[186:187], v[220:221], 0, s[28:29]
	s_mov_b32 m0, s54
	s_nop 0
	global_load_lds_dwordx4 v[186:187], off
	v_lshl_add_u64 v[186:187], v[222:223], 0, s[28:29]
	s_mov_b32 m0, s55
	s_nop 0
	global_load_lds_dwordx4 v[186:187], off
	s_waitcnt vmcnt(8)
	s_waitcnt lgkmcnt(0)
	s_barrier
	s_setprio 1
	v_mfma_f32_16x16x32_bf16 v[62:65], v[130:133], v[174:177], v[62:65]
	v_mfma_f32_16x16x32_bf16 v[58:61], v[138:141], v[174:177], v[58:61]
	v_mfma_f32_16x16x32_bf16 v[46:49], v[130:133], v[182:185], v[46:49]
	v_mfma_f32_16x16x32_bf16 v[42:45], v[138:141], v[182:185], v[42:45]
	v_mfma_f32_16x16x32_bf16 v[30:33], v[130:133], v[198:201], v[30:33]
	v_mfma_f32_16x16x32_bf16 v[26:29], v[138:141], v[198:201], v[26:29]
	v_mfma_f32_16x16x32_bf16 v[14:17], v[130:133], v[210:213], v[14:17]
	v_mfma_f32_16x16x32_bf16 v[10:13], v[138:141], v[210:213], v[10:13]
	v_mfma_f32_16x16x32_bf16 v[62:65], v[134:137], v[178:181], v[62:65]
	v_mfma_f32_16x16x32_bf16 v[58:61], v[142:145], v[178:181], v[58:61]
	v_mfma_f32_16x16x32_bf16 v[46:49], v[134:137], v[194:197], v[46:49]
	v_mfma_f32_16x16x32_bf16 v[42:45], v[142:145], v[194:197], v[42:45]
	v_mfma_f32_16x16x32_bf16 v[30:33], v[134:137], v[206:209], v[30:33]
	v_mfma_f32_16x16x32_bf16 v[26:29], v[142:145], v[206:209], v[26:29]
	v_mfma_f32_16x16x32_bf16 v[14:17], v[134:137], v[214:217], v[14:17]
	v_mfma_f32_16x16x32_bf16 v[10:13], v[142:145], v[214:217], v[10:13]
	v_mfma_f32_16x16x32_bf16 v[54:57], v[146:149], v[174:177], v[54:57]
	v_mfma_f32_16x16x32_bf16 v[50:53], v[154:157], v[174:177], v[50:53]
	v_mfma_f32_16x16x32_bf16 v[38:41], v[146:149], v[182:185], v[38:41]
	v_mfma_f32_16x16x32_bf16 v[34:37], v[154:157], v[182:185], v[34:37]
	v_mfma_f32_16x16x32_bf16 v[22:25], v[146:149], v[198:201], v[22:25]
	v_mfma_f32_16x16x32_bf16 v[18:21], v[154:157], v[198:201], v[18:21]
	v_mfma_f32_16x16x32_bf16 v[6:9], v[146:149], v[210:213], v[6:9]
	v_mfma_f32_16x16x32_bf16 v[2:5], v[154:157], v[210:213], v[2:5]
	v_mfma_f32_16x16x32_bf16 v[54:57], v[150:153], v[178:181], v[54:57]
	v_mfma_f32_16x16x32_bf16 v[50:53], v[170:173], v[178:181], v[50:53]
	v_mfma_f32_16x16x32_bf16 v[38:41], v[150:153], v[194:197], v[38:41]
	v_mfma_f32_16x16x32_bf16 v[34:37], v[170:173], v[194:197], v[34:37]
	v_mfma_f32_16x16x32_bf16 v[22:25], v[150:153], v[206:209], v[22:25]
	v_mfma_f32_16x16x32_bf16 v[18:21], v[170:173], v[206:209], v[18:21]
	v_mfma_f32_16x16x32_bf16 v[6:9], v[150:153], v[214:217], v[6:9]
	v_mfma_f32_16x16x32_bf16 v[2:5], v[170:173], v[214:217], v[2:5]
	s_setprio 0
	s_barrier
	s_add_i32 s64, s64, 2
	s_add_u32 s46, s46, 0x100
	s_addc_u32 s47, s47, 0
	s_add_u32 s62, s62, 0x100
	s_addc_u32 s63, s63, 0
	s_cmp_gt_u32 s64, 13
	s_cbranch_scc0 .LBB0_457
	s_and_b64 vcc, exec, s[12:13]
	s_cbranch_vccz .LBB0_460
	s_barrier
